# first K-tile pair of each tile peeled: C=0 MFMAs instead of clearing, and its first two counted waits dropped (they only made the epilogue stores drain)
# speedup vs baseline: 1.0122x; 1.0001x over previous
; #define PG8_STAGE(bufoff, gbase, voff) do { _Pragma("unroll") for (int _i = 0; _i < 2; ++_i) \
;         __builtin_amdgcn_global_load_lds((const unsigned*)((const char*)(gbase) + (voff)[_i]), (PG8_LAS unsigned*)(lds + (bufoff) + ldsw + _i * 8192), 16, 0, 0); } while (0)
; #define PG8_WAIT_V(n) asm volatile("s_waitcnt vmcnt(" #n ")" ::: "memory")
; #define PG8_BAR __builtin_amdgcn_s_barrier()
; template <class Epi, class Sched, bool ALIGN_EPI = false, bool SP2 = false>
; __device__ __forceinline__ void gemm_phase(PG8_LAS unsigned char* lds, const Gemm g, const Sched& S, const Epi& E) {
;     ...
;         PG8_STAGE(PG8_SB(0, 0), cB, voffB); PG8_STAGE(PG8_SB(0, 1), cB + hstep, voffB); PG8_STAGE(PG8_SA(0, 0), cA, voffA); PG8_STAGE(PG8_SA(0, 1), cA + hstep, voffA);
;         if (wr == 1) PG8_BAR;
;         PG8_WAIT_V(2); PG8_BAR;
;         PG8_STAGE(PG8_SB(1, 0), cB + kstep, voffB); PG8_STAGE(PG8_SA(1, 0), cA + kstep, voffA); PG8_STAGE(PG8_SB(1, 1), cB + hstep + kstep, voffB);
;         PG8_WAIT_V(6); PG8_BAR;
;     __device__ __forceinline__ void operator()(const f32x4 (&acc)[2][2][4][2], const Unit& u, int wr, int wc, int fr, int fq) const {
;     ...
;         const int row0 = u.pm * BM + wr * 64 + fr, ch = u.pn * 64 + wc * 16 + fq * 4;
;         float rsv[2][4];
; #pragma unroll
;         for (int ai = 0; ai < 2; ++ai)
; #pragma unroll
;             for (int m = 0; m < 4; ++m) rsv[ai][m] = SS ? SS[row0 + ai * HALF + m * 16] : 1.f;
;         const f32x4 w0 = *(const f32x4*)(cw + ch), w1 = *(const f32x4*)(cw + 2048 + ch), w2 = *(const f32x4*)(cw + 4096 + ch), bb = *(const f32x4*)(cb + ch);
.LBB0_117:
	s_mov_b64 s[12:13], 0x80
	s_and_b32 s4, s2, 3
	s_add_i32 m0, s63, 0x18000
	v_lshl_add_u64 v[6:7], v[6:7], 0, s[12:13]
	s_lshl_b32 s5, s72, 13
	s_lshl_b32 s7, s4, 12
	s_waitcnt vmcnt(2)
	s_barrier
	global_load_lds_dwordx4 v[6:7], off
	v_lshl_add_u64 v[4:5], v[4:5], 0, s[12:13]
	s_add_i32 m0, s63, 0x1a000
	s_add_i32 s68, s63, 0x8000
	s_add_i32 s69, s63, 0xa000
	global_load_lds_dwordx4 v[4:5], off
	v_lshl_add_u64 v[0:1], v[0:1], 0, s[12:13]
	s_mov_b32 m0, s68
	s_add_u32 s2, s44, 0x80080
	global_load_lds_dwordx4 v[0:1], off
	v_lshl_add_u64 v[0:1], v[2:3], 0, s[12:13]
	s_mov_b32 m0, s69
	s_addc_u32 s3, s45, 0
	global_load_lds_dwordx4 v[0:1], off
	s_add_i32 m0, s63, 0x1c000
	v_lshl_add_u64 v[0:1], s[2:3], 0, v[144:145]
	global_load_lds_dwordx4 v[0:1], off
	v_lshl_add_u64 v[0:1], s[2:3], 0, v[146:147]
	s_add_i32 m0, s63, 0x1e000
	v_and_b32_e32 v2, 15, v196
	global_load_lds_dwordx4 v[0:1], off
	v_bfe_u32 v0, v196, 4, 2
	v_lshlrev_b32_e32 v1, 4, v0
	v_lshlrev_b32_e32 v4, 2, v196
	v_lshl_or_b32 v3, v2, 6, v1
	v_and_b32_e32 v4, 32, v4
	v_bitop3_b32 v5, v3, s5, v4 bitop3:0xde
	v_lshlrev_b32_e32 v3, 6, v196
	s_movk_i32 s2, 0x3c0
	v_and_or_b32 v1, v3, s2, v1
	v_lshlrev_b32_e32 v0, 2, v0
	v_bitop3_b32 v167, s7, v1, v4 bitop3:0xf6
	v_lshl_or_b32 v169, s4, 4, v0
	v_add_u32_e32 v0, -14, v2
	v_mov_b32_e32 v1, v145
	v_lshlrev_b64 v[0:1], 12, v[0:1]
	v_lshl_add_u64 v[152:153], s[70:71], 0, v[0:1]
	v_cvt_f32_u32_e32 v0, s59
	v_readlane_b32 s16, v254, 55
	v_lshl_or_b32 v163, s72, 6, v2
	s_cmpk_lt_u32 s6, 0x100
	v_rcp_iflag_f32_e32 v0, v0
	v_cmp_eq_u32_e64 s[2:3], 0, v2
	v_cmp_gt_u32_e64 s[4:5], 2, v2
	v_cmp_lt_u32_e64 s[6:7], 13, v2
	v_lshlrev_b32_e32 v2, 12, v2
	v_mov_b32_e32 v3, v145
	v_readlane_b32 s17, v254, 56
	s_cselect_b64 s[14:15], -1, 0
	s_ashr_i32 s33, s88, 31
	v_lshl_add_u64 v[150:151], s[16:17], 0, v[2:3]
	v_readlane_b32 s16, v254, 24
	s_ashr_i32 s73, s89, 31
	v_readlane_b32 s17, v254, 25
	v_readlane_b32 s18, v254, 26
	v_readlane_b32 s19, v254, 27
	v_readlane_b32 s20, v254, 28
	v_readlane_b32 s21, v254, 29
	v_readlane_b32 s22, v254, 30
	v_readlane_b32 s23, v254, 31
	s_cmp_lg_u64 s[22:23], 0
	v_readlane_b32 s16, v254, 35
	v_mul_f32_e32 v0, 0x4f7ffffe, v0
	v_readlane_b32 s18, v254, 37
	v_readlane_b32 s22, v254, 41
	v_cvt_u32_f32_e32 v0, v0
	v_lshl_add_u64 v[148:149], s[70:71], 0, v[2:3]
	s_cselect_b64 s[70:71], -1, 0
	v_readlane_b32 s19, v254, 38
	v_readlane_b32 s23, v254, 42
	s_add_u32 s18, s22, 0x2000
	v_readlane_b32 s20, v254, 39
	s_addc_u32 s19, s23, 0
	v_readlane_b32 s21, v254, 40
	s_add_u32 s20, s22, 0x4000
	s_addc_u32 s21, s23, 0
	v_readfirstlane_b32 s23, v0
	v_lshlrev_b32_e32 v0, 9, v196
	v_and_b32_e32 v0, 0x70000, v0
	v_lshlrev_b32_e32 v1, 12, v10
	v_or3_b32 v0, v8, v0, v1
	s_sub_i32 s22, 0, s59
	v_add_u32_e32 v154, v0, v9
	v_lshlrev_b32_e32 v0, 5, v11
	s_waitcnt vmcnt(0)
	s_mul_i32 s22, s22, s23
	v_and_b32_e32 v0, 0xf0000, v0
	s_mul_hi_u32 s22, s23, s22
	v_or3_b32 v0, v8, v0, v1
	s_add_i32 s52, 0, 0x10000
	s_add_i32 s53, 0, 0x14000
	v_readlane_b32 s24, v254, 43
	s_add_i32 s16, s23, s22
	v_mov_b32_e32 v155, v145
	v_add_u32_e32 v156, v0, v9
	v_mov_b32_e32 v157, v145
	v_add_u32_e32 v173, s52, v167
	v_add_u32_e32 v175, s53, v167
	v_add_u32_e32 v177, 0, v5
	v_mov_b64_e32 v[158:159], 0xfff
	s_barrier
	v_readlane_b32 s17, v254, 36
	v_readlane_b32 s25, v254, 44
	v_readlane_b32 s26, v254, 45
	v_readlane_b32 s27, v254, 46
	v_readlane_b32 s28, v254, 47
	v_readlane_b32 s29, v254, 48
	v_readlane_b32 s30, v254, 49
	v_readlane_b32 s31, v254, 50
	s_branch .LBB0_120

; #define PG8_STAGE(bufoff, gbase, voff) do { _Pragma("unroll") for (int _i = 0; _i < 2; ++_i) \
;         __builtin_amdgcn_global_load_lds((const unsigned*)((const char*)(gbase) + (voff)[_i]), (PG8_LAS unsigned*)(lds + (bufoff) + ldsw + _i * 8192), 16, 0, 0); } while (0)
; #define PG8_LDA(dst, b, h) do { _Pragma("unroll") for (int m = 0; m < 4; ++m) _Pragma("unroll") for (int k = 0; k < 2; ++k) dst[m][k] = *(const PG8_LAS bf16x8*)(lds + PG8_SA(b, h) + aoff + m * 2048 + k * 1024); } while (0)
; #define PG8_LDB(dst, b, h) do { _Pragma("unroll") for (int n = 0; n < 2; ++n) _Pragma("unroll") for (int k = 0; k < 2; ++k) dst[n][k] = *(const PG8_LAS bf16x8*)(lds + PG8_SB(b, h) + boff + n * 2048 + k * 1024); } while (0)
; #define PG8_WAIT_V(n) asm volatile("s_waitcnt vmcnt(" #n ")" ::: "memory")
; #define PG8_BAR __builtin_amdgcn_s_barrier()
; template <class Epi, class Sched, bool ALIGN_EPI = false, bool SP2 = false>
; __device__ __forceinline__ void gemm_phase(PG8_LAS unsigned char* lds, const Gemm g, const Sched& S, const Epi& E) {
;     ...
;         const char* nA = has_next ? (const char*)g.A + (size_t)nxt.pm * tstep : cA; const char* nB = has_next ? (const char*)g.Bt + (size_t)nxt.pn * tstep : cB;
;         for (int t = 0; t < nt; t += 2) {
;             const bool last = (t == nt - 2);
;             const char* a1 = cA + (size_t)(t + 1) * kstep;
;             const char* a2 = last ? nA : cA + (size_t)(t + 2) * kstep; const char* b2 = last ? nB : cB + (size_t)(t + 2) * kstep;
;             const char* a3 = a2 + kstep; const char* b3 = b2 + kstep;
;             if (last && has_next) S.a_ready(nxt);
;             if constexpr (SP2) {
;             PG8_LDB(B0, 0, 0); PG8_LDB(B1, 0, 1); PG8_SCHED; PG8_LDA(At, 0, 0); PG8_STAGE(PG8_SA(1, 1), a1 + hstep, voffA);
;             PG8_WAIT_V(8); PG8_WAIT_L(0); PG8_BAR; PG8_MMA(0, 0, At, B0); PG8_MMA(0, 1, At, B1); PG8_BAR; PG8_SCHED;
;             PG8_LDA(At, 0, 1); PG8_STAGE(PG8_SB(0, 0), b2, voffB); PG8_STAGE(PG8_SB(0, 1), b2 + hstep, voffB); PG8_STAGE(PG8_SA(0, 0), a2, voffA);
;     ...
; #pragma unroll
;         for (int a = 0; a < 2; ++a)
; #pragma unroll
;             for (int b = 0; b < 2; ++b)
; #pragma unroll
;                 for (int m = 0; m < 4; ++m)
; #pragma unroll
;                     for (int n = 0; n < 2; ++n) acc[a][b][m][n] = (f32x4){0.f, 0.f, 0.f, 0.f};
;         cur = nxt; cA = nA; cB = nB; ++ui;
.LBB0_128:
	s_ashr_i32 s25, s24, 31
	s_lshl_b64 s[28:29], s[24:25], 20
	v_readlane_b32 s30, v254, 51
	v_readlane_b32 s31, v254, 52
	s_add_u32 s28, s30, s28
	s_addc_u32 s29, s31, s29
	s_and_b64 s[30:31], s[26:27], exec
	s_cselect_b32 s25, s29, s9
	s_cselect_b32 s35, s28, s8
	s_ashr_i32 s23, s22, 31
	s_lshl_b64 s[30:31], s[22:23], 20
	s_add_u32 s30, s94, s30
	s_addc_u32 s31, s95, s31
	s_and_b64 s[46:47], s[26:27], exec
	s_cselect_b32 s23, s31, s45
	s_cselect_b32 s43, s30, s44
	s_add_u32 s8, s8, 0x80080
	s_addc_u32 s9, s9, 0
	s_add_u32 s48, s44, 0x100
	s_addc_u32 s49, s45, 0
	s_mov_b32 s54, -2
	s_waitcnt lgkmcnt(0)
	ds_read_b128 v[96:99], v173
	ds_read_b128 v[100:103], v173 offset:1024
	ds_read_b128 v[104:107], v173 offset:2048
	ds_read_b128 v[112:115], v173 offset:3072
	ds_read_b128 v[178:181], v175
	ds_read_b128 v[182:185], v175 offset:1024
	ds_read_b128 v[186:189], v175 offset:2048
	ds_read_b128 v[190:193], v175 offset:3072
	s_add_u32 s44, s8, 0xfff80080
	s_addc_u32 s45, s9, -1
	s_cmp_eq_u32 s54, 28
	s_cselect_b32 s47, s25, s45
	s_cselect_b32 s46, s35, s44
	s_cselect_b32 s45, s23, s49
	s_cselect_b32 s44, s43, s48
	v_lshl_add_u64 v[160:161], s[8:9], 0, v[154:155]
	s_add_i32 m0, s63, 0xc000
	ds_read_b128 v[198:201], v177
	ds_read_b128 v[202:205], v177 offset:1024
	ds_read_b128 v[206:209], v177 offset:2048
	ds_read_b128 v[210:213], v177 offset:3072
	ds_read_b128 v[214:217], v177 offset:4096
	ds_read_b128 v[218:221], v177 offset:5120
	ds_read_b128 v[222:225], v177 offset:6144
	ds_read_b128 v[226:229], v177 offset:7168
	global_load_lds_dwordx4 v[160:161], off
	v_lshl_add_u64 v[160:161], s[8:9], 0, v[156:157]
	s_add_i32 m0, s63, 0xe000
	s_nop 0
	global_load_lds_dwordx4 v[160:161], off
	s_nop 0
	s_waitcnt lgkmcnt(0)
	s_setprio 1
	s_barrier
	v_mfma_f32_16x16x32_bf16 v[140:143], v[96:99], v[198:201], 0
	v_mfma_f32_16x16x32_bf16 v[132:135], v[104:107], v[198:201], 0
	v_mfma_f32_16x16x32_bf16 v[116:119], v[96:99], v[206:209], 0
	v_mfma_f32_16x16x32_bf16 v[124:127], v[104:107], v[206:209], 0
	v_mfma_f32_16x16x32_bf16 v[84:87], v[96:99], v[214:217], 0
	v_mfma_f32_16x16x32_bf16 v[92:95], v[104:107], v[214:217], 0
	v_mfma_f32_16x16x32_bf16 v[68:71], v[96:99], v[222:225], 0
	v_mfma_f32_16x16x32_bf16 v[76:79], v[104:107], v[222:225], 0
	v_mfma_f32_16x16x32_bf16 v[140:143], v[100:103], v[202:205], v[140:143]
	v_mfma_f32_16x16x32_bf16 v[132:135], v[112:115], v[202:205], v[132:135]
	v_mfma_f32_16x16x32_bf16 v[116:119], v[100:103], v[210:213], v[116:119]
	v_mfma_f32_16x16x32_bf16 v[124:127], v[112:115], v[210:213], v[124:127]
	v_mfma_f32_16x16x32_bf16 v[84:87], v[100:103], v[218:221], v[84:87]
	v_mfma_f32_16x16x32_bf16 v[92:95], v[112:115], v[218:221], v[92:95]
	v_mfma_f32_16x16x32_bf16 v[68:71], v[100:103], v[226:229], v[68:71]
	v_mfma_f32_16x16x32_bf16 v[76:79], v[112:115], v[226:229], v[76:79]
	v_mfma_f32_16x16x32_bf16 v[128:131], v[178:181], v[198:201], 0
	v_mfma_f32_16x16x32_bf16 v[136:139], v[186:189], v[198:201], 0
	v_mfma_f32_16x16x32_bf16 v[120:123], v[178:181], v[206:209], 0
	v_mfma_f32_16x16x32_bf16 v[108:111], v[186:189], v[206:209], 0
	v_mfma_f32_16x16x32_bf16 v[88:91], v[178:181], v[214:217], 0
	v_mfma_f32_16x16x32_bf16 v[80:83], v[186:189], v[214:217], 0
	v_mfma_f32_16x16x32_bf16 v[72:75], v[178:181], v[222:225], 0
	v_mfma_f32_16x16x32_bf16 v[64:67], v[186:189], v[222:225], 0
	v_mfma_f32_16x16x32_bf16 v[128:131], v[182:185], v[202:205], v[128:131]
	v_mfma_f32_16x16x32_bf16 v[136:139], v[190:193], v[202:205], v[136:139]
	v_mfma_f32_16x16x32_bf16 v[120:123], v[182:185], v[210:213], v[120:123]
	v_mfma_f32_16x16x32_bf16 v[108:111], v[190:193], v[210:213], v[108:111]
	v_mfma_f32_16x16x32_bf16 v[88:91], v[182:185], v[218:221], v[88:91]
	v_mfma_f32_16x16x32_bf16 v[80:83], v[190:193], v[218:221], v[80:83]
	v_mfma_f32_16x16x32_bf16 v[72:75], v[182:185], v[226:229], v[72:75]
	v_mfma_f32_16x16x32_bf16 v[64:67], v[190:193], v[226:229], v[64:67]
	s_barrier
	s_setprio 0
	s_add_i32 s55, s52, s62
	v_lshl_add_u64 v[160:161], s[44:45], 0, v[144:145]
	s_mov_b32 m0, s55
	ds_read_b128 v[198:201], v177 offset:16384
	ds_read_b128 v[202:205], v177 offset:17408
	ds_read_b128 v[206:209], v177 offset:18432
	ds_read_b128 v[210:213], v177 offset:19456
	ds_read_b128 v[214:217], v177 offset:20480
	ds_read_b128 v[218:221], v177 offset:21504
	ds_read_b128 v[222:225], v177 offset:22528
	ds_read_b128 v[226:229], v177 offset:23552
	global_load_lds_dwordx4 v[160:161], off
	s_add_i32 m0, s55, 0x2000
	s_add_u32 s56, s44, 0x80000
	v_lshl_add_u64 v[164:165], s[44:45], 0, v[146:147]
	s_addc_u32 s57, s45, 0
	s_add_i32 s55, s53, s62
	global_load_lds_dwordx4 v[164:165], off
	v_lshl_add_u64 v[170:171], s[56:57], 0, v[144:145]
	s_mov_b32 m0, s55
	v_lshl_add_u64 v[194:195], s[46:47], 0, v[146:147]
	global_load_lds_dwordx4 v[170:171], off
	v_lshl_add_u64 v[170:171], s[56:57], 0, v[146:147]
	s_add_i32 m0, s55, 0x2000
	s_nop 0
	global_load_lds_dwordx4 v[170:171], off
	v_lshl_add_u64 v[170:171], s[46:47], 0, v[144:145]
	s_mov_b32 m0, s63
	s_nop 0
	global_load_lds_dwordx4 v[170:171], off
	s_mov_b32 m0, s64
	s_nop 0
	global_load_lds_dwordx4 v[194:195], off
	s_nop 0
	s_waitcnt lgkmcnt(0)
	s_setprio 1
	s_barrier
; #define PG8_STAGE(bufoff, gbase, voff) do { _Pragma("unroll") for (int _i = 0; _i < 2; ++_i) \
;         __builtin_amdgcn_global_load_lds((const unsigned*)((const char*)(gbase) + (voff)[_i]), (PG8_LAS unsigned*)(lds + (bufoff) + ldsw + _i * 8192), 16, 0, 0); } while (0)
; #define PG8_LDA(dst, b, h) do { _Pragma("unroll") for (int m = 0; m < 4; ++m) _Pragma("unroll") for (int k = 0; k < 2; ++k) dst[m][k] = *(const PG8_LAS bf16x8*)(lds + PG8_SA(b, h) + aoff + m * 2048 + k * 1024); } while (0)
; #define PG8_LDB(dst, b, h) do { _Pragma("unroll") for (int n = 0; n < 2; ++n) _Pragma("unroll") for (int k = 0; k < 2; ++k) dst[n][k] = *(const PG8_LAS bf16x8*)(lds + PG8_SB(b, h) + boff + n * 2048 + k * 1024); } while (0)
; #define PG8_MMA(ai, bj, At, Bt) do { __builtin_amdgcn_s_setprio(1); _Pragma("unroll") for (int m = 0; m < 4; ++m) _Pragma("unroll") for (int n = 0; n < 2; ++n) _Pragma("unroll") for (int k = 0; k < 2; ++k) \
;         acc[ai][bj][m][n] = __builtin_amdgcn_mfma_f32_16x16x32_bf16(Bt[n][k], At[m][k], acc[ai][bj][m][n], 0, 0, 0); __builtin_amdgcn_s_setprio(0); } while (0)
; #define PG8_WAIT_V(n) asm volatile("s_waitcnt vmcnt(" #n ")" ::: "memory")
; #define PG8_WAIT_L(n) asm volatile("s_waitcnt lgkmcnt(" #n ")" ::: "memory")
; #define PG8_BAR __builtin_amdgcn_s_barrier()
; #define PG8_SCHED __builtin_amdgcn_sched_barrier(0)
; template <class Epi, class Sched, bool ALIGN_EPI = false, bool SP2 = false>
; __device__ __forceinline__ void gemm_phase(PG8_LAS unsigned char* lds, const Gemm g, const Sched& S, const Epi& E) {
;     ...
;             PG8_WAIT_V(8); PG8_WAIT_L(0); PG8_BAR; PG8_MMA(1, 0, At, B0); PG8_MMA(1, 1, At, B1); PG8_BAR; PG8_SCHED;
;             PG8_LDB(B0, 1, 0); PG8_LDB(B1, 1, 1); PG8_SCHED; PG8_LDA(At, 1, 0); PG8_STAGE(PG8_SA(0, 1), a2 + hstep, voffA);
;             PG8_WAIT_V(8); PG8_WAIT_L(0); PG8_BAR; PG8_MMA(0, 0, At, B0); PG8_MMA(0, 1, At, B1); PG8_BAR; PG8_SCHED;
	v_mfma_f32_16x16x32_bf16 v[60:63], v[96:99], v[198:201], 0
	v_mfma_f32_16x16x32_bf16 v[52:55], v[104:107], v[198:201], 0
	v_mfma_f32_16x16x32_bf16 v[36:39], v[96:99], v[206:209], 0
	v_mfma_f32_16x16x32_bf16 v[44:47], v[104:107], v[206:209], 0
	v_mfma_f32_16x16x32_bf16 v[20:23], v[96:99], v[214:217], 0
	v_mfma_f32_16x16x32_bf16 v[28:31], v[104:107], v[214:217], 0
	v_mfma_f32_16x16x32_bf16 v[4:7], v[96:99], v[222:225], 0
	v_mfma_f32_16x16x32_bf16 v[12:15], v[104:107], v[222:225], 0
	v_mfma_f32_16x16x32_bf16 v[60:63], v[100:103], v[202:205], v[60:63]
	v_mfma_f32_16x16x32_bf16 v[52:55], v[112:115], v[202:205], v[52:55]
	v_mfma_f32_16x16x32_bf16 v[36:39], v[100:103], v[210:213], v[36:39]
	v_mfma_f32_16x16x32_bf16 v[44:47], v[112:115], v[210:213], v[44:47]
	v_mfma_f32_16x16x32_bf16 v[20:23], v[100:103], v[218:221], v[20:23]
	v_mfma_f32_16x16x32_bf16 v[28:31], v[112:115], v[218:221], v[28:31]
	v_mfma_f32_16x16x32_bf16 v[4:7], v[100:103], v[226:229], v[4:7]
	v_mfma_f32_16x16x32_bf16 v[12:15], v[112:115], v[226:229], v[12:15]
	v_mfma_f32_16x16x32_bf16 v[48:51], v[178:181], v[198:201], 0
	v_mfma_f32_16x16x32_bf16 v[56:59], v[186:189], v[198:201], 0
	v_mfma_f32_16x16x32_bf16 v[40:43], v[178:181], v[206:209], 0
	v_mfma_f32_16x16x32_bf16 v[32:35], v[186:189], v[206:209], 0
	v_mfma_f32_16x16x32_bf16 v[24:27], v[178:181], v[214:217], 0
	v_mfma_f32_16x16x32_bf16 v[16:19], v[186:189], v[214:217], 0
	v_mfma_f32_16x16x32_bf16 v[8:11], v[178:181], v[222:225], 0
	v_mfma_f32_16x16x32_bf16 v[0:3], v[186:189], v[222:225], 0
	v_mfma_f32_16x16x32_bf16 v[48:51], v[182:185], v[202:205], v[48:51]
	v_mfma_f32_16x16x32_bf16 v[56:59], v[190:193], v[202:205], v[56:59]
	v_mfma_f32_16x16x32_bf16 v[40:43], v[182:185], v[210:213], v[40:43]
	v_mfma_f32_16x16x32_bf16 v[32:35], v[190:193], v[210:213], v[32:35]
	v_mfma_f32_16x16x32_bf16 v[24:27], v[182:185], v[218:221], v[24:27]
	v_mfma_f32_16x16x32_bf16 v[16:19], v[190:193], v[218:221], v[16:19]
	v_mfma_f32_16x16x32_bf16 v[8:11], v[182:185], v[226:229], v[8:11]
	v_mfma_f32_16x16x32_bf16 v[0:3], v[190:193], v[226:229], v[0:3]
	s_barrier
	s_setprio 0
	s_add_i32 s55, 0, 0x18000
	s_add_i32 s56, 0, 0x1c000
	v_add_u32_e32 v112, s55, v167
	v_add_u32_e32 v162, s56, v167
	ds_read_b128 v[96:99], v112
	ds_read_b128 v[100:103], v112 offset:1024
	ds_read_b128 v[104:107], v112 offset:2048
	ds_read_b128 v[112:115], v112 offset:3072
	ds_read_b128 v[178:181], v162
	ds_read_b128 v[182:185], v162 offset:1024
	ds_read_b128 v[186:189], v162 offset:2048
	ds_read_b128 v[190:193], v162 offset:3072
	s_add_u32 s46, s46, 0x80000
	s_addc_u32 s47, s47, 0
	s_mov_b32 m0, s65
	v_lshl_add_u64 v[230:231], s[46:47], 0, v[144:145]
	ds_read_b128 v[198:201], v177 offset:32768
	ds_read_b128 v[202:205], v177 offset:33792
	ds_read_b128 v[206:209], v177 offset:34816
	ds_read_b128 v[210:213], v177 offset:35840
	ds_read_b128 v[214:217], v177 offset:36864
	ds_read_b128 v[218:221], v177 offset:37888
	ds_read_b128 v[222:225], v177 offset:38912
	ds_read_b128 v[226:229], v177 offset:39936
	global_load_lds_dwordx4 v[230:231], off
	v_lshl_add_u64 v[230:231], s[46:47], 0, v[146:147]
	s_mov_b32 m0, s66
	s_nop 0
	global_load_lds_dwordx4 v[230:231], off
	s_waitcnt vmcnt(8)
	s_waitcnt lgkmcnt(0)
	s_setprio 1
	s_barrier
	v_mfma_f32_16x16x32_bf16 v[140:143], v[96:99], v[198:201], v[140:143]
	v_mfma_f32_16x16x32_bf16 v[132:135], v[104:107], v[198:201], v[132:135]
	v_mfma_f32_16x16x32_bf16 v[116:119], v[96:99], v[206:209], v[116:119]
	v_mfma_f32_16x16x32_bf16 v[124:127], v[104:107], v[206:209], v[124:127]
	v_mfma_f32_16x16x32_bf16 v[84:87], v[96:99], v[214:217], v[84:87]
	v_mfma_f32_16x16x32_bf16 v[92:95], v[104:107], v[214:217], v[92:95]
	v_mfma_f32_16x16x32_bf16 v[68:71], v[96:99], v[222:225], v[68:71]
	v_mfma_f32_16x16x32_bf16 v[76:79], v[104:107], v[222:225], v[76:79]
	v_mfma_f32_16x16x32_bf16 v[140:143], v[100:103], v[202:205], v[140:143]
	v_mfma_f32_16x16x32_bf16 v[132:135], v[112:115], v[202:205], v[132:135]
	v_mfma_f32_16x16x32_bf16 v[116:119], v[100:103], v[210:213], v[116:119]
	v_mfma_f32_16x16x32_bf16 v[124:127], v[112:115], v[210:213], v[124:127]
	v_mfma_f32_16x16x32_bf16 v[84:87], v[100:103], v[218:221], v[84:87]
	v_mfma_f32_16x16x32_bf16 v[92:95], v[112:115], v[218:221], v[92:95]
	v_mfma_f32_16x16x32_bf16 v[68:71], v[100:103], v[226:229], v[68:71]
	v_mfma_f32_16x16x32_bf16 v[76:79], v[112:115], v[226:229], v[76:79]
	v_mfma_f32_16x16x32_bf16 v[128:131], v[178:181], v[198:201], v[128:131]
	v_mfma_f32_16x16x32_bf16 v[136:139], v[186:189], v[198:201], v[136:139]
	v_mfma_f32_16x16x32_bf16 v[120:123], v[178:181], v[206:209], v[120:123]
	v_mfma_f32_16x16x32_bf16 v[108:111], v[186:189], v[206:209], v[108:111]
	v_mfma_f32_16x16x32_bf16 v[88:91], v[178:181], v[214:217], v[88:91]
	v_mfma_f32_16x16x32_bf16 v[80:83], v[186:189], v[214:217], v[80:83]
	v_mfma_f32_16x16x32_bf16 v[72:75], v[178:181], v[222:225], v[72:75]
	v_mfma_f32_16x16x32_bf16 v[64:67], v[186:189], v[222:225], v[64:67]
	v_mfma_f32_16x16x32_bf16 v[128:131], v[182:185], v[202:205], v[128:131]
	v_mfma_f32_16x16x32_bf16 v[136:139], v[190:193], v[202:205], v[136:139]
	v_mfma_f32_16x16x32_bf16 v[120:123], v[182:185], v[210:213], v[120:123]
	v_mfma_f32_16x16x32_bf16 v[108:111], v[190:193], v[210:213], v[108:111]
	v_mfma_f32_16x16x32_bf16 v[88:91], v[182:185], v[218:221], v[88:91]
	v_mfma_f32_16x16x32_bf16 v[80:83], v[190:193], v[218:221], v[80:83]
	v_mfma_f32_16x16x32_bf16 v[72:75], v[182:185], v[226:229], v[72:75]
	v_mfma_f32_16x16x32_bf16 v[64:67], v[190:193], v[226:229], v[64:67]
	s_barrier
; #define PG8_STAGE(bufoff, gbase, voff) do { _Pragma("unroll") for (int _i = 0; _i < 2; ++_i) \
;         __builtin_amdgcn_global_load_lds((const unsigned*)((const char*)(gbase) + (voff)[_i]), (PG8_LAS unsigned*)(lds + (bufoff) + ldsw + _i * 8192), 16, 0, 0); } while (0)
; #define PG8_LDA(dst, b, h) do { _Pragma("unroll") for (int m = 0; m < 4; ++m) _Pragma("unroll") for (int k = 0; k < 2; ++k) dst[m][k] = *(const PG8_LAS bf16x8*)(lds + PG8_SA(b, h) + aoff + m * 2048 + k * 1024); } while (0)
; #define PG8_MMA(ai, bj, At, Bt) do { __builtin_amdgcn_s_setprio(1); _Pragma("unroll") for (int m = 0; m < 4; ++m) _Pragma("unroll") for (int n = 0; n < 2; ++n) _Pragma("unroll") for (int k = 0; k < 2; ++k) \
;         acc[ai][bj][m][n] = __builtin_amdgcn_mfma_f32_16x16x32_bf16(Bt[n][k], At[m][k], acc[ai][bj][m][n], 0, 0, 0); __builtin_amdgcn_s_setprio(0); } while (0)
; #define PG8_WAIT_V(n) asm volatile("s_waitcnt vmcnt(" #n ")" ::: "memory")
; #define PG8_WAIT_L(n) asm volatile("s_waitcnt lgkmcnt(" #n ")" ::: "memory")
; #define PG8_BAR __builtin_amdgcn_s_barrier()
; #define PG8_SCHED __builtin_amdgcn_sched_barrier(0)
; template <class Epi, class Sched, bool ALIGN_EPI = false, bool SP2 = false>
; __device__ __forceinline__ void gemm_phase(PG8_LAS unsigned char* lds, const Gemm g, const Sched& S, const Epi& E) {
;     ...
;             PG8_LDA(At, 1, 1); PG8_STAGE(PG8_SB(1, 0), b3, voffB); PG8_STAGE(PG8_SB(1, 1), b3 + hstep, voffB); PG8_STAGE(PG8_SA(1, 0), a3, voffA);
;             PG8_WAIT_V(8); PG8_WAIT_L(0); PG8_BAR; PG8_MMA(1, 0, At, B0); PG8_MMA(1, 1, At, B1); PG8_BAR; PG8_SCHED;
	s_setprio 0
	s_add_i32 s46, s55, s62
	v_lshl_add_u64 v[160:161], v[160:161], 0, s[12:13]
	s_mov_b32 m0, s46
	ds_read_b128 v[198:201], v177 offset:49152
	ds_read_b128 v[202:205], v177 offset:50176
	ds_read_b128 v[206:209], v177 offset:51200
	ds_read_b128 v[210:213], v177 offset:52224
	ds_read_b128 v[214:217], v177 offset:53248
	ds_read_b128 v[218:221], v177 offset:54272
	ds_read_b128 v[222:225], v177 offset:55296
	ds_read_b128 v[226:229], v177 offset:56320
	global_load_lds_dwordx4 v[160:161], off
	s_add_i32 m0, s46, 0x2000
	s_add_u32 s44, s44, 0x80080
	v_lshl_add_u64 v[160:161], v[164:165], 0, s[12:13]
	s_addc_u32 s45, s45, 0
	s_add_i32 s46, s56, s62
	global_load_lds_dwordx4 v[160:161], off
	v_lshl_add_u64 v[160:161], s[44:45], 0, v[144:145]
	s_mov_b32 m0, s46
	s_nop 0
	global_load_lds_dwordx4 v[160:161], off
	v_lshl_add_u64 v[160:161], s[44:45], 0, v[146:147]
	s_add_i32 m0, s46, 0x2000
	s_nop 0
	global_load_lds_dwordx4 v[160:161], off
	v_lshl_add_u64 v[160:161], v[170:171], 0, s[12:13]
	s_mov_b32 m0, s68
	s_nop 0
	global_load_lds_dwordx4 v[160:161], off
	v_lshl_add_u64 v[160:161], v[194:195], 0, s[12:13]
	s_mov_b32 m0, s69
	s_nop 0
	global_load_lds_dwordx4 v[160:161], off
	s_waitcnt vmcnt(8)
	s_waitcnt lgkmcnt(0)
	s_setprio 1
	s_barrier
	v_mfma_f32_16x16x32_bf16 v[60:63], v[96:99], v[198:201], v[60:63]
	v_mfma_f32_16x16x32_bf16 v[52:55], v[104:107], v[198:201], v[52:55]
	v_mfma_f32_16x16x32_bf16 v[36:39], v[96:99], v[206:209], v[36:39]
	v_mfma_f32_16x16x32_bf16 v[44:47], v[104:107], v[206:209], v[44:47]
	v_mfma_f32_16x16x32_bf16 v[20:23], v[96:99], v[214:217], v[20:23]
	v_mfma_f32_16x16x32_bf16 v[28:31], v[104:107], v[214:217], v[28:31]
	v_mfma_f32_16x16x32_bf16 v[4:7], v[96:99], v[222:225], v[4:7]
	v_mfma_f32_16x16x32_bf16 v[12:15], v[104:107], v[222:225], v[12:15]
	v_mfma_f32_16x16x32_bf16 v[60:63], v[100:103], v[202:205], v[60:63]
	v_mfma_f32_16x16x32_bf16 v[52:55], v[112:115], v[202:205], v[52:55]
	v_mfma_f32_16x16x32_bf16 v[36:39], v[100:103], v[210:213], v[36:39]
	v_mfma_f32_16x16x32_bf16 v[44:47], v[112:115], v[210:213], v[44:47]
	v_mfma_f32_16x16x32_bf16 v[20:23], v[100:103], v[218:221], v[20:23]
	v_mfma_f32_16x16x32_bf16 v[28:31], v[112:115], v[218:221], v[28:31]
	v_mfma_f32_16x16x32_bf16 v[4:7], v[100:103], v[226:229], v[4:7]
	v_mfma_f32_16x16x32_bf16 v[12:15], v[112:115], v[226:229], v[12:15]
	v_mfma_f32_16x16x32_bf16 v[48:51], v[178:181], v[198:201], v[48:51]
	v_mfma_f32_16x16x32_bf16 v[56:59], v[186:189], v[198:201], v[56:59]
	v_mfma_f32_16x16x32_bf16 v[40:43], v[178:181], v[206:209], v[40:43]
	v_mfma_f32_16x16x32_bf16 v[32:35], v[186:189], v[206:209], v[32:35]
	v_mfma_f32_16x16x32_bf16 v[24:27], v[178:181], v[214:217], v[24:27]
	v_mfma_f32_16x16x32_bf16 v[16:19], v[186:189], v[214:217], v[16:19]
	v_mfma_f32_16x16x32_bf16 v[8:11], v[178:181], v[222:225], v[8:11]
	v_mfma_f32_16x16x32_bf16 v[0:3], v[186:189], v[222:225], v[0:3]
	v_mfma_f32_16x16x32_bf16 v[48:51], v[182:185], v[202:205], v[48:51]
	v_mfma_f32_16x16x32_bf16 v[56:59], v[190:193], v[202:205], v[56:59]
	v_mfma_f32_16x16x32_bf16 v[40:43], v[182:185], v[210:213], v[40:43]
	v_mfma_f32_16x16x32_bf16 v[32:35], v[190:193], v[210:213], v[32:35]
	v_mfma_f32_16x16x32_bf16 v[24:27], v[182:185], v[218:221], v[24:27]
	v_mfma_f32_16x16x32_bf16 v[16:19], v[190:193], v[218:221], v[16:19]
	v_mfma_f32_16x16x32_bf16 v[8:11], v[182:185], v[226:229], v[8:11]
	v_mfma_f32_16x16x32_bf16 v[0:3], v[190:193], v[226:229], v[0:3]
	s_barrier
	s_setprio 0
	s_add_i32 s54, s54, 2
	s_add_u32 s8, s8, 0x100
	s_addc_u32 s9, s9, 0
	s_add_u32 s48, s48, 0x100
	s_addc_u32 s49, s49, 0

; #define PG8_STAGE(bufoff, gbase, voff) do { _Pragma("unroll") for (int _i = 0; _i < 2; ++_i) \
;         __builtin_amdgcn_global_load_lds((const unsigned*)((const char*)(gbase) + (voff)[_i]), (PG8_LAS unsigned*)(lds + (bufoff) + ldsw + _i * 8192), 16, 0, 0); } while (0)
; #define PG8_WAIT_V(n) asm volatile("s_waitcnt vmcnt(" #n ")" ::: "memory")
; #define PG8_BAR __builtin_amdgcn_s_barrier()
; template <class Epi, class Sched, bool ALIGN_EPI = false, bool SP2 = false>
; __device__ __forceinline__ void gemm_phase(PG8_LAS unsigned char* lds, const Gemm g, const Sched& S, const Epi& E) {
;     ...
;         PG8_STAGE(PG8_SB(0, 0), cB, voffB); PG8_STAGE(PG8_SB(0, 1), cB + hstep, voffB); PG8_STAGE(PG8_SA(0, 0), cA, voffA); PG8_STAGE(PG8_SA(0, 1), cA + hstep, voffA);
;         if (wr == 1) PG8_BAR;
;         PG8_WAIT_V(2); PG8_BAR;
;         PG8_STAGE(PG8_SB(1, 0), cB + kstep, voffB); PG8_STAGE(PG8_SA(1, 0), cA + kstep, voffA); PG8_STAGE(PG8_SB(1, 1), cB + hstep + kstep, voffB);
;         PG8_WAIT_V(6); PG8_BAR;
.LBB0_297:
	s_mov_b64 s[12:13], 0x80
	s_and_b32 s43, s3, 3
	s_add_i32 m0, s35, 0x18000
	v_lshl_add_u64 v[6:7], v[6:7], 0, s[12:13]
	s_lshl_b32 s3, s2, 13
	s_lshl_b32 s7, s43, 12
	s_waitcnt vmcnt(2)
	s_barrier
	global_load_lds_dwordx4 v[6:7], off
	v_lshl_add_u64 v[4:5], v[4:5], 0, s[12:13]
	s_add_i32 m0, s35, 0x1a000
	s_add_i32 s44, s35, 0x8000
	s_add_i32 s45, s35, 0xa000
	global_load_lds_dwordx4 v[4:5], off
	v_lshl_add_u64 v[0:1], v[0:1], 0, s[12:13]
	s_mov_b32 m0, s44
	s_add_u32 s4, s28, 0x80080
	global_load_lds_dwordx4 v[0:1], off
	v_lshl_add_u64 v[0:1], v[2:3], 0, s[12:13]
	s_mov_b32 m0, s45
	s_addc_u32 s5, s29, 0
	global_load_lds_dwordx4 v[0:1], off
	s_add_i32 m0, s35, 0x1c000
	v_lshl_add_u64 v[0:1], s[4:5], 0, v[154:155]
	global_load_lds_dwordx4 v[0:1], off
	v_lshl_add_u64 v[0:1], s[4:5], 0, v[158:159]
	s_add_i32 m0, s35, 0x1e000
	v_lshlrev_b32_e32 v4, 2, v196
	global_load_lds_dwordx4 v[0:1], off
	v_bfe_u32 v0, v196, 4, 2
	v_and_b32_e32 v1, 15, v196
	v_lshlrev_b32_e32 v3, 4, v0
	v_lshl_or_b32 v178, s2, 6, v1
	v_lshl_or_b32 v1, v1, 6, v3
	v_and_b32_e32 v4, 32, v4
	v_lshlrev_b32_e32 v5, 6, v196
	s_movk_i32 s2, 0x3c0
	v_lshlrev_b32_e32 v2, 3, v0
	v_bitop3_b32 v1, v1, s3, v4 bitop3:0xde
	v_and_or_b32 v3, v5, s2, v3
	v_cmp_eq_u32_e64 s[2:3], 0, v0
	v_lshlrev_b32_e32 v0, 9, v196
	v_lshl_or_b32 v180, s43, 5, v2
	v_and_b32_e32 v0, 0x70000, v0
	v_lshlrev_b32_e32 v2, 12, v10
	v_or3_b32 v0, v8, v0, v2
	s_cmpk_lt_u32 s14, 0x100
	v_readlane_b32 s16, v254, 24
	v_add_u32_e32 v160, v0, v9
	v_lshlrev_b32_e32 v0, 5, v11
	s_cselect_b64 s[14:15], -1, 0
	s_ashr_i32 s46, s88, 31
	s_ashr_i32 s47, s89, 31
	v_readlane_b32 s22, v254, 30
	v_readlane_b32 s23, v254, 31
	v_and_b32_e32 v0, 0xf0000, v0
	s_waitcnt vmcnt(0)
	v_readlane_b32 s17, v254, 25
	s_cmp_lg_u64 s[22:23], 0
	v_or3_b32 v0, v8, v0, v2
	v_bitop3_b32 v179, s7, v3, v4 bitop3:0xf6
	s_cselect_b64 s[16:17], -1, 0
	v_add_u32_e32 v162, v0, v9
	s_add_i32 s62, 0, 0x10000
	s_add_i32 s63, 0, 0x14000
	v_mbcnt_lo_u32_b32 v0, -1, 0
	v_readlane_b32 s18, v254, 26
	v_readlane_b32 s20, v254, 28
	v_mov_b32_e32 v161, v155
	v_mov_b32_e32 v163, v155
	v_mov_b64_e32 v[164:165], 0x400
	v_mov_b64_e32 v[166:167], 0x3ff
	v_add_u32_e32 v181, s62, v179
	v_add_u32_e32 v182, s63, v179
	v_add_u32_e32 v183, 0, v1
	v_mbcnt_hi_u32_b32 v184, -1, v0
	s_mov_b32 s64, 0
	s_barrier
	v_readlane_b32 s19, v254, 27
	v_readlane_b32 s21, v254, 29
	s_branch .LBB0_300

; #define PG8_STAGE(bufoff, gbase, voff) do { _Pragma("unroll") for (int _i = 0; _i < 2; ++_i) \
;         __builtin_amdgcn_global_load_lds((const unsigned*)((const char*)(gbase) + (voff)[_i]), (PG8_LAS unsigned*)(lds + (bufoff) + ldsw + _i * 8192), 16, 0, 0); } while (0)
; #define PG8_LDA(dst, b, h) do { _Pragma("unroll") for (int m = 0; m < 4; ++m) _Pragma("unroll") for (int k = 0; k < 2; ++k) dst[m][k] = *(const PG8_LAS bf16x8*)(lds + PG8_SA(b, h) + aoff + m * 2048 + k * 1024); } while (0)
; #define PG8_LDB(dst, b, h) do { _Pragma("unroll") for (int n = 0; n < 2; ++n) _Pragma("unroll") for (int k = 0; k < 2; ++k) dst[n][k] = *(const PG8_LAS bf16x8*)(lds + PG8_SB(b, h) + boff + n * 2048 + k * 1024); } while (0)
; #define PG8_WAIT_V(n) asm volatile("s_waitcnt vmcnt(" #n ")" ::: "memory")
; #define PG8_BAR __builtin_amdgcn_s_barrier()
; template <class Epi, class Sched, bool ALIGN_EPI = false, bool SP2 = false>
; __device__ __forceinline__ void gemm_phase(PG8_LAS unsigned char* lds, const Gemm g, const Sched& S, const Epi& E) {
;     ...
;         const char* nA = has_next ? (const char*)g.A + (size_t)nxt.pm * tstep : cA; const char* nB = has_next ? (const char*)g.Bt + (size_t)nxt.pn * tstep : cB;
;         for (int t = 0; t < nt; t += 2) {
;             const bool last = (t == nt - 2);
;             const char* a1 = cA + (size_t)(t + 1) * kstep;
;             const char* a2 = last ? nA : cA + (size_t)(t + 2) * kstep; const char* b2 = last ? nB : cB + (size_t)(t + 2) * kstep;
;             const char* a3 = a2 + kstep; const char* b3 = b2 + kstep;
;             if (last && has_next) S.a_ready(nxt);
;             if constexpr (SP2) {
;             PG8_LDB(B0, 0, 0); PG8_LDB(B1, 0, 1); PG8_SCHED; PG8_LDA(At, 0, 0); PG8_STAGE(PG8_SA(1, 1), a1 + hstep, voffA);
;             PG8_WAIT_V(8); PG8_WAIT_L(0); PG8_BAR; PG8_MMA(0, 0, At, B0); PG8_MMA(0, 1, At, B1); PG8_BAR; PG8_SCHED;
;             PG8_LDA(At, 0, 1); PG8_STAGE(PG8_SB(0, 0), b2, voffB); PG8_STAGE(PG8_SB(0, 1), b2 + hstep, voffB); PG8_STAGE(PG8_SA(0, 0), a2, voffA);
;     ...
; #pragma unroll
;         for (int a = 0; a < 2; ++a)
; #pragma unroll
;             for (int b = 0; b < 2; ++b)
; #pragma unroll
;                 for (int m = 0; m < 4; ++m)
; #pragma unroll
;                     for (int n = 0; n < 2; ++n) acc[a][b][m][n] = (f32x4){0.f, 0.f, 0.f, 0.f};
;         cur = nxt; cA = nA; cB = nB; ++ui;
.LBB0_306:
	s_ashr_i32 s21, s20, 31
	s_lshl_b64 s[22:23], s[20:21], 20
	s_add_u32 s22, s60, s22
	s_addc_u32 s23, s61, s23
	s_and_b64 s[24:25], s[4:5], exec
	s_cselect_b32 s7, s23, s27
	s_cselect_b32 s21, s22, s26
	s_ashr_i32 s19, s18, 31
	s_lshl_b64 s[24:25], s[18:19], 20
	s_add_u32 s24, s68, s24
	s_addc_u32 s25, s69, s25
	s_and_b64 s[30:31], s[4:5], exec
	s_cselect_b32 s19, s25, s29
	s_cselect_b32 s33, s24, s28
	s_add_u32 s26, s26, 0x80080
	s_addc_u32 s27, s27, 0
	s_add_u32 s48, s28, 0x100
	s_addc_u32 s49, s29, 0
	s_mov_b32 s50, -2
	s_waitcnt lgkmcnt(0)
	s_waitcnt lgkmcnt(0)
	ds_read_b128 v[128:131], v181
	ds_read_b128 v[132:135], v181 offset:1024
	ds_read_b128 v[136:139], v181 offset:2048
	ds_read_b128 v[140:143], v181 offset:3072
	ds_read_b128 v[144:147], v182
	ds_read_b128 v[148:151], v182 offset:1024
	ds_read_b128 v[168:171], v182 offset:2048
	ds_read_b128 v[172:175], v182 offset:3072
	s_add_u32 s28, s26, 0xfff80080
	s_addc_u32 s29, s27, -1
	s_cmp_eq_u32 s50, 28
	s_cselect_b32 s31, s7, s29
	s_cselect_b32 s30, s21, s28
	s_cselect_b32 s29, s19, s49
	s_cselect_b32 s28, s33, s48
	v_lshl_add_u64 v[176:177], s[26:27], 0, v[160:161]
	s_add_i32 m0, s35, 0xc000
	ds_read_b128 v[186:189], v183
	ds_read_b128 v[190:193], v183 offset:1024
	ds_read_b128 v[198:201], v183 offset:2048
	ds_read_b128 v[202:205], v183 offset:3072
	ds_read_b128 v[206:209], v183 offset:4096
	ds_read_b128 v[210:213], v183 offset:5120
	ds_read_b128 v[214:217], v183 offset:6144
	ds_read_b128 v[218:221], v183 offset:7168
	global_load_lds_dwordx4 v[176:177], off
	v_lshl_add_u64 v[176:177], s[26:27], 0, v[162:163]
	s_add_i32 m0, s35, 0xe000
	s_nop 0
	global_load_lds_dwordx4 v[176:177], off
	s_nop 0
	s_waitcnt lgkmcnt(0)
	s_setprio 1
	s_barrier
	v_mfma_f32_16x16x32_bf16 v[124:127], v[128:131], v[186:189], 0
	v_mfma_f32_16x16x32_bf16 v[120:123], v[136:139], v[186:189], 0
	v_mfma_f32_16x16x32_bf16 v[104:107], v[128:131], v[198:201], 0
	v_mfma_f32_16x16x32_bf16 v[108:111], v[136:139], v[198:201], 0
	v_mfma_f32_16x16x32_bf16 v[88:91], v[128:131], v[206:209], 0
	v_mfma_f32_16x16x32_bf16 v[92:95], v[136:139], v[206:209], 0
	v_mfma_f32_16x16x32_bf16 v[72:75], v[128:131], v[214:217], 0
	v_mfma_f32_16x16x32_bf16 v[76:79], v[136:139], v[214:217], 0
	v_mfma_f32_16x16x32_bf16 v[124:127], v[132:135], v[190:193], v[124:127]
	v_mfma_f32_16x16x32_bf16 v[120:123], v[140:143], v[190:193], v[120:123]
	v_mfma_f32_16x16x32_bf16 v[104:107], v[132:135], v[202:205], v[104:107]
	v_mfma_f32_16x16x32_bf16 v[108:111], v[140:143], v[202:205], v[108:111]
	v_mfma_f32_16x16x32_bf16 v[88:91], v[132:135], v[210:213], v[88:91]
	v_mfma_f32_16x16x32_bf16 v[92:95], v[140:143], v[210:213], v[92:95]
	v_mfma_f32_16x16x32_bf16 v[72:75], v[132:135], v[218:221], v[72:75]
	v_mfma_f32_16x16x32_bf16 v[76:79], v[140:143], v[218:221], v[76:79]
	v_mfma_f32_16x16x32_bf16 v[116:119], v[144:147], v[186:189], 0
	v_mfma_f32_16x16x32_bf16 v[112:115], v[168:171], v[186:189], 0
	v_mfma_f32_16x16x32_bf16 v[100:103], v[144:147], v[198:201], 0
	v_mfma_f32_16x16x32_bf16 v[96:99], v[168:171], v[198:201], 0
	v_mfma_f32_16x16x32_bf16 v[84:87], v[144:147], v[206:209], 0
	v_mfma_f32_16x16x32_bf16 v[80:83], v[168:171], v[206:209], 0
	v_mfma_f32_16x16x32_bf16 v[68:71], v[144:147], v[214:217], 0
	v_mfma_f32_16x16x32_bf16 v[64:67], v[168:171], v[214:217], 0
	v_mfma_f32_16x16x32_bf16 v[116:119], v[148:151], v[190:193], v[116:119]
	v_mfma_f32_16x16x32_bf16 v[112:115], v[172:175], v[190:193], v[112:115]
	v_mfma_f32_16x16x32_bf16 v[100:103], v[148:151], v[202:205], v[100:103]
	v_mfma_f32_16x16x32_bf16 v[96:99], v[172:175], v[202:205], v[96:99]
	v_mfma_f32_16x16x32_bf16 v[84:87], v[148:151], v[210:213], v[84:87]
	v_mfma_f32_16x16x32_bf16 v[80:83], v[172:175], v[210:213], v[80:83]
	v_mfma_f32_16x16x32_bf16 v[68:71], v[148:151], v[218:221], v[68:71]
	v_mfma_f32_16x16x32_bf16 v[64:67], v[172:175], v[218:221], v[64:67]
	s_barrier
	s_setprio 0
	s_add_i32 s51, s62, s34
	v_lshl_add_u64 v[176:177], s[28:29], 0, v[154:155]
	s_mov_b32 m0, s51
	ds_read_b128 v[186:189], v183 offset:16384
	ds_read_b128 v[190:193], v183 offset:17408
	ds_read_b128 v[198:201], v183 offset:18432
	ds_read_b128 v[202:205], v183 offset:19456
	ds_read_b128 v[206:209], v183 offset:20480
	ds_read_b128 v[210:213], v183 offset:21504
	ds_read_b128 v[214:217], v183 offset:22528
	ds_read_b128 v[218:221], v183 offset:23552
	global_load_lds_dwordx4 v[176:177], off
	s_add_i32 m0, s51, 0x2000
	s_add_u32 s52, s28, 0x80000
	v_lshl_add_u64 v[194:195], s[28:29], 0, v[158:159]
	s_addc_u32 s53, s29, 0
	s_add_i32 s51, s63, s34
	global_load_lds_dwordx4 v[194:195], off
	v_lshl_add_u64 v[222:223], s[52:53], 0, v[154:155]
	s_mov_b32 m0, s51
	v_lshl_add_u64 v[224:225], s[30:31], 0, v[156:157]
	global_load_lds_dwordx4 v[222:223], off
	v_lshl_add_u64 v[222:223], s[52:53], 0, v[158:159]
	s_add_i32 m0, s51, 0x2000
	s_nop 0
	global_load_lds_dwordx4 v[222:223], off
	v_lshl_add_u64 v[222:223], s[30:31], 0, v[152:153]
	s_mov_b32 m0, s35
	s_nop 0
	global_load_lds_dwordx4 v[222:223], off
	s_mov_b32 m0, s37
	s_nop 0
	global_load_lds_dwordx4 v[224:225], off
	s_nop 0
	s_waitcnt lgkmcnt(0)
	s_setprio 1
	s_barrier
; #define PG8_STAGE(bufoff, gbase, voff) do { _Pragma("unroll") for (int _i = 0; _i < 2; ++_i) \
;         __builtin_amdgcn_global_load_lds((const unsigned*)((const char*)(gbase) + (voff)[_i]), (PG8_LAS unsigned*)(lds + (bufoff) + ldsw + _i * 8192), 16, 0, 0); } while (0)
; #define PG8_LDA(dst, b, h) do { _Pragma("unroll") for (int m = 0; m < 4; ++m) _Pragma("unroll") for (int k = 0; k < 2; ++k) dst[m][k] = *(const PG8_LAS bf16x8*)(lds + PG8_SA(b, h) + aoff + m * 2048 + k * 1024); } while (0)
; #define PG8_LDB(dst, b, h) do { _Pragma("unroll") for (int n = 0; n < 2; ++n) _Pragma("unroll") for (int k = 0; k < 2; ++k) dst[n][k] = *(const PG8_LAS bf16x8*)(lds + PG8_SB(b, h) + boff + n * 2048 + k * 1024); } while (0)
; #define PG8_MMA(ai, bj, At, Bt) do { __builtin_amdgcn_s_setprio(1); _Pragma("unroll") for (int m = 0; m < 4; ++m) _Pragma("unroll") for (int n = 0; n < 2; ++n) _Pragma("unroll") for (int k = 0; k < 2; ++k) \
;         acc[ai][bj][m][n] = __builtin_amdgcn_mfma_f32_16x16x32_bf16(Bt[n][k], At[m][k], acc[ai][bj][m][n], 0, 0, 0); __builtin_amdgcn_s_setprio(0); } while (0)
; #define PG8_WAIT_V(n) asm volatile("s_waitcnt vmcnt(" #n ")" ::: "memory")
; #define PG8_WAIT_L(n) asm volatile("s_waitcnt lgkmcnt(" #n ")" ::: "memory")
; #define PG8_BAR __builtin_amdgcn_s_barrier()
; #define PG8_SCHED __builtin_amdgcn_sched_barrier(0)
; template <class Epi, class Sched, bool ALIGN_EPI = false, bool SP2 = false>
; __device__ __forceinline__ void gemm_phase(PG8_LAS unsigned char* lds, const Gemm g, const Sched& S, const Epi& E) {
;     ...
;             PG8_WAIT_V(8); PG8_WAIT_L(0); PG8_BAR; PG8_MMA(1, 0, At, B0); PG8_MMA(1, 1, At, B1); PG8_BAR; PG8_SCHED;
;             PG8_LDB(B0, 1, 0); PG8_LDB(B1, 1, 1); PG8_SCHED; PG8_LDA(At, 1, 0); PG8_STAGE(PG8_SA(0, 1), a2 + hstep, voffA);
;             PG8_WAIT_V(8); PG8_WAIT_L(0); PG8_BAR; PG8_MMA(0, 0, At, B0); PG8_MMA(0, 1, At, B1); PG8_BAR; PG8_SCHED;
	v_mfma_f32_16x16x32_bf16 v[56:59], v[128:131], v[186:189], 0
	v_mfma_f32_16x16x32_bf16 v[60:63], v[136:139], v[186:189], 0
	v_mfma_f32_16x16x32_bf16 v[40:43], v[128:131], v[198:201], 0
	v_mfma_f32_16x16x32_bf16 v[44:47], v[136:139], v[198:201], 0
	v_mfma_f32_16x16x32_bf16 v[24:27], v[128:131], v[206:209], 0
	v_mfma_f32_16x16x32_bf16 v[28:31], v[136:139], v[206:209], 0
	v_mfma_f32_16x16x32_bf16 v[8:11], v[128:131], v[214:217], 0
	v_mfma_f32_16x16x32_bf16 v[12:15], v[136:139], v[214:217], 0
	v_mfma_f32_16x16x32_bf16 v[56:59], v[132:135], v[190:193], v[56:59]
	v_mfma_f32_16x16x32_bf16 v[60:63], v[140:143], v[190:193], v[60:63]
	v_mfma_f32_16x16x32_bf16 v[40:43], v[132:135], v[202:205], v[40:43]
	v_mfma_f32_16x16x32_bf16 v[44:47], v[140:143], v[202:205], v[44:47]
	v_mfma_f32_16x16x32_bf16 v[24:27], v[132:135], v[210:213], v[24:27]
	v_mfma_f32_16x16x32_bf16 v[28:31], v[140:143], v[210:213], v[28:31]
	v_mfma_f32_16x16x32_bf16 v[8:11], v[132:135], v[218:221], v[8:11]
	v_mfma_f32_16x16x32_bf16 v[12:15], v[140:143], v[218:221], v[12:15]
	v_mfma_f32_16x16x32_bf16 v[52:55], v[144:147], v[186:189], 0
	v_mfma_f32_16x16x32_bf16 v[48:51], v[168:171], v[186:189], 0
	v_mfma_f32_16x16x32_bf16 v[36:39], v[144:147], v[198:201], 0
	v_mfma_f32_16x16x32_bf16 v[32:35], v[168:171], v[198:201], 0
	v_mfma_f32_16x16x32_bf16 v[20:23], v[144:147], v[206:209], 0
	v_mfma_f32_16x16x32_bf16 v[16:19], v[168:171], v[206:209], 0
	v_mfma_f32_16x16x32_bf16 v[4:7], v[144:147], v[214:217], 0
	v_mfma_f32_16x16x32_bf16 v[0:3], v[168:171], v[214:217], 0
	v_mfma_f32_16x16x32_bf16 v[52:55], v[148:151], v[190:193], v[52:55]
	v_mfma_f32_16x16x32_bf16 v[48:51], v[172:175], v[190:193], v[48:51]
	v_mfma_f32_16x16x32_bf16 v[36:39], v[148:151], v[202:205], v[36:39]
	v_mfma_f32_16x16x32_bf16 v[32:35], v[172:175], v[202:205], v[32:35]
	v_mfma_f32_16x16x32_bf16 v[20:23], v[148:151], v[210:213], v[20:23]
	v_mfma_f32_16x16x32_bf16 v[16:19], v[172:175], v[210:213], v[16:19]
	v_mfma_f32_16x16x32_bf16 v[4:7], v[148:151], v[218:221], v[4:7]
	v_mfma_f32_16x16x32_bf16 v[0:3], v[172:175], v[218:221], v[0:3]
	s_barrier
	s_setprio 0
	s_add_i32 s51, 0, 0x18000
	s_add_i32 s52, 0, 0x1c000
	v_add_u32_e32 v140, s51, v179
	v_add_u32_e32 v172, s52, v179
	ds_read_b128 v[128:131], v140
	ds_read_b128 v[132:135], v140 offset:1024
	ds_read_b128 v[136:139], v140 offset:2048
	ds_read_b128 v[140:143], v140 offset:3072
	ds_read_b128 v[144:147], v172
	ds_read_b128 v[148:151], v172 offset:1024
	ds_read_b128 v[168:171], v172 offset:2048
	ds_read_b128 v[172:175], v172 offset:3072
	s_add_u32 s30, s30, 0x80000
	s_addc_u32 s31, s31, 0
	s_mov_b32 m0, s39
	v_lshl_add_u64 v[226:227], s[30:31], 0, v[152:153]
	ds_read_b128 v[186:189], v183 offset:32768
	ds_read_b128 v[190:193], v183 offset:33792
	ds_read_b128 v[198:201], v183 offset:34816
	ds_read_b128 v[202:205], v183 offset:35840
	ds_read_b128 v[206:209], v183 offset:36864
	ds_read_b128 v[210:213], v183 offset:37888
	ds_read_b128 v[214:217], v183 offset:38912
	ds_read_b128 v[218:221], v183 offset:39936
	global_load_lds_dwordx4 v[226:227], off
	v_lshl_add_u64 v[226:227], s[30:31], 0, v[156:157]
	s_mov_b32 m0, s42
	s_nop 0
	global_load_lds_dwordx4 v[226:227], off
	s_waitcnt vmcnt(8)
	s_waitcnt lgkmcnt(0)
	s_setprio 1
	s_barrier
	v_mfma_f32_16x16x32_bf16 v[124:127], v[128:131], v[186:189], v[124:127]
	v_mfma_f32_16x16x32_bf16 v[120:123], v[136:139], v[186:189], v[120:123]
	v_mfma_f32_16x16x32_bf16 v[104:107], v[128:131], v[198:201], v[104:107]
	v_mfma_f32_16x16x32_bf16 v[108:111], v[136:139], v[198:201], v[108:111]
	v_mfma_f32_16x16x32_bf16 v[88:91], v[128:131], v[206:209], v[88:91]
	v_mfma_f32_16x16x32_bf16 v[92:95], v[136:139], v[206:209], v[92:95]
	v_mfma_f32_16x16x32_bf16 v[72:75], v[128:131], v[214:217], v[72:75]
	v_mfma_f32_16x16x32_bf16 v[76:79], v[136:139], v[214:217], v[76:79]
	v_mfma_f32_16x16x32_bf16 v[124:127], v[132:135], v[190:193], v[124:127]
	v_mfma_f32_16x16x32_bf16 v[120:123], v[140:143], v[190:193], v[120:123]
	v_mfma_f32_16x16x32_bf16 v[104:107], v[132:135], v[202:205], v[104:107]
	v_mfma_f32_16x16x32_bf16 v[108:111], v[140:143], v[202:205], v[108:111]
	v_mfma_f32_16x16x32_bf16 v[88:91], v[132:135], v[210:213], v[88:91]
	v_mfma_f32_16x16x32_bf16 v[92:95], v[140:143], v[210:213], v[92:95]
	v_mfma_f32_16x16x32_bf16 v[72:75], v[132:135], v[218:221], v[72:75]
	v_mfma_f32_16x16x32_bf16 v[76:79], v[140:143], v[218:221], v[76:79]
	v_mfma_f32_16x16x32_bf16 v[116:119], v[144:147], v[186:189], v[116:119]
	v_mfma_f32_16x16x32_bf16 v[112:115], v[168:171], v[186:189], v[112:115]
	v_mfma_f32_16x16x32_bf16 v[100:103], v[144:147], v[198:201], v[100:103]
	v_mfma_f32_16x16x32_bf16 v[96:99], v[168:171], v[198:201], v[96:99]
	v_mfma_f32_16x16x32_bf16 v[84:87], v[144:147], v[206:209], v[84:87]
	v_mfma_f32_16x16x32_bf16 v[80:83], v[168:171], v[206:209], v[80:83]
	v_mfma_f32_16x16x32_bf16 v[68:71], v[144:147], v[214:217], v[68:71]
	v_mfma_f32_16x16x32_bf16 v[64:67], v[168:171], v[214:217], v[64:67]
	v_mfma_f32_16x16x32_bf16 v[116:119], v[148:151], v[190:193], v[116:119]
	v_mfma_f32_16x16x32_bf16 v[112:115], v[172:175], v[190:193], v[112:115]
	v_mfma_f32_16x16x32_bf16 v[100:103], v[148:151], v[202:205], v[100:103]
	v_mfma_f32_16x16x32_bf16 v[96:99], v[172:175], v[202:205], v[96:99]
	v_mfma_f32_16x16x32_bf16 v[84:87], v[148:151], v[210:213], v[84:87]
	v_mfma_f32_16x16x32_bf16 v[80:83], v[172:175], v[210:213], v[80:83]
	v_mfma_f32_16x16x32_bf16 v[68:71], v[148:151], v[218:221], v[68:71]
	v_mfma_f32_16x16x32_bf16 v[64:67], v[172:175], v[218:221], v[64:67]
	s_barrier
; #define PG8_STAGE(bufoff, gbase, voff) do { _Pragma("unroll") for (int _i = 0; _i < 2; ++_i) \
;         __builtin_amdgcn_global_load_lds((const unsigned*)((const char*)(gbase) + (voff)[_i]), (PG8_LAS unsigned*)(lds + (bufoff) + ldsw + _i * 8192), 16, 0, 0); } while (0)
; #define PG8_LDA(dst, b, h) do { _Pragma("unroll") for (int m = 0; m < 4; ++m) _Pragma("unroll") for (int k = 0; k < 2; ++k) dst[m][k] = *(const PG8_LAS bf16x8*)(lds + PG8_SA(b, h) + aoff + m * 2048 + k * 1024); } while (0)
; #define PG8_MMA(ai, bj, At, Bt) do { __builtin_amdgcn_s_setprio(1); _Pragma("unroll") for (int m = 0; m < 4; ++m) _Pragma("unroll") for (int n = 0; n < 2; ++n) _Pragma("unroll") for (int k = 0; k < 2; ++k) \
;         acc[ai][bj][m][n] = __builtin_amdgcn_mfma_f32_16x16x32_bf16(Bt[n][k], At[m][k], acc[ai][bj][m][n], 0, 0, 0); __builtin_amdgcn_s_setprio(0); } while (0)
; #define PG8_WAIT_V(n) asm volatile("s_waitcnt vmcnt(" #n ")" ::: "memory")
; #define PG8_WAIT_L(n) asm volatile("s_waitcnt lgkmcnt(" #n ")" ::: "memory")
; #define PG8_BAR __builtin_amdgcn_s_barrier()
; #define PG8_SCHED __builtin_amdgcn_sched_barrier(0)
; template <class Epi, class Sched, bool ALIGN_EPI = false, bool SP2 = false>
; __device__ __forceinline__ void gemm_phase(PG8_LAS unsigned char* lds, const Gemm g, const Sched& S, const Epi& E) {
;     ...
;             PG8_LDA(At, 1, 1); PG8_STAGE(PG8_SB(1, 0), b3, voffB); PG8_STAGE(PG8_SB(1, 1), b3 + hstep, voffB); PG8_STAGE(PG8_SA(1, 0), a3, voffA);
;             PG8_WAIT_V(8); PG8_WAIT_L(0); PG8_BAR; PG8_MMA(1, 0, At, B0); PG8_MMA(1, 1, At, B1); PG8_BAR; PG8_SCHED;
	s_setprio 0
	s_add_i32 s30, s51, s34
	v_lshl_add_u64 v[176:177], v[176:177], 0, s[12:13]
	s_mov_b32 m0, s30
	ds_read_b128 v[186:189], v183 offset:49152
	ds_read_b128 v[190:193], v183 offset:50176
	ds_read_b128 v[198:201], v183 offset:51200
	ds_read_b128 v[202:205], v183 offset:52224
	ds_read_b128 v[206:209], v183 offset:53248
	ds_read_b128 v[210:213], v183 offset:54272
	ds_read_b128 v[214:217], v183 offset:55296
	ds_read_b128 v[218:221], v183 offset:56320
	global_load_lds_dwordx4 v[176:177], off
	s_add_i32 m0, s30, 0x2000
	s_add_u32 s28, s28, 0x80080
	v_lshl_add_u64 v[176:177], v[194:195], 0, s[12:13]
	s_addc_u32 s29, s29, 0
	s_add_i32 s30, s52, s34
	global_load_lds_dwordx4 v[176:177], off
	v_lshl_add_u64 v[176:177], s[28:29], 0, v[154:155]
	s_mov_b32 m0, s30
	s_nop 0
	global_load_lds_dwordx4 v[176:177], off
	v_lshl_add_u64 v[176:177], s[28:29], 0, v[158:159]
	s_add_i32 m0, s30, 0x2000
	s_nop 0
	global_load_lds_dwordx4 v[176:177], off
	v_lshl_add_u64 v[176:177], v[222:223], 0, s[12:13]
	s_mov_b32 m0, s44
	s_nop 0
	global_load_lds_dwordx4 v[176:177], off
	v_lshl_add_u64 v[176:177], v[224:225], 0, s[12:13]
	s_mov_b32 m0, s45
	s_nop 0
	global_load_lds_dwordx4 v[176:177], off
	s_waitcnt vmcnt(8)
	s_waitcnt lgkmcnt(0)
	s_setprio 1
	s_barrier
	v_mfma_f32_16x16x32_bf16 v[56:59], v[128:131], v[186:189], v[56:59]
	v_mfma_f32_16x16x32_bf16 v[60:63], v[136:139], v[186:189], v[60:63]
	v_mfma_f32_16x16x32_bf16 v[40:43], v[128:131], v[198:201], v[40:43]
	v_mfma_f32_16x16x32_bf16 v[44:47], v[136:139], v[198:201], v[44:47]
	v_mfma_f32_16x16x32_bf16 v[24:27], v[128:131], v[206:209], v[24:27]
	v_mfma_f32_16x16x32_bf16 v[28:31], v[136:139], v[206:209], v[28:31]
	v_mfma_f32_16x16x32_bf16 v[8:11], v[128:131], v[214:217], v[8:11]
	v_mfma_f32_16x16x32_bf16 v[12:15], v[136:139], v[214:217], v[12:15]
	v_mfma_f32_16x16x32_bf16 v[56:59], v[132:135], v[190:193], v[56:59]
	v_mfma_f32_16x16x32_bf16 v[60:63], v[140:143], v[190:193], v[60:63]
	v_mfma_f32_16x16x32_bf16 v[40:43], v[132:135], v[202:205], v[40:43]
	v_mfma_f32_16x16x32_bf16 v[44:47], v[140:143], v[202:205], v[44:47]
	v_mfma_f32_16x16x32_bf16 v[24:27], v[132:135], v[210:213], v[24:27]
	v_mfma_f32_16x16x32_bf16 v[28:31], v[140:143], v[210:213], v[28:31]
	v_mfma_f32_16x16x32_bf16 v[8:11], v[132:135], v[218:221], v[8:11]
	v_mfma_f32_16x16x32_bf16 v[12:15], v[140:143], v[218:221], v[12:15]
	v_mfma_f32_16x16x32_bf16 v[52:55], v[144:147], v[186:189], v[52:55]
	v_mfma_f32_16x16x32_bf16 v[48:51], v[168:171], v[186:189], v[48:51]
	v_mfma_f32_16x16x32_bf16 v[36:39], v[144:147], v[198:201], v[36:39]
	v_mfma_f32_16x16x32_bf16 v[32:35], v[168:171], v[198:201], v[32:35]
	v_mfma_f32_16x16x32_bf16 v[20:23], v[144:147], v[206:209], v[20:23]
	v_mfma_f32_16x16x32_bf16 v[16:19], v[168:171], v[206:209], v[16:19]
	v_mfma_f32_16x16x32_bf16 v[4:7], v[144:147], v[214:217], v[4:7]
	v_mfma_f32_16x16x32_bf16 v[0:3], v[168:171], v[214:217], v[0:3]
	v_mfma_f32_16x16x32_bf16 v[52:55], v[148:151], v[190:193], v[52:55]
	v_mfma_f32_16x16x32_bf16 v[48:51], v[172:175], v[190:193], v[48:51]
	v_mfma_f32_16x16x32_bf16 v[36:39], v[148:151], v[202:205], v[36:39]
	v_mfma_f32_16x16x32_bf16 v[32:35], v[172:175], v[202:205], v[32:35]
	v_mfma_f32_16x16x32_bf16 v[20:23], v[148:151], v[210:213], v[20:23]
	v_mfma_f32_16x16x32_bf16 v[16:19], v[172:175], v[210:213], v[16:19]
	v_mfma_f32_16x16x32_bf16 v[4:7], v[148:151], v[218:221], v[4:7]
	v_mfma_f32_16x16x32_bf16 v[0:3], v[172:175], v[218:221], v[0:3]
	s_barrier
	s_setprio 0
	s_add_i32 s50, s50, 2
	s_add_u32 s26, s26, 0x100
	s_addc_u32 s27, s27, 0
	s_add_u32 s48, s48, 0x100
	s_addc_u32 s49, s49, 0

; #define PG8_STAGE(bufoff, gbase, voff) do { _Pragma("unroll") for (int _i = 0; _i < 2; ++_i) \
;         __builtin_amdgcn_global_load_lds((const unsigned*)((const char*)(gbase) + (voff)[_i]), (PG8_LAS unsigned*)(lds + (bufoff) + ldsw + _i * 8192), 16, 0, 0); } while (0)
; #define PG8_WAIT_V(n) asm volatile("s_waitcnt vmcnt(" #n ")" ::: "memory")
; #define PG8_BAR __builtin_amdgcn_s_barrier()
; template <class Epi, class Sched, bool ALIGN_EPI = false, bool SP2 = false>
; __device__ __forceinline__ void gemm_phase(PG8_LAS unsigned char* lds, const Gemm g, const Sched& S, const Epi& E) {
;     ...
;         PG8_STAGE(PG8_SB(0, 0), cB, voffB); PG8_STAGE(PG8_SB(0, 1), cB + hstep, voffB); PG8_STAGE(PG8_SA(0, 0), cA, voffA); PG8_STAGE(PG8_SA(0, 1), cA + hstep, voffA);
;         if (wr == 1) PG8_BAR;
;         PG8_WAIT_V(2); PG8_BAR;
;         PG8_STAGE(PG8_SB(1, 0), cB + kstep, voffB); PG8_STAGE(PG8_SA(1, 0), cA + kstep, voffA); PG8_STAGE(PG8_SB(1, 1), cB + hstep + kstep, voffB);
;         PG8_WAIT_V(6); PG8_BAR;
;     __device__ __forceinline__ void operator()(const f32x4 (&acc)[2][2][4][2], const Unit& u, int wr, int wc, int fr, int fq) const {
;     ...
;         const float l2g = log2f(1.f - exp2f(-5.f - (float)h));
;         float invf[8], g1[8], g2[8];
; #pragma unroll
;         for (int j = 0; j < 8; ++j) { invf[j] = exp2f(-(float)(d0 + j) * (13.287712379549449f / 128.f)); g1[j] = gn[d0 + j]; g2[j] = gn[128 + d0 + j]; }
.LBB0_484:
	v_bfe_u32 v13, v196, 4, 2
	v_and_b32_e32 v12, 15, v196
	v_lshlrev_b32_e32 v15, 4, v13
	v_lshlrev_b32_e32 v17, 2, v196
	s_and_b32 s5, s0, 3
	v_lshl_or_b32 v16, v12, 6, v15
	s_lshl_b32 s0, s1, 13
	v_and_b32_e32 v17, 32, v17
	s_mov_b64 s[10:11], 0x80
	v_bitop3_b32 v16, v16, s0, v17 bitop3:0xde
	v_lshlrev_b32_e32 v18, 6, v196
	s_movk_i32 s0, 0x3c0
	s_add_i32 m0, s17, 0x18000
	v_lshl_add_u64 v[6:7], v[6:7], 0, s[10:11]
	v_and_or_b32 v15, v18, s0, v15
	s_lshl_b32 s0, s5, 12
	s_waitcnt vmcnt(2)
	s_barrier
	global_load_lds_dwordx4 v[6:7], off
	v_lshl_add_u64 v[4:5], v[4:5], 0, s[10:11]
	s_add_i32 m0, s17, 0x1a000
	s_add_i32 s43, s17, 0x8000
	s_add_i32 s46, s17, 0xa000
	v_bitop3_b32 v163, s0, v15, v17 bitop3:0xf6
	global_load_lds_dwordx4 v[4:5], off
	v_lshl_add_u64 v[0:1], v[0:1], 0, s[10:11]
	s_mov_b32 m0, s43
	s_add_u32 s0, s28, 0x80080
	v_lshl_or_b32 v155, s1, 6, v12
	global_load_lds_dwordx4 v[0:1], off
	v_lshl_add_u64 v[0:1], v[2:3], 0, s[10:11]
	s_mov_b32 m0, s46
	s_addc_u32 s1, s29, 0
	v_lshlrev_b32_e32 v14, 3, v13
	global_load_lds_dwordx4 v[0:1], off
	s_add_i32 m0, s17, 0x1c000
	v_lshl_add_u64 v[0:1], s[0:1], 0, v[146:147]
	global_load_lds_dwordx4 v[0:1], off
	v_lshl_add_u64 v[0:1], s[0:1], 0, v[150:151]
	s_add_i32 m0, s17, 0x1e000
	v_lshl_or_b32 v154, s5, 5, v14
	global_load_lds_dwordx4 v[0:1], off
	v_cvt_f32_ubyte0_e32 v0, v154
	v_mul_f32_e32 v1, 0xbdd49a78, v0
	s_mov_b32 s47, 0xc2fc0000
	v_mov_b32_e32 v167, 0x42800000
	v_cmp_gt_f32_e32 vcc, s47, v1
	v_not_b32_e32 v169, 63
	s_cmpk_lt_u32 s2, 0x100
	v_cndmask_b32_e32 v1, 0, v167, vcc
	v_fmac_f32_e32 v1, 0xbdd49a78, v0
	v_exp_f32_e32 v0, v1
	v_or_b32_e32 v1, 1, v154
	v_cvt_f32_ubyte0_e32 v1, v1
	v_mul_f32_e32 v2, 0xbdd49a78, v1
	v_cmp_gt_f32_e64 s[0:1], s47, v2
	s_cselect_b64 s[12:13], -1, 0
	s_waitcnt vmcnt(0)
	v_add_u32_e32 v160, 0xb0, v155
	v_cndmask_b32_e64 v2, 0, v167, s[0:1]
	v_fmac_f32_e32 v2, 0xbdd49a78, v1
	v_exp_f32_e32 v1, v2
	v_cndmask_b32_e32 v2, 0, v169, vcc
	v_ldexp_f32 v171, v0, v2
	v_cndmask_b32_e64 v0, 0, v169, s[0:1]
	v_ldexp_f32 v175, v1, v0
	v_or_b32_e32 v0, 2, v154
	v_cvt_f32_ubyte0_e32 v0, v0
	v_mul_f32_e32 v1, 0xbdd49a78, v0
	v_cmp_gt_f32_e32 vcc, s47, v1
	v_cmp_eq_u32_e64 s[2:3], 0, v13
	v_lshlrev_b32_e32 v165, 4, v155
	v_cndmask_b32_e32 v1, 0, v167, vcc
	v_fmac_f32_e32 v1, 0xbdd49a78, v0
	v_exp_f32_e32 v0, v1
	v_or_b32_e32 v1, 3, v154
	v_cvt_f32_ubyte0_e32 v1, v1
	v_mul_f32_e32 v2, 0xbdd49a78, v1
	v_cmp_gt_f32_e64 s[0:1], s47, v2
	v_or_b32_e32 v195, 16, v155
	v_or_b32_e32 v200, 32, v155
	v_cndmask_b32_e64 v2, 0, v167, s[0:1]
	v_fmac_f32_e32 v2, 0xbdd49a78, v1
	v_exp_f32_e32 v1, v2
	v_cndmask_b32_e32 v2, 0, v169, vcc
	v_ldexp_f32 v179, v0, v2
	v_cndmask_b32_e64 v0, 0, v169, s[0:1]
	v_ldexp_f32 v183, v1, v0
	v_or_b32_e32 v0, 4, v154
	v_cvt_f32_ubyte0_e32 v0, v0
	v_mul_f32_e32 v1, 0xbdd49a78, v0
	v_cmp_gt_f32_e32 vcc, s47, v1
	v_or_b32_e32 v203, 48, v155
	v_add_u32_e32 v197, 0x80, v155
	v_cndmask_b32_e32 v1, 0, v167, vcc
	v_fmac_f32_e32 v1, 0xbdd49a78, v0
	v_exp_f32_e32 v0, v1
	v_or_b32_e32 v1, 5, v154
	v_cvt_f32_ubyte0_e32 v1, v1
	v_mul_f32_e32 v2, 0xbdd49a78, v1
	v_cmp_gt_f32_e64 s[0:1], s47, v2
	v_add_u32_e32 v201, 0x90, v155
	v_add_u32_e32 v198, 0xa0, v155
	v_cndmask_b32_e64 v2, 0, v167, s[0:1]
	v_fmac_f32_e32 v2, 0xbdd49a78, v1
	v_exp_f32_e32 v1, v2
	v_cndmask_b32_e32 v2, 0, v169, vcc
	v_ldexp_f32 v190, v0, v2
	v_cndmask_b32_e64 v0, 0, v169, s[0:1]
	v_ldexp_f32 v191, v1, v0
	v_or_b32_e32 v0, 6, v154
	v_cvt_f32_ubyte0_e32 v0, v0
	v_mul_f32_e32 v1, 0xbdd49a78, v0
	v_cmp_gt_f32_e32 vcc, s47, v1
	v_lshlrev_b32_e32 v161, 4, v160
	s_ashr_i32 s64, s88, 31
	v_cndmask_b32_e32 v1, 0, v167, vcc
	v_fmac_f32_e32 v1, 0xbdd49a78, v0
	v_exp_f32_e32 v0, v1
	v_or_b32_e32 v1, 7, v154
	v_cvt_f32_ubyte0_e32 v1, v1
	v_mul_f32_e32 v2, 0xbdd49a78, v1
	v_cmp_gt_f32_e64 s[0:1], s47, v2
	s_ashr_i32 s65, s89, 31
	v_mov_b32_e32 v157, v153
	v_cndmask_b32_e64 v2, 0, v167, s[0:1]
	v_fmac_f32_e32 v2, 0xbdd49a78, v1
	v_exp_f32_e32 v1, v2
	v_cndmask_b32_e32 v2, 0, v169, vcc
	v_ldexp_f32 v192, v0, v2
	v_cndmask_b32_e64 v0, 0, v169, s[0:1]
	v_ldexp_f32 v193, v1, v0
	v_add_u32_e32 v0, 1, v12
	v_cvt_f32_ubyte0_e32 v194, v0
	v_add_u32_e32 v0, 17, v12
	v_cvt_f32_ubyte0_e32 v199, v0
	v_add_u32_e32 v0, 33, v12
	v_cvt_f32_ubyte0_e32 v202, v0
	v_add_u32_e32 v0, 49, v12
	v_cvt_f32_ubyte0_e32 v205, v0
	v_cvt_f32_u32_e32 v0, s15
	v_lshlrev_b32_e32 v1, 12, v10
	s_lshl_b32 s0, s5, 2
	s_add_i32 s66, s0, 0
	v_rcp_iflag_f32_e32 v0, v0
	s_sub_i32 s0, 0, s15
	s_add_i32 s66, s66, 0x20000
	v_mov_b32_e32 v159, v153
	v_mul_f32_e32 v0, 0x4f7ffffe, v0
	v_cvt_u32_f32_e32 v0, v0
	s_add_i32 s68, 0, 0x10000
	s_add_i32 s69, 0, 0x14000
	v_add_u32_e32 v214, 0, v16
	v_readfirstlane_b32 s1, v0
	v_lshlrev_b32_e32 v0, 9, v196
	v_and_b32_e32 v0, 0x70000, v0
	v_or3_b32 v0, v8, v0, v1
	v_add_u32_e32 v156, v0, v9
	v_lshlrev_b32_e32 v0, 5, v11
	v_and_b32_e32 v0, 0xf0000, v0
	s_mul_i32 s0, s0, s1
	v_or3_b32 v0, v8, v0, v1
	s_mul_hi_u32 s0, s1, s0
	v_add_u32_e32 v158, v0, v9
	v_mbcnt_lo_u32_b32 v0, -1, 0
	s_add_i32 s67, s1, s0
	s_mov_b32 s70, 0x800000
	s_mov_b32 s71, 0x3d800000
	s_mov_b32 s14, 0x3b800000
	v_mbcnt_hi_u32_b32 v215, -1, v0
	v_mov_b32_e32 v204, 0x42000000
	s_barrier
	s_branch .LBB0_487

; #define PG8_STAGE(bufoff, gbase, voff) do { _Pragma("unroll") for (int _i = 0; _i < 2; ++_i) \
;         __builtin_amdgcn_global_load_lds((const unsigned*)((const char*)(gbase) + (voff)[_i]), (PG8_LAS unsigned*)(lds + (bufoff) + ldsw + _i * 8192), 16, 0, 0); } while (0)
; #define PG8_LDA(dst, b, h) do { _Pragma("unroll") for (int m = 0; m < 4; ++m) _Pragma("unroll") for (int k = 0; k < 2; ++k) dst[m][k] = *(const PG8_LAS bf16x8*)(lds + PG8_SA(b, h) + aoff + m * 2048 + k * 1024); } while (0)
; #define PG8_LDB(dst, b, h) do { _Pragma("unroll") for (int n = 0; n < 2; ++n) _Pragma("unroll") for (int k = 0; k < 2; ++k) dst[n][k] = *(const PG8_LAS bf16x8*)(lds + PG8_SB(b, h) + boff + n * 2048 + k * 1024); } while (0)
; #define PG8_WAIT_V(n) asm volatile("s_waitcnt vmcnt(" #n ")" ::: "memory")
; #define PG8_BAR __builtin_amdgcn_s_barrier()
; template <class Epi, class Sched, bool ALIGN_EPI = false, bool SP2 = false>
; __device__ __forceinline__ void gemm_phase(PG8_LAS unsigned char* lds, const Gemm g, const Sched& S, const Epi& E) {
;     ...
;         const char* nA = has_next ? (const char*)g.A + (size_t)nxt.pm * tstep : cA; const char* nB = has_next ? (const char*)g.Bt + (size_t)nxt.pn * tstep : cB;
;         for (int t = 0; t < nt; t += 2) {
;             const bool last = (t == nt - 2);
;             const char* a1 = cA + (size_t)(t + 1) * kstep;
;             const char* a2 = last ? nA : cA + (size_t)(t + 2) * kstep; const char* b2 = last ? nB : cB + (size_t)(t + 2) * kstep;
;             const char* a3 = a2 + kstep; const char* b3 = b2 + kstep;
;             if (last && has_next) S.a_ready(nxt);
;             if constexpr (SP2) {
;             PG8_LDB(B0, 0, 0); PG8_LDB(B1, 0, 1); PG8_SCHED; PG8_LDA(At, 0, 0); PG8_STAGE(PG8_SA(1, 1), a1 + hstep, voffA);
;             PG8_WAIT_V(8); PG8_WAIT_L(0); PG8_BAR; PG8_MMA(0, 0, At, B0); PG8_MMA(0, 1, At, B1); PG8_BAR; PG8_SCHED;
;             PG8_LDA(At, 0, 1); PG8_STAGE(PG8_SB(0, 0), b2, voffB); PG8_STAGE(PG8_SB(0, 1), b2 + hstep, voffB); PG8_STAGE(PG8_SA(0, 0), a2, voffA);
;     ...
; #pragma unroll
;         for (int a = 0; a < 2; ++a)
; #pragma unroll
;             for (int b = 0; b < 2; ++b)
; #pragma unroll
;                 for (int m = 0; m < 4; ++m)
; #pragma unroll
;                     for (int n = 0; n < 2; ++n) acc[a][b][m][n] = (f32x4){0.f, 0.f, 0.f, 0.f};
;         cur = nxt; cA = nA; cB = nB; ++ui;
.LBB0_490:
	s_ashr_i32 s21, s20, 31
	s_lshl_b64 s[0:1], s[20:21], 20
	v_readlane_b32 s24, v254, 51
	v_readlane_b32 s25, v254, 52
	s_add_u32 s24, s24, s0
	s_addc_u32 s25, s25, s1
	s_and_b64 s[0:1], s[22:23], exec
	s_cselect_b32 s5, s25, s31
	s_cselect_b32 s21, s24, s30
	s_ashr_i32 s19, s18, 31
	s_lshl_b64 s[0:1], s[18:19], 20
	v_readlane_b32 s26, v254, 22
	v_readlane_b32 s27, v254, 23
	s_add_u32 s26, s26, s0
	s_addc_u32 s27, s27, s1
	s_and_b64 s[0:1], s[22:23], exec
	s_cselect_b32 s19, s27, s29
	s_cselect_b32 s33, s26, s28
	s_add_u32 s0, s30, 0x80080
	s_addc_u32 s1, s31, 0
	s_add_u32 s44, s28, 0x100
	s_addc_u32 s45, s29, 0
	s_mov_b32 s48, -2
	v_add_u32_e32 v140, s68, v163
	v_add_u32_e32 v152, s69, v163
	ds_read_b128 v[128:131], v140
	ds_read_b128 v[132:135], v140 offset:1024
	ds_read_b128 v[136:139], v140 offset:2048
	ds_read_b128 v[140:143], v140 offset:3072
	ds_read_b128 v[184:187], v152
	ds_read_b128 v[218:221], v152 offset:1024
	ds_read_b128 v[222:225], v152 offset:2048
	ds_read_b128 v[226:229], v152 offset:3072
	s_add_u32 s28, s0, 0xfff80080
	s_addc_u32 s29, s1, -1
	s_cmp_eq_u32 s48, 28
	s_cselect_b32 s31, s5, s29
	s_cselect_b32 s30, s21, s28
	s_cselect_b32 s29, s19, s45
	s_cselect_b32 s28, s33, s44
	v_lshl_add_u64 v[172:173], s[0:1], 0, v[156:157]
	s_add_i32 m0, s17, 0xc000
	ds_read_b128 v[230:233], v214
	ds_read_b128 v[234:237], v214 offset:1024
	ds_read_b128 v[238:241], v214 offset:2048
	ds_read_b128 v[242:245], v214 offset:3072
	ds_read_b128 v[246:249], v214 offset:4096
	ds_read_b128 v[250:253], v214 offset:5120
	ds_read_b128 v[206:209], v214 offset:6144
	ds_read_b128 v[210:213], v214 offset:7168
	global_load_lds_dwordx4 v[172:173], off
	v_lshl_add_u64 v[172:173], s[0:1], 0, v[158:159]
	s_add_i32 m0, s17, 0xe000
	s_nop 0
	global_load_lds_dwordx4 v[172:173], off
	s_nop 0
	s_waitcnt lgkmcnt(0)
	s_setprio 1
	s_barrier
	v_mfma_f32_16x16x32_bf16 v[124:127], v[128:131], v[230:233], 0
	v_mfma_f32_16x16x32_bf16 v[120:123], v[136:139], v[230:233], 0
	v_mfma_f32_16x16x32_bf16 v[116:119], v[128:131], v[238:241], 0
	v_mfma_f32_16x16x32_bf16 v[108:111], v[136:139], v[238:241], 0
	v_mfma_f32_16x16x32_bf16 v[100:103], v[128:131], v[246:249], 0
	v_mfma_f32_16x16x32_bf16 v[92:95], v[136:139], v[246:249], 0
	v_mfma_f32_16x16x32_bf16 v[84:87], v[128:131], v[206:209], 0
	v_mfma_f32_16x16x32_bf16 v[76:79], v[136:139], v[206:209], 0
	v_mfma_f32_16x16x32_bf16 v[124:127], v[132:135], v[234:237], v[124:127]
	v_mfma_f32_16x16x32_bf16 v[120:123], v[140:143], v[234:237], v[120:123]
	v_mfma_f32_16x16x32_bf16 v[116:119], v[132:135], v[242:245], v[116:119]
	v_mfma_f32_16x16x32_bf16 v[108:111], v[140:143], v[242:245], v[108:111]
	v_mfma_f32_16x16x32_bf16 v[100:103], v[132:135], v[250:253], v[100:103]
	v_mfma_f32_16x16x32_bf16 v[92:95], v[140:143], v[250:253], v[92:95]
	v_mfma_f32_16x16x32_bf16 v[84:87], v[132:135], v[210:213], v[84:87]
	v_mfma_f32_16x16x32_bf16 v[76:79], v[140:143], v[210:213], v[76:79]
	v_mfma_f32_16x16x32_bf16 v[112:115], v[184:187], v[230:233], 0
	v_mfma_f32_16x16x32_bf16 v[104:107], v[222:225], v[230:233], 0
	v_mfma_f32_16x16x32_bf16 v[96:99], v[184:187], v[238:241], 0
	v_mfma_f32_16x16x32_bf16 v[88:91], v[222:225], v[238:241], 0
	v_mfma_f32_16x16x32_bf16 v[80:83], v[184:187], v[246:249], 0
	v_mfma_f32_16x16x32_bf16 v[72:75], v[222:225], v[246:249], 0
	v_mfma_f32_16x16x32_bf16 v[68:71], v[184:187], v[206:209], 0
	v_mfma_f32_16x16x32_bf16 v[64:67], v[222:225], v[206:209], 0
	v_mfma_f32_16x16x32_bf16 v[112:115], v[218:221], v[234:237], v[112:115]
	v_mfma_f32_16x16x32_bf16 v[104:107], v[226:229], v[234:237], v[104:107]
	v_mfma_f32_16x16x32_bf16 v[96:99], v[218:221], v[242:245], v[96:99]
	v_mfma_f32_16x16x32_bf16 v[88:91], v[226:229], v[242:245], v[88:91]
	v_mfma_f32_16x16x32_bf16 v[80:83], v[218:221], v[250:253], v[80:83]
	v_mfma_f32_16x16x32_bf16 v[72:75], v[226:229], v[250:253], v[72:75]
	v_mfma_f32_16x16x32_bf16 v[68:71], v[218:221], v[210:213], v[68:71]
	v_mfma_f32_16x16x32_bf16 v[64:67], v[226:229], v[210:213], v[64:67]
	s_barrier
	s_setprio 0
	s_add_i32 s49, s68, s34
	v_lshl_add_u64 v[172:173], s[28:29], 0, v[146:147]
	s_mov_b32 m0, s49
	ds_read_b128 v[206:209], v214 offset:16384
	ds_read_b128 v[210:213], v214 offset:17408
	ds_read_b128 v[230:233], v214 offset:18432
	ds_read_b128 v[234:237], v214 offset:19456
	ds_read_b128 v[238:241], v214 offset:20480
	ds_read_b128 v[242:245], v214 offset:21504
	ds_read_b128 v[246:249], v214 offset:22528
	ds_read_b128 v[250:253], v214 offset:23552
	global_load_lds_dwordx4 v[172:173], off
	s_add_i32 m0, s49, 0x2000
	s_add_u32 s50, s28, 0x80000
	v_lshl_add_u64 v[176:177], s[28:29], 0, v[150:151]
	s_addc_u32 s51, s29, 0
	s_add_i32 s49, s69, s34
	global_load_lds_dwordx4 v[176:177], off
	v_lshl_add_u64 v[180:181], s[50:51], 0, v[146:147]
	s_mov_b32 m0, s49
	v_lshl_add_u64 v[188:189], s[30:31], 0, v[148:149]
	global_load_lds_dwordx4 v[180:181], off
	v_lshl_add_u64 v[180:181], s[50:51], 0, v[150:151]
	s_add_i32 m0, s49, 0x2000
	s_nop 0
	global_load_lds_dwordx4 v[180:181], off
	v_lshl_add_u64 v[180:181], s[30:31], 0, v[144:145]
	s_mov_b32 m0, s17
	s_nop 0
	global_load_lds_dwordx4 v[180:181], off
	s_mov_b32 m0, s35
	s_nop 0
	global_load_lds_dwordx4 v[188:189], off
	s_nop 0
	s_waitcnt lgkmcnt(0)
	s_setprio 1
	s_barrier
; #define PG8_STAGE(bufoff, gbase, voff) do { _Pragma("unroll") for (int _i = 0; _i < 2; ++_i) \
;         __builtin_amdgcn_global_load_lds((const unsigned*)((const char*)(gbase) + (voff)[_i]), (PG8_LAS unsigned*)(lds + (bufoff) + ldsw + _i * 8192), 16, 0, 0); } while (0)
; #define PG8_LDA(dst, b, h) do { _Pragma("unroll") for (int m = 0; m < 4; ++m) _Pragma("unroll") for (int k = 0; k < 2; ++k) dst[m][k] = *(const PG8_LAS bf16x8*)(lds + PG8_SA(b, h) + aoff + m * 2048 + k * 1024); } while (0)
; #define PG8_LDB(dst, b, h) do { _Pragma("unroll") for (int n = 0; n < 2; ++n) _Pragma("unroll") for (int k = 0; k < 2; ++k) dst[n][k] = *(const PG8_LAS bf16x8*)(lds + PG8_SB(b, h) + boff + n * 2048 + k * 1024); } while (0)
; #define PG8_MMA(ai, bj, At, Bt) do { __builtin_amdgcn_s_setprio(1); _Pragma("unroll") for (int m = 0; m < 4; ++m) _Pragma("unroll") for (int n = 0; n < 2; ++n) _Pragma("unroll") for (int k = 0; k < 2; ++k) \
;         acc[ai][bj][m][n] = __builtin_amdgcn_mfma_f32_16x16x32_bf16(Bt[n][k], At[m][k], acc[ai][bj][m][n], 0, 0, 0); __builtin_amdgcn_s_setprio(0); } while (0)
; #define PG8_WAIT_V(n) asm volatile("s_waitcnt vmcnt(" #n ")" ::: "memory")
; #define PG8_WAIT_L(n) asm volatile("s_waitcnt lgkmcnt(" #n ")" ::: "memory")
; #define PG8_BAR __builtin_amdgcn_s_barrier()
; #define PG8_SCHED __builtin_amdgcn_sched_barrier(0)
; template <class Epi, class Sched, bool ALIGN_EPI = false, bool SP2 = false>
; __device__ __forceinline__ void gemm_phase(PG8_LAS unsigned char* lds, const Gemm g, const Sched& S, const Epi& E) {
;     ...
;             PG8_WAIT_V(8); PG8_WAIT_L(0); PG8_BAR; PG8_MMA(1, 0, At, B0); PG8_MMA(1, 1, At, B1); PG8_BAR; PG8_SCHED;
;             PG8_LDB(B0, 1, 0); PG8_LDB(B1, 1, 1); PG8_SCHED; PG8_LDA(At, 1, 0); PG8_STAGE(PG8_SA(0, 1), a2 + hstep, voffA);
;             PG8_WAIT_V(8); PG8_WAIT_L(0); PG8_BAR; PG8_MMA(0, 0, At, B0); PG8_MMA(0, 1, At, B1); PG8_BAR; PG8_SCHED;
	v_mfma_f32_16x16x32_bf16 v[60:63], v[128:131], v[206:209], 0
	v_mfma_f32_16x16x32_bf16 v[56:59], v[136:139], v[206:209], 0
	v_mfma_f32_16x16x32_bf16 v[52:55], v[128:131], v[230:233], 0
	v_mfma_f32_16x16x32_bf16 v[44:47], v[136:139], v[230:233], 0
	v_mfma_f32_16x16x32_bf16 v[36:39], v[128:131], v[238:241], 0
	v_mfma_f32_16x16x32_bf16 v[28:31], v[136:139], v[238:241], 0
	v_mfma_f32_16x16x32_bf16 v[20:23], v[128:131], v[246:249], 0
	v_mfma_f32_16x16x32_bf16 v[12:15], v[136:139], v[246:249], 0
	v_mfma_f32_16x16x32_bf16 v[60:63], v[132:135], v[210:213], v[60:63]
	v_mfma_f32_16x16x32_bf16 v[56:59], v[140:143], v[210:213], v[56:59]
	v_mfma_f32_16x16x32_bf16 v[52:55], v[132:135], v[234:237], v[52:55]
	v_mfma_f32_16x16x32_bf16 v[44:47], v[140:143], v[234:237], v[44:47]
	v_mfma_f32_16x16x32_bf16 v[36:39], v[132:135], v[242:245], v[36:39]
	v_mfma_f32_16x16x32_bf16 v[28:31], v[140:143], v[242:245], v[28:31]
	v_mfma_f32_16x16x32_bf16 v[20:23], v[132:135], v[250:253], v[20:23]
	v_mfma_f32_16x16x32_bf16 v[12:15], v[140:143], v[250:253], v[12:15]
	v_mfma_f32_16x16x32_bf16 v[48:51], v[184:187], v[206:209], 0
	v_mfma_f32_16x16x32_bf16 v[40:43], v[222:225], v[206:209], 0
	v_mfma_f32_16x16x32_bf16 v[32:35], v[184:187], v[230:233], 0
	v_mfma_f32_16x16x32_bf16 v[24:27], v[222:225], v[230:233], 0
	v_mfma_f32_16x16x32_bf16 v[16:19], v[184:187], v[238:241], 0
	v_mfma_f32_16x16x32_bf16 v[8:11], v[222:225], v[238:241], 0
	v_mfma_f32_16x16x32_bf16 v[4:7], v[184:187], v[246:249], 0
	v_mfma_f32_16x16x32_bf16 v[0:3], v[222:225], v[246:249], 0
	v_mfma_f32_16x16x32_bf16 v[48:51], v[218:221], v[210:213], v[48:51]
	v_mfma_f32_16x16x32_bf16 v[40:43], v[226:229], v[210:213], v[40:43]
	v_mfma_f32_16x16x32_bf16 v[32:35], v[218:221], v[234:237], v[32:35]
	v_mfma_f32_16x16x32_bf16 v[24:27], v[226:229], v[234:237], v[24:27]
	v_mfma_f32_16x16x32_bf16 v[16:19], v[218:221], v[242:245], v[16:19]
	v_mfma_f32_16x16x32_bf16 v[8:11], v[226:229], v[242:245], v[8:11]
	v_mfma_f32_16x16x32_bf16 v[4:7], v[218:221], v[250:253], v[4:7]
	v_mfma_f32_16x16x32_bf16 v[0:3], v[226:229], v[250:253], v[0:3]
	s_barrier
	s_setprio 0
	s_add_i32 s49, 0, 0x18000
	s_add_i32 s50, 0, 0x1c000
	v_add_u32_e32 v140, s49, v163
	v_add_u32_e32 v152, s50, v163
	ds_read_b128 v[128:131], v140
	ds_read_b128 v[132:135], v140 offset:1024
	ds_read_b128 v[136:139], v140 offset:2048
	ds_read_b128 v[140:143], v140 offset:3072
	ds_read_b128 v[184:187], v152
	ds_read_b128 v[206:209], v152 offset:1024
	ds_read_b128 v[210:213], v152 offset:2048
	ds_read_b128 v[218:221], v152 offset:3072
	s_add_u32 s30, s30, 0x80000
	s_addc_u32 s31, s31, 0
	s_mov_b32 m0, s37
	v_lshl_add_u64 v[216:217], s[30:31], 0, v[144:145]
	ds_read_b128 v[222:225], v214 offset:32768
	ds_read_b128 v[226:229], v214 offset:33792
	ds_read_b128 v[230:233], v214 offset:34816
	ds_read_b128 v[234:237], v214 offset:35840
	ds_read_b128 v[238:241], v214 offset:36864
	ds_read_b128 v[242:245], v214 offset:37888
	ds_read_b128 v[246:249], v214 offset:38912
	ds_read_b128 v[250:253], v214 offset:39936
	global_load_lds_dwordx4 v[216:217], off
	v_lshl_add_u64 v[216:217], s[30:31], 0, v[148:149]
	s_mov_b32 m0, s39
	s_nop 0
	global_load_lds_dwordx4 v[216:217], off
	s_waitcnt vmcnt(8)
	s_waitcnt lgkmcnt(0)
	s_setprio 1
	s_barrier
	v_mfma_f32_16x16x32_bf16 v[124:127], v[128:131], v[222:225], v[124:127]
	v_mfma_f32_16x16x32_bf16 v[120:123], v[136:139], v[222:225], v[120:123]
	v_mfma_f32_16x16x32_bf16 v[116:119], v[128:131], v[230:233], v[116:119]
	v_mfma_f32_16x16x32_bf16 v[108:111], v[136:139], v[230:233], v[108:111]
	v_mfma_f32_16x16x32_bf16 v[100:103], v[128:131], v[238:241], v[100:103]
	v_mfma_f32_16x16x32_bf16 v[92:95], v[136:139], v[238:241], v[92:95]
	v_mfma_f32_16x16x32_bf16 v[84:87], v[128:131], v[246:249], v[84:87]
	v_mfma_f32_16x16x32_bf16 v[76:79], v[136:139], v[246:249], v[76:79]
	v_mfma_f32_16x16x32_bf16 v[124:127], v[132:135], v[226:229], v[124:127]
	v_mfma_f32_16x16x32_bf16 v[120:123], v[140:143], v[226:229], v[120:123]
	v_mfma_f32_16x16x32_bf16 v[116:119], v[132:135], v[234:237], v[116:119]
	v_mfma_f32_16x16x32_bf16 v[108:111], v[140:143], v[234:237], v[108:111]
	v_mfma_f32_16x16x32_bf16 v[100:103], v[132:135], v[242:245], v[100:103]
	v_mfma_f32_16x16x32_bf16 v[92:95], v[140:143], v[242:245], v[92:95]
	v_mfma_f32_16x16x32_bf16 v[84:87], v[132:135], v[250:253], v[84:87]
	v_mfma_f32_16x16x32_bf16 v[76:79], v[140:143], v[250:253], v[76:79]
	v_mfma_f32_16x16x32_bf16 v[112:115], v[184:187], v[222:225], v[112:115]
	v_mfma_f32_16x16x32_bf16 v[104:107], v[210:213], v[222:225], v[104:107]
	v_mfma_f32_16x16x32_bf16 v[96:99], v[184:187], v[230:233], v[96:99]
	v_mfma_f32_16x16x32_bf16 v[88:91], v[210:213], v[230:233], v[88:91]
	v_mfma_f32_16x16x32_bf16 v[80:83], v[184:187], v[238:241], v[80:83]
	v_mfma_f32_16x16x32_bf16 v[72:75], v[210:213], v[238:241], v[72:75]
	v_mfma_f32_16x16x32_bf16 v[68:71], v[184:187], v[246:249], v[68:71]
	v_mfma_f32_16x16x32_bf16 v[64:67], v[210:213], v[246:249], v[64:67]
	v_mfma_f32_16x16x32_bf16 v[112:115], v[206:209], v[226:229], v[112:115]
	v_mfma_f32_16x16x32_bf16 v[104:107], v[218:221], v[226:229], v[104:107]
	v_mfma_f32_16x16x32_bf16 v[96:99], v[206:209], v[234:237], v[96:99]
	v_mfma_f32_16x16x32_bf16 v[88:91], v[218:221], v[234:237], v[88:91]
	v_mfma_f32_16x16x32_bf16 v[80:83], v[206:209], v[242:245], v[80:83]
	v_mfma_f32_16x16x32_bf16 v[72:75], v[218:221], v[242:245], v[72:75]
	v_mfma_f32_16x16x32_bf16 v[68:71], v[206:209], v[250:253], v[68:71]
	v_mfma_f32_16x16x32_bf16 v[64:67], v[218:221], v[250:253], v[64:67]
	s_barrier
; #define PG8_STAGE(bufoff, gbase, voff) do { _Pragma("unroll") for (int _i = 0; _i < 2; ++_i) \
;         __builtin_amdgcn_global_load_lds((const unsigned*)((const char*)(gbase) + (voff)[_i]), (PG8_LAS unsigned*)(lds + (bufoff) + ldsw + _i * 8192), 16, 0, 0); } while (0)
; #define PG8_LDA(dst, b, h) do { _Pragma("unroll") for (int m = 0; m < 4; ++m) _Pragma("unroll") for (int k = 0; k < 2; ++k) dst[m][k] = *(const PG8_LAS bf16x8*)(lds + PG8_SA(b, h) + aoff + m * 2048 + k * 1024); } while (0)
; #define PG8_MMA(ai, bj, At, Bt) do { __builtin_amdgcn_s_setprio(1); _Pragma("unroll") for (int m = 0; m < 4; ++m) _Pragma("unroll") for (int n = 0; n < 2; ++n) _Pragma("unroll") for (int k = 0; k < 2; ++k) \
;         acc[ai][bj][m][n] = __builtin_amdgcn_mfma_f32_16x16x32_bf16(Bt[n][k], At[m][k], acc[ai][bj][m][n], 0, 0, 0); __builtin_amdgcn_s_setprio(0); } while (0)
; #define PG8_WAIT_V(n) asm volatile("s_waitcnt vmcnt(" #n ")" ::: "memory")
; #define PG8_WAIT_L(n) asm volatile("s_waitcnt lgkmcnt(" #n ")" ::: "memory")
; #define PG8_BAR __builtin_amdgcn_s_barrier()
; #define PG8_SCHED __builtin_amdgcn_sched_barrier(0)
; template <class Epi, class Sched, bool ALIGN_EPI = false, bool SP2 = false>
; __device__ __forceinline__ void gemm_phase(PG8_LAS unsigned char* lds, const Gemm g, const Sched& S, const Epi& E) {
;     ...
;             PG8_LDA(At, 1, 1); PG8_STAGE(PG8_SB(1, 0), b3, voffB); PG8_STAGE(PG8_SB(1, 1), b3 + hstep, voffB); PG8_STAGE(PG8_SA(1, 0), a3, voffA);
;             PG8_WAIT_V(8); PG8_WAIT_L(0); PG8_BAR; PG8_MMA(1, 0, At, B0); PG8_MMA(1, 1, At, B1); PG8_BAR; PG8_SCHED;
	s_setprio 0
	s_add_i32 s30, s49, s34
	v_lshl_add_u64 v[172:173], v[172:173], 0, s[10:11]
	s_mov_b32 m0, s30
	ds_read_b128 v[222:225], v214 offset:49152
	ds_read_b128 v[226:229], v214 offset:50176
	ds_read_b128 v[230:233], v214 offset:51200
	ds_read_b128 v[234:237], v214 offset:52224
	ds_read_b128 v[238:241], v214 offset:53248
	ds_read_b128 v[242:245], v214 offset:54272
	ds_read_b128 v[246:249], v214 offset:55296
	ds_read_b128 v[250:253], v214 offset:56320
	global_load_lds_dwordx4 v[172:173], off
	s_add_i32 m0, s30, 0x2000
	s_add_u32 s28, s28, 0x80080
	v_lshl_add_u64 v[172:173], v[176:177], 0, s[10:11]
	s_addc_u32 s29, s29, 0
	s_add_i32 s30, s50, s34
	global_load_lds_dwordx4 v[172:173], off
	v_lshl_add_u64 v[172:173], s[28:29], 0, v[146:147]
	s_mov_b32 m0, s30
	s_nop 0
	global_load_lds_dwordx4 v[172:173], off
	v_lshl_add_u64 v[172:173], s[28:29], 0, v[150:151]
	s_add_i32 m0, s30, 0x2000
	s_nop 0
	global_load_lds_dwordx4 v[172:173], off
	v_lshl_add_u64 v[172:173], v[180:181], 0, s[10:11]
	s_mov_b32 m0, s43
	s_nop 0
	global_load_lds_dwordx4 v[172:173], off
	v_lshl_add_u64 v[172:173], v[188:189], 0, s[10:11]
	s_mov_b32 m0, s46
	s_nop 0
	global_load_lds_dwordx4 v[172:173], off
	s_waitcnt vmcnt(8)
	s_waitcnt lgkmcnt(0)
	s_setprio 1
	s_barrier
	v_mfma_f32_16x16x32_bf16 v[60:63], v[128:131], v[222:225], v[60:63]
	v_mfma_f32_16x16x32_bf16 v[56:59], v[136:139], v[222:225], v[56:59]
	v_mfma_f32_16x16x32_bf16 v[52:55], v[128:131], v[230:233], v[52:55]
	v_mfma_f32_16x16x32_bf16 v[44:47], v[136:139], v[230:233], v[44:47]
	v_mfma_f32_16x16x32_bf16 v[36:39], v[128:131], v[238:241], v[36:39]
	v_mfma_f32_16x16x32_bf16 v[28:31], v[136:139], v[238:241], v[28:31]
	v_mfma_f32_16x16x32_bf16 v[20:23], v[128:131], v[246:249], v[20:23]
	v_mfma_f32_16x16x32_bf16 v[12:15], v[136:139], v[246:249], v[12:15]
	v_mfma_f32_16x16x32_bf16 v[60:63], v[132:135], v[226:229], v[60:63]
	v_mfma_f32_16x16x32_bf16 v[56:59], v[140:143], v[226:229], v[56:59]
	v_mfma_f32_16x16x32_bf16 v[52:55], v[132:135], v[234:237], v[52:55]
	v_mfma_f32_16x16x32_bf16 v[44:47], v[140:143], v[234:237], v[44:47]
	v_mfma_f32_16x16x32_bf16 v[36:39], v[132:135], v[242:245], v[36:39]
	v_mfma_f32_16x16x32_bf16 v[28:31], v[140:143], v[242:245], v[28:31]
	v_mfma_f32_16x16x32_bf16 v[20:23], v[132:135], v[250:253], v[20:23]
	v_mfma_f32_16x16x32_bf16 v[12:15], v[140:143], v[250:253], v[12:15]
	v_mfma_f32_16x16x32_bf16 v[48:51], v[184:187], v[222:225], v[48:51]
	v_mfma_f32_16x16x32_bf16 v[40:43], v[210:213], v[222:225], v[40:43]
	v_mfma_f32_16x16x32_bf16 v[32:35], v[184:187], v[230:233], v[32:35]
	v_mfma_f32_16x16x32_bf16 v[24:27], v[210:213], v[230:233], v[24:27]
	v_mfma_f32_16x16x32_bf16 v[16:19], v[184:187], v[238:241], v[16:19]
	v_mfma_f32_16x16x32_bf16 v[8:11], v[210:213], v[238:241], v[8:11]
	v_mfma_f32_16x16x32_bf16 v[4:7], v[184:187], v[246:249], v[4:7]
	v_mfma_f32_16x16x32_bf16 v[0:3], v[210:213], v[246:249], v[0:3]
	v_mfma_f32_16x16x32_bf16 v[48:51], v[206:209], v[226:229], v[48:51]
	v_mfma_f32_16x16x32_bf16 v[40:43], v[218:221], v[226:229], v[40:43]
	v_mfma_f32_16x16x32_bf16 v[32:35], v[206:209], v[234:237], v[32:35]
	v_mfma_f32_16x16x32_bf16 v[24:27], v[218:221], v[234:237], v[24:27]
	v_mfma_f32_16x16x32_bf16 v[16:19], v[206:209], v[242:245], v[16:19]
	v_mfma_f32_16x16x32_bf16 v[8:11], v[218:221], v[242:245], v[8:11]
	v_mfma_f32_16x16x32_bf16 v[4:7], v[206:209], v[250:253], v[4:7]
	v_mfma_f32_16x16x32_bf16 v[0:3], v[218:221], v[250:253], v[0:3]
	s_barrier
	s_setprio 0
	s_add_i32 s48, s48, 2
	s_add_u32 s0, s0, 0x100
	s_addc_u32 s1, s1, 0
	s_add_u32 s44, s44, 0x100
	s_addc_u32 s45, s45, 0

; #define PG8_STAGE(bufoff, gbase, voff) do { _Pragma("unroll") for (int _i = 0; _i < 2; ++_i) \
;         __builtin_amdgcn_global_load_lds((const unsigned*)((const char*)(gbase) + (voff)[_i]), (PG8_LAS unsigned*)(lds + (bufoff) + ldsw + _i * 8192), 16, 0, 0); } while (0)
; #define PG8_WAIT_V(n) asm volatile("s_waitcnt vmcnt(" #n ")" ::: "memory")
; #define PG8_BAR __builtin_amdgcn_s_barrier()
; template <class Epi, class Sched, bool ALIGN_EPI = false, bool SP2 = false>
; __device__ __forceinline__ void gemm_phase(PG8_LAS unsigned char* lds, const Gemm g, const Sched& S, const Epi& E) {
;     ...
;         PG8_STAGE(PG8_SB(0, 0), cB, voffB); PG8_STAGE(PG8_SB(0, 1), cB + hstep, voffB); PG8_STAGE(PG8_SA(0, 0), cA, voffA); PG8_STAGE(PG8_SA(0, 1), cA + hstep, voffA);
;         if (wr == 1) PG8_BAR;
;         PG8_WAIT_V(2); PG8_BAR;
;         PG8_STAGE(PG8_SB(1, 0), cB + kstep, voffB); PG8_STAGE(PG8_SA(1, 0), cA + kstep, voffA); PG8_STAGE(PG8_SB(1, 1), cB + hstep + kstep, voffB);
;         PG8_WAIT_V(6); PG8_BAR;
.LBB0_753:
	s_mov_b64 s[12:13], 0x80
	s_and_b32 s42, s3, 3
	s_add_i32 m0, s35, 0x18000
	v_lshl_add_u64 v[6:7], v[6:7], 0, s[12:13]
	s_lshl_b32 s3, s2, 13
	s_lshl_b32 s7, s42, 12
	s_waitcnt vmcnt(2)
	s_barrier
	global_load_lds_dwordx4 v[6:7], off
	v_lshl_add_u64 v[4:5], v[4:5], 0, s[12:13]
	s_add_i32 m0, s35, 0x1a000
	s_add_i32 s43, s35, 0x8000
	s_add_i32 s44, s35, 0xa000
	global_load_lds_dwordx4 v[4:5], off
	v_lshl_add_u64 v[0:1], v[0:1], 0, s[12:13]
	s_mov_b32 m0, s43
	s_add_u32 s4, s28, 0x100080
	global_load_lds_dwordx4 v[0:1], off
	v_lshl_add_u64 v[0:1], v[2:3], 0, s[12:13]
	s_mov_b32 m0, s44
	s_addc_u32 s5, s29, 0
	global_load_lds_dwordx4 v[0:1], off
	s_add_i32 m0, s35, 0x1c000
	v_lshl_add_u64 v[0:1], s[4:5], 0, v[154:155]
	global_load_lds_dwordx4 v[0:1], off
	v_lshl_add_u64 v[0:1], s[4:5], 0, v[158:159]
	s_add_i32 m0, s35, 0x1e000
	v_lshlrev_b32_e32 v4, 2, v196
	global_load_lds_dwordx4 v[0:1], off
	v_bfe_u32 v0, v196, 4, 2
	v_and_b32_e32 v1, 15, v196
	v_lshlrev_b32_e32 v3, 4, v0
	s_waitcnt vmcnt(0)
	v_lshl_or_b32 v178, s2, 6, v1
	v_lshl_or_b32 v1, v1, 6, v3
	v_and_b32_e32 v4, 32, v4
	v_lshlrev_b32_e32 v5, 6, v196
	s_movk_i32 s2, 0x3c0
	v_lshlrev_b32_e32 v2, 3, v0
	v_bitop3_b32 v1, v1, s3, v4 bitop3:0xde
	v_and_or_b32 v3, v5, s2, v3
	v_cmp_eq_u32_e64 s[2:3], 0, v0
	v_lshlrev_b32_e32 v0, 10, v196
	v_lshl_or_b32 v180, s42, 5, v2
	v_and_b32_e32 v0, 0xe0000, v0
	v_lshlrev_b32_e32 v2, 13, v10
	v_or3_b32 v0, v8, v0, v2
	s_cmpk_lt_u32 s14, 0x100
	v_readlane_b32 s16, v254, 24
	v_add_u32_e32 v160, v0, v9
	v_lshlrev_b32_e32 v0, 6, v11
	s_cselect_b64 s[14:15], -1, 0
	s_ashr_i32 s45, s88, 31
	s_ashr_i32 s46, s89, 31
	v_readlane_b32 s22, v254, 30
	v_readlane_b32 s23, v254, 31
	v_and_b32_e32 v0, 0x1e0000, v0
	s_waitcnt vmcnt(0)
	v_readlane_b32 s17, v254, 25
	s_cmp_lg_u64 s[22:23], 0
	v_or3_b32 v0, v8, v0, v2
	v_bitop3_b32 v179, s7, v3, v4 bitop3:0xf6
	s_cselect_b64 s[16:17], -1, 0
	v_add_u32_e32 v162, v0, v9
	s_add_i32 s47, 0, 0x10000
	s_add_i32 s50, 0, 0x14000
	v_mbcnt_lo_u32_b32 v0, -1, 0
	v_readlane_b32 s18, v254, 26
	v_readlane_b32 s20, v254, 28
	v_mov_b32_e32 v161, v155
	v_mov_b32_e32 v163, v155
	v_mov_b64_e32 v[164:165], 0x400
	v_mov_b64_e32 v[166:167], 0x3ff
	v_add_u32_e32 v181, s47, v179
	v_add_u32_e32 v182, s50, v179
	v_add_u32_e32 v183, 0, v1
	v_mbcnt_hi_u32_b32 v184, -1, v0
	s_mov_b32 s51, 0
	s_barrier
	v_readlane_b32 s19, v254, 27
	v_readlane_b32 s21, v254, 29
	s_branch .LBB0_756

; #define PG8_STAGE(bufoff, gbase, voff) do { _Pragma("unroll") for (int _i = 0; _i < 2; ++_i) \
;         __builtin_amdgcn_global_load_lds((const unsigned*)((const char*)(gbase) + (voff)[_i]), (PG8_LAS unsigned*)(lds + (bufoff) + ldsw + _i * 8192), 16, 0, 0); } while (0)
; #define PG8_LDA(dst, b, h) do { _Pragma("unroll") for (int m = 0; m < 4; ++m) _Pragma("unroll") for (int k = 0; k < 2; ++k) dst[m][k] = *(const PG8_LAS bf16x8*)(lds + PG8_SA(b, h) + aoff + m * 2048 + k * 1024); } while (0)
; #define PG8_LDB(dst, b, h) do { _Pragma("unroll") for (int n = 0; n < 2; ++n) _Pragma("unroll") for (int k = 0; k < 2; ++k) dst[n][k] = *(const PG8_LAS bf16x8*)(lds + PG8_SB(b, h) + boff + n * 2048 + k * 1024); } while (0)
; #define PG8_WAIT_V(n) asm volatile("s_waitcnt vmcnt(" #n ")" ::: "memory")
; #define PG8_BAR __builtin_amdgcn_s_barrier()
; template <class Epi, class Sched, bool ALIGN_EPI = false, bool SP2 = false>
; __device__ __forceinline__ void gemm_phase(PG8_LAS unsigned char* lds, const Gemm g, const Sched& S, const Epi& E) {
;     ...
;         const char* nA = has_next ? (const char*)g.A + (size_t)nxt.pm * tstep : cA; const char* nB = has_next ? (const char*)g.Bt + (size_t)nxt.pn * tstep : cB;
;         for (int t = 0; t < nt; t += 2) {
;             const bool last = (t == nt - 2);
;             const char* a1 = cA + (size_t)(t + 1) * kstep;
;             const char* a2 = last ? nA : cA + (size_t)(t + 2) * kstep; const char* b2 = last ? nB : cB + (size_t)(t + 2) * kstep;
;             const char* a3 = a2 + kstep; const char* b3 = b2 + kstep;
;             if (last && has_next) S.a_ready(nxt);
;             if constexpr (SP2) {
;             PG8_LDB(B0, 0, 0); PG8_LDB(B1, 0, 1); PG8_SCHED; PG8_LDA(At, 0, 0); PG8_STAGE(PG8_SA(1, 1), a1 + hstep, voffA);
;             PG8_WAIT_V(8); PG8_WAIT_L(0); PG8_BAR; PG8_MMA(0, 0, At, B0); PG8_MMA(0, 1, At, B1); PG8_BAR; PG8_SCHED;
;             PG8_LDA(At, 0, 1); PG8_STAGE(PG8_SB(0, 0), b2, voffB); PG8_STAGE(PG8_SB(0, 1), b2 + hstep, voffB); PG8_STAGE(PG8_SA(0, 0), a2, voffA);
;     ...
; #pragma unroll
;         for (int a = 0; a < 2; ++a)
; #pragma unroll
;             for (int b = 0; b < 2; ++b)
; #pragma unroll
;                 for (int m = 0; m < 4; ++m)
; #pragma unroll
;                     for (int n = 0; n < 2; ++n) acc[a][b][m][n] = (f32x4){0.f, 0.f, 0.f, 0.f};
;         cur = nxt; cA = nA; cB = nB; ++ui;
.LBB0_762:
	s_ashr_i32 s21, s20, 31
	s_lshl_b64 s[22:23], s[20:21], 21
	s_add_u32 s22, s60, s22
	s_addc_u32 s23, s61, s23
	s_and_b64 s[24:25], s[4:5], exec
	s_cselect_b32 s7, s23, s27
	s_cselect_b32 s21, s22, s26
	s_ashr_i32 s19, s18, 31
	s_lshl_b64 s[24:25], s[18:19], 21
	v_readlane_b32 s30, v254, 32
	v_readlane_b32 s31, v254, 33
	s_add_u32 s24, s30, s24
	s_addc_u32 s25, s31, s25
	s_and_b64 s[30:31], s[4:5], exec
	s_cselect_b32 s19, s25, s29
	s_cselect_b32 s48, s24, s28
	s_add_u32 s26, s26, 0x100080
	s_addc_u32 s27, s27, 0
	s_add_u32 s49, s28, 0x100
	s_addc_u32 s52, s29, 0
	s_mov_b32 s53, -2
	s_waitcnt lgkmcnt(0)
	ds_read_b128 v[128:131], v181
	ds_read_b128 v[132:135], v181 offset:1024
	ds_read_b128 v[136:139], v181 offset:2048
	ds_read_b128 v[140:143], v181 offset:3072
	ds_read_b128 v[144:147], v182
	ds_read_b128 v[148:151], v182 offset:1024
	ds_read_b128 v[168:171], v182 offset:2048
	ds_read_b128 v[172:175], v182 offset:3072
	s_add_u32 s28, s26, 0xfff00080
	s_addc_u32 s29, s27, -1
	s_cmp_eq_u32 s53, 60
	s_cselect_b32 s31, s7, s29
	s_cselect_b32 s30, s21, s28
	s_cselect_b32 s29, s19, s52
	s_cselect_b32 s28, s48, s49
	v_lshl_add_u64 v[176:177], s[26:27], 0, v[160:161]
	s_add_i32 m0, s35, 0xc000
	ds_read_b128 v[186:189], v183
	ds_read_b128 v[190:193], v183 offset:1024
	ds_read_b128 v[198:201], v183 offset:2048
	ds_read_b128 v[202:205], v183 offset:3072
	ds_read_b128 v[206:209], v183 offset:4096
	ds_read_b128 v[210:213], v183 offset:5120
	ds_read_b128 v[214:217], v183 offset:6144
	ds_read_b128 v[218:221], v183 offset:7168
	global_load_lds_dwordx4 v[176:177], off
	v_lshl_add_u64 v[176:177], s[26:27], 0, v[162:163]
	s_add_i32 m0, s35, 0xe000
	s_nop 0
	global_load_lds_dwordx4 v[176:177], off
	s_nop 0
	s_waitcnt lgkmcnt(0)
	s_setprio 1
	s_barrier
	v_mfma_f32_16x16x32_bf16 v[124:127], v[128:131], v[186:189], 0
	v_mfma_f32_16x16x32_bf16 v[120:123], v[136:139], v[186:189], 0
	v_mfma_f32_16x16x32_bf16 v[104:107], v[128:131], v[198:201], 0
	v_mfma_f32_16x16x32_bf16 v[108:111], v[136:139], v[198:201], 0
	v_mfma_f32_16x16x32_bf16 v[88:91], v[128:131], v[206:209], 0
	v_mfma_f32_16x16x32_bf16 v[92:95], v[136:139], v[206:209], 0
	v_mfma_f32_16x16x32_bf16 v[72:75], v[128:131], v[214:217], 0
	v_mfma_f32_16x16x32_bf16 v[76:79], v[136:139], v[214:217], 0
	v_mfma_f32_16x16x32_bf16 v[124:127], v[132:135], v[190:193], v[124:127]
	v_mfma_f32_16x16x32_bf16 v[120:123], v[140:143], v[190:193], v[120:123]
	v_mfma_f32_16x16x32_bf16 v[104:107], v[132:135], v[202:205], v[104:107]
	v_mfma_f32_16x16x32_bf16 v[108:111], v[140:143], v[202:205], v[108:111]
	v_mfma_f32_16x16x32_bf16 v[88:91], v[132:135], v[210:213], v[88:91]
	v_mfma_f32_16x16x32_bf16 v[92:95], v[140:143], v[210:213], v[92:95]
	v_mfma_f32_16x16x32_bf16 v[72:75], v[132:135], v[218:221], v[72:75]
	v_mfma_f32_16x16x32_bf16 v[76:79], v[140:143], v[218:221], v[76:79]
	v_mfma_f32_16x16x32_bf16 v[116:119], v[144:147], v[186:189], 0
	v_mfma_f32_16x16x32_bf16 v[112:115], v[168:171], v[186:189], 0
	v_mfma_f32_16x16x32_bf16 v[100:103], v[144:147], v[198:201], 0
	v_mfma_f32_16x16x32_bf16 v[96:99], v[168:171], v[198:201], 0
	v_mfma_f32_16x16x32_bf16 v[84:87], v[144:147], v[206:209], 0
	v_mfma_f32_16x16x32_bf16 v[80:83], v[168:171], v[206:209], 0
	v_mfma_f32_16x16x32_bf16 v[68:71], v[144:147], v[214:217], 0
	v_mfma_f32_16x16x32_bf16 v[64:67], v[168:171], v[214:217], 0
	v_mfma_f32_16x16x32_bf16 v[116:119], v[148:151], v[190:193], v[116:119]
	v_mfma_f32_16x16x32_bf16 v[112:115], v[172:175], v[190:193], v[112:115]
	v_mfma_f32_16x16x32_bf16 v[100:103], v[148:151], v[202:205], v[100:103]
	v_mfma_f32_16x16x32_bf16 v[96:99], v[172:175], v[202:205], v[96:99]
	v_mfma_f32_16x16x32_bf16 v[84:87], v[148:151], v[210:213], v[84:87]
	v_mfma_f32_16x16x32_bf16 v[80:83], v[172:175], v[210:213], v[80:83]
	v_mfma_f32_16x16x32_bf16 v[68:71], v[148:151], v[218:221], v[68:71]
	v_mfma_f32_16x16x32_bf16 v[64:67], v[172:175], v[218:221], v[64:67]
	s_barrier
	s_setprio 0
	s_add_i32 s54, s47, s34
	v_lshl_add_u64 v[176:177], s[28:29], 0, v[154:155]
	s_mov_b32 m0, s54
	ds_read_b128 v[186:189], v183 offset:16384
	ds_read_b128 v[190:193], v183 offset:17408
	ds_read_b128 v[198:201], v183 offset:18432
	ds_read_b128 v[202:205], v183 offset:19456
	ds_read_b128 v[206:209], v183 offset:20480
	ds_read_b128 v[210:213], v183 offset:21504
	ds_read_b128 v[214:217], v183 offset:22528
	ds_read_b128 v[218:221], v183 offset:23552
	global_load_lds_dwordx4 v[176:177], off
	s_add_i32 m0, s54, 0x2000
	s_add_u32 s54, s28, 0x100000
	v_lshl_add_u64 v[194:195], s[28:29], 0, v[158:159]
	s_addc_u32 s55, s29, 0
	s_add_i32 s56, s50, s34
	global_load_lds_dwordx4 v[194:195], off
	v_lshl_add_u64 v[222:223], s[54:55], 0, v[154:155]
	s_mov_b32 m0, s56
	v_lshl_add_u64 v[224:225], s[30:31], 0, v[156:157]
	global_load_lds_dwordx4 v[222:223], off
	v_lshl_add_u64 v[222:223], s[54:55], 0, v[158:159]
	s_add_i32 m0, s56, 0x2000
	s_nop 0
	global_load_lds_dwordx4 v[222:223], off
	v_lshl_add_u64 v[222:223], s[30:31], 0, v[152:153]
	s_mov_b32 m0, s35
	s_nop 0
	global_load_lds_dwordx4 v[222:223], off
	s_mov_b32 m0, s33
	s_nop 0
	global_load_lds_dwordx4 v[224:225], off
	s_nop 0
	s_waitcnt lgkmcnt(0)
	s_setprio 1
	s_barrier
; #define PG8_STAGE(bufoff, gbase, voff) do { _Pragma("unroll") for (int _i = 0; _i < 2; ++_i) \
;         __builtin_amdgcn_global_load_lds((const unsigned*)((const char*)(gbase) + (voff)[_i]), (PG8_LAS unsigned*)(lds + (bufoff) + ldsw + _i * 8192), 16, 0, 0); } while (0)
; #define PG8_LDA(dst, b, h) do { _Pragma("unroll") for (int m = 0; m < 4; ++m) _Pragma("unroll") for (int k = 0; k < 2; ++k) dst[m][k] = *(const PG8_LAS bf16x8*)(lds + PG8_SA(b, h) + aoff + m * 2048 + k * 1024); } while (0)
; #define PG8_LDB(dst, b, h) do { _Pragma("unroll") for (int n = 0; n < 2; ++n) _Pragma("unroll") for (int k = 0; k < 2; ++k) dst[n][k] = *(const PG8_LAS bf16x8*)(lds + PG8_SB(b, h) + boff + n * 2048 + k * 1024); } while (0)
; #define PG8_MMA(ai, bj, At, Bt) do { __builtin_amdgcn_s_setprio(1); _Pragma("unroll") for (int m = 0; m < 4; ++m) _Pragma("unroll") for (int n = 0; n < 2; ++n) _Pragma("unroll") for (int k = 0; k < 2; ++k) \
;         acc[ai][bj][m][n] = __builtin_amdgcn_mfma_f32_16x16x32_bf16(Bt[n][k], At[m][k], acc[ai][bj][m][n], 0, 0, 0); __builtin_amdgcn_s_setprio(0); } while (0)
; #define PG8_WAIT_V(n) asm volatile("s_waitcnt vmcnt(" #n ")" ::: "memory")
; #define PG8_WAIT_L(n) asm volatile("s_waitcnt lgkmcnt(" #n ")" ::: "memory")
; #define PG8_BAR __builtin_amdgcn_s_barrier()
; #define PG8_SCHED __builtin_amdgcn_sched_barrier(0)
; template <class Epi, class Sched, bool ALIGN_EPI = false, bool SP2 = false>
; __device__ __forceinline__ void gemm_phase(PG8_LAS unsigned char* lds, const Gemm g, const Sched& S, const Epi& E) {
;     ...
;             PG8_WAIT_V(8); PG8_WAIT_L(0); PG8_BAR; PG8_MMA(1, 0, At, B0); PG8_MMA(1, 1, At, B1); PG8_BAR; PG8_SCHED;
;             PG8_LDB(B0, 1, 0); PG8_LDB(B1, 1, 1); PG8_SCHED; PG8_LDA(At, 1, 0); PG8_STAGE(PG8_SA(0, 1), a2 + hstep, voffA);
;             PG8_WAIT_V(8); PG8_WAIT_L(0); PG8_BAR; PG8_MMA(0, 0, At, B0); PG8_MMA(0, 1, At, B1); PG8_BAR; PG8_SCHED;
	v_mfma_f32_16x16x32_bf16 v[56:59], v[128:131], v[186:189], 0
	v_mfma_f32_16x16x32_bf16 v[60:63], v[136:139], v[186:189], 0
	v_mfma_f32_16x16x32_bf16 v[40:43], v[128:131], v[198:201], 0
	v_mfma_f32_16x16x32_bf16 v[44:47], v[136:139], v[198:201], 0
	v_mfma_f32_16x16x32_bf16 v[24:27], v[128:131], v[206:209], 0
	v_mfma_f32_16x16x32_bf16 v[28:31], v[136:139], v[206:209], 0
	v_mfma_f32_16x16x32_bf16 v[8:11], v[128:131], v[214:217], 0
	v_mfma_f32_16x16x32_bf16 v[12:15], v[136:139], v[214:217], 0
	v_mfma_f32_16x16x32_bf16 v[56:59], v[132:135], v[190:193], v[56:59]
	v_mfma_f32_16x16x32_bf16 v[60:63], v[140:143], v[190:193], v[60:63]
	v_mfma_f32_16x16x32_bf16 v[40:43], v[132:135], v[202:205], v[40:43]
	v_mfma_f32_16x16x32_bf16 v[44:47], v[140:143], v[202:205], v[44:47]
	v_mfma_f32_16x16x32_bf16 v[24:27], v[132:135], v[210:213], v[24:27]
	v_mfma_f32_16x16x32_bf16 v[28:31], v[140:143], v[210:213], v[28:31]
	v_mfma_f32_16x16x32_bf16 v[8:11], v[132:135], v[218:221], v[8:11]
	v_mfma_f32_16x16x32_bf16 v[12:15], v[140:143], v[218:221], v[12:15]
	v_mfma_f32_16x16x32_bf16 v[52:55], v[144:147], v[186:189], 0
	v_mfma_f32_16x16x32_bf16 v[48:51], v[168:171], v[186:189], 0
	v_mfma_f32_16x16x32_bf16 v[36:39], v[144:147], v[198:201], 0
	v_mfma_f32_16x16x32_bf16 v[32:35], v[168:171], v[198:201], 0
	v_mfma_f32_16x16x32_bf16 v[20:23], v[144:147], v[206:209], 0
	v_mfma_f32_16x16x32_bf16 v[16:19], v[168:171], v[206:209], 0
	v_mfma_f32_16x16x32_bf16 v[4:7], v[144:147], v[214:217], 0
	v_mfma_f32_16x16x32_bf16 v[0:3], v[168:171], v[214:217], 0
	v_mfma_f32_16x16x32_bf16 v[52:55], v[148:151], v[190:193], v[52:55]
	v_mfma_f32_16x16x32_bf16 v[48:51], v[172:175], v[190:193], v[48:51]
	v_mfma_f32_16x16x32_bf16 v[36:39], v[148:151], v[202:205], v[36:39]
	v_mfma_f32_16x16x32_bf16 v[32:35], v[172:175], v[202:205], v[32:35]
	v_mfma_f32_16x16x32_bf16 v[20:23], v[148:151], v[210:213], v[20:23]
	v_mfma_f32_16x16x32_bf16 v[16:19], v[172:175], v[210:213], v[16:19]
	v_mfma_f32_16x16x32_bf16 v[4:7], v[148:151], v[218:221], v[4:7]
	v_mfma_f32_16x16x32_bf16 v[0:3], v[172:175], v[218:221], v[0:3]
	s_barrier
	s_setprio 0
	s_add_i32 s54, 0, 0x18000
	s_add_i32 s55, 0, 0x1c000
	v_add_u32_e32 v140, s54, v179
	v_add_u32_e32 v172, s55, v179
	ds_read_b128 v[128:131], v140
	ds_read_b128 v[132:135], v140 offset:1024
	ds_read_b128 v[136:139], v140 offset:2048
	ds_read_b128 v[140:143], v140 offset:3072
	ds_read_b128 v[144:147], v172
	ds_read_b128 v[148:151], v172 offset:1024
	ds_read_b128 v[168:171], v172 offset:2048
	ds_read_b128 v[172:175], v172 offset:3072
	s_add_u32 s30, s30, 0x100000
	s_addc_u32 s31, s31, 0
	s_mov_b32 m0, s37
	v_lshl_add_u64 v[226:227], s[30:31], 0, v[152:153]
	ds_read_b128 v[186:189], v183 offset:32768
	ds_read_b128 v[190:193], v183 offset:33792
	ds_read_b128 v[198:201], v183 offset:34816
	ds_read_b128 v[202:205], v183 offset:35840
	ds_read_b128 v[206:209], v183 offset:36864
	ds_read_b128 v[210:213], v183 offset:37888
	ds_read_b128 v[214:217], v183 offset:38912
	ds_read_b128 v[218:221], v183 offset:39936
	global_load_lds_dwordx4 v[226:227], off
	v_lshl_add_u64 v[226:227], s[30:31], 0, v[156:157]
	s_mov_b32 m0, s39
	s_nop 0
	global_load_lds_dwordx4 v[226:227], off
	s_waitcnt vmcnt(8)
	s_waitcnt lgkmcnt(0)
	s_setprio 1
	s_barrier
	v_mfma_f32_16x16x32_bf16 v[124:127], v[128:131], v[186:189], v[124:127]
	v_mfma_f32_16x16x32_bf16 v[120:123], v[136:139], v[186:189], v[120:123]
	v_mfma_f32_16x16x32_bf16 v[104:107], v[128:131], v[198:201], v[104:107]
	v_mfma_f32_16x16x32_bf16 v[108:111], v[136:139], v[198:201], v[108:111]
	v_mfma_f32_16x16x32_bf16 v[88:91], v[128:131], v[206:209], v[88:91]
	v_mfma_f32_16x16x32_bf16 v[92:95], v[136:139], v[206:209], v[92:95]
	v_mfma_f32_16x16x32_bf16 v[72:75], v[128:131], v[214:217], v[72:75]
	v_mfma_f32_16x16x32_bf16 v[76:79], v[136:139], v[214:217], v[76:79]
	v_mfma_f32_16x16x32_bf16 v[124:127], v[132:135], v[190:193], v[124:127]
	v_mfma_f32_16x16x32_bf16 v[120:123], v[140:143], v[190:193], v[120:123]
	v_mfma_f32_16x16x32_bf16 v[104:107], v[132:135], v[202:205], v[104:107]
	v_mfma_f32_16x16x32_bf16 v[108:111], v[140:143], v[202:205], v[108:111]
	v_mfma_f32_16x16x32_bf16 v[88:91], v[132:135], v[210:213], v[88:91]
	v_mfma_f32_16x16x32_bf16 v[92:95], v[140:143], v[210:213], v[92:95]
	v_mfma_f32_16x16x32_bf16 v[72:75], v[132:135], v[218:221], v[72:75]
	v_mfma_f32_16x16x32_bf16 v[76:79], v[140:143], v[218:221], v[76:79]
	v_mfma_f32_16x16x32_bf16 v[116:119], v[144:147], v[186:189], v[116:119]
	v_mfma_f32_16x16x32_bf16 v[112:115], v[168:171], v[186:189], v[112:115]
	v_mfma_f32_16x16x32_bf16 v[100:103], v[144:147], v[198:201], v[100:103]
	v_mfma_f32_16x16x32_bf16 v[96:99], v[168:171], v[198:201], v[96:99]
	v_mfma_f32_16x16x32_bf16 v[84:87], v[144:147], v[206:209], v[84:87]
	v_mfma_f32_16x16x32_bf16 v[80:83], v[168:171], v[206:209], v[80:83]
	v_mfma_f32_16x16x32_bf16 v[68:71], v[144:147], v[214:217], v[68:71]
	v_mfma_f32_16x16x32_bf16 v[64:67], v[168:171], v[214:217], v[64:67]
	v_mfma_f32_16x16x32_bf16 v[116:119], v[148:151], v[190:193], v[116:119]
	v_mfma_f32_16x16x32_bf16 v[112:115], v[172:175], v[190:193], v[112:115]
	v_mfma_f32_16x16x32_bf16 v[100:103], v[148:151], v[202:205], v[100:103]
	v_mfma_f32_16x16x32_bf16 v[96:99], v[172:175], v[202:205], v[96:99]
	v_mfma_f32_16x16x32_bf16 v[84:87], v[148:151], v[210:213], v[84:87]
	v_mfma_f32_16x16x32_bf16 v[80:83], v[172:175], v[210:213], v[80:83]
	v_mfma_f32_16x16x32_bf16 v[68:71], v[148:151], v[218:221], v[68:71]
	v_mfma_f32_16x16x32_bf16 v[64:67], v[172:175], v[218:221], v[64:67]
	s_barrier
; #define PG8_STAGE(bufoff, gbase, voff) do { _Pragma("unroll") for (int _i = 0; _i < 2; ++_i) \
;         __builtin_amdgcn_global_load_lds((const unsigned*)((const char*)(gbase) + (voff)[_i]), (PG8_LAS unsigned*)(lds + (bufoff) + ldsw + _i * 8192), 16, 0, 0); } while (0)
; #define PG8_LDA(dst, b, h) do { _Pragma("unroll") for (int m = 0; m < 4; ++m) _Pragma("unroll") for (int k = 0; k < 2; ++k) dst[m][k] = *(const PG8_LAS bf16x8*)(lds + PG8_SA(b, h) + aoff + m * 2048 + k * 1024); } while (0)
; #define PG8_MMA(ai, bj, At, Bt) do { __builtin_amdgcn_s_setprio(1); _Pragma("unroll") for (int m = 0; m < 4; ++m) _Pragma("unroll") for (int n = 0; n < 2; ++n) _Pragma("unroll") for (int k = 0; k < 2; ++k) \
;         acc[ai][bj][m][n] = __builtin_amdgcn_mfma_f32_16x16x32_bf16(Bt[n][k], At[m][k], acc[ai][bj][m][n], 0, 0, 0); __builtin_amdgcn_s_setprio(0); } while (0)
; #define PG8_WAIT_V(n) asm volatile("s_waitcnt vmcnt(" #n ")" ::: "memory")
; #define PG8_WAIT_L(n) asm volatile("s_waitcnt lgkmcnt(" #n ")" ::: "memory")
; #define PG8_BAR __builtin_amdgcn_s_barrier()
; #define PG8_SCHED __builtin_amdgcn_sched_barrier(0)
; template <class Epi, class Sched, bool ALIGN_EPI = false, bool SP2 = false>
; __device__ __forceinline__ void gemm_phase(PG8_LAS unsigned char* lds, const Gemm g, const Sched& S, const Epi& E) {
;     ...
;             PG8_LDA(At, 1, 1); PG8_STAGE(PG8_SB(1, 0), b3, voffB); PG8_STAGE(PG8_SB(1, 1), b3 + hstep, voffB); PG8_STAGE(PG8_SA(1, 0), a3, voffA);
;             PG8_WAIT_V(8); PG8_WAIT_L(0); PG8_BAR; PG8_MMA(1, 0, At, B0); PG8_MMA(1, 1, At, B1); PG8_BAR; PG8_SCHED;
	s_setprio 0
	s_add_i32 s30, s54, s34
	v_lshl_add_u64 v[176:177], v[176:177], 0, s[12:13]
	s_mov_b32 m0, s30
	ds_read_b128 v[186:189], v183 offset:49152
	ds_read_b128 v[190:193], v183 offset:50176
	ds_read_b128 v[198:201], v183 offset:51200
	ds_read_b128 v[202:205], v183 offset:52224
	ds_read_b128 v[206:209], v183 offset:53248
	ds_read_b128 v[210:213], v183 offset:54272
	ds_read_b128 v[214:217], v183 offset:55296
	ds_read_b128 v[218:221], v183 offset:56320
	global_load_lds_dwordx4 v[176:177], off
	s_add_i32 m0, s30, 0x2000
	s_add_u32 s28, s28, 0x100080
	v_lshl_add_u64 v[176:177], v[194:195], 0, s[12:13]
	s_addc_u32 s29, s29, 0
	s_add_i32 s30, s55, s34
	global_load_lds_dwordx4 v[176:177], off
	v_lshl_add_u64 v[176:177], s[28:29], 0, v[154:155]
	s_mov_b32 m0, s30
	s_nop 0
	global_load_lds_dwordx4 v[176:177], off
	v_lshl_add_u64 v[176:177], s[28:29], 0, v[158:159]
	s_add_i32 m0, s30, 0x2000
	s_nop 0
	global_load_lds_dwordx4 v[176:177], off
	v_lshl_add_u64 v[176:177], v[222:223], 0, s[12:13]
	s_mov_b32 m0, s43
	s_nop 0
	global_load_lds_dwordx4 v[176:177], off
	v_lshl_add_u64 v[176:177], v[224:225], 0, s[12:13]
	s_mov_b32 m0, s44
	s_nop 0
	global_load_lds_dwordx4 v[176:177], off
	s_waitcnt vmcnt(8)
	s_waitcnt lgkmcnt(0)
	s_setprio 1
	s_barrier
	v_mfma_f32_16x16x32_bf16 v[56:59], v[128:131], v[186:189], v[56:59]
	v_mfma_f32_16x16x32_bf16 v[60:63], v[136:139], v[186:189], v[60:63]
	v_mfma_f32_16x16x32_bf16 v[40:43], v[128:131], v[198:201], v[40:43]
	v_mfma_f32_16x16x32_bf16 v[44:47], v[136:139], v[198:201], v[44:47]
	v_mfma_f32_16x16x32_bf16 v[24:27], v[128:131], v[206:209], v[24:27]
	v_mfma_f32_16x16x32_bf16 v[28:31], v[136:139], v[206:209], v[28:31]
	v_mfma_f32_16x16x32_bf16 v[8:11], v[128:131], v[214:217], v[8:11]
	v_mfma_f32_16x16x32_bf16 v[12:15], v[136:139], v[214:217], v[12:15]
	v_mfma_f32_16x16x32_bf16 v[56:59], v[132:135], v[190:193], v[56:59]
	v_mfma_f32_16x16x32_bf16 v[60:63], v[140:143], v[190:193], v[60:63]
	v_mfma_f32_16x16x32_bf16 v[40:43], v[132:135], v[202:205], v[40:43]
	v_mfma_f32_16x16x32_bf16 v[44:47], v[140:143], v[202:205], v[44:47]
	v_mfma_f32_16x16x32_bf16 v[24:27], v[132:135], v[210:213], v[24:27]
	v_mfma_f32_16x16x32_bf16 v[28:31], v[140:143], v[210:213], v[28:31]
	v_mfma_f32_16x16x32_bf16 v[8:11], v[132:135], v[218:221], v[8:11]
	v_mfma_f32_16x16x32_bf16 v[12:15], v[140:143], v[218:221], v[12:15]
	v_mfma_f32_16x16x32_bf16 v[52:55], v[144:147], v[186:189], v[52:55]
	v_mfma_f32_16x16x32_bf16 v[48:51], v[168:171], v[186:189], v[48:51]
	v_mfma_f32_16x16x32_bf16 v[36:39], v[144:147], v[198:201], v[36:39]
	v_mfma_f32_16x16x32_bf16 v[32:35], v[168:171], v[198:201], v[32:35]
	v_mfma_f32_16x16x32_bf16 v[20:23], v[144:147], v[206:209], v[20:23]
	v_mfma_f32_16x16x32_bf16 v[16:19], v[168:171], v[206:209], v[16:19]
	v_mfma_f32_16x16x32_bf16 v[4:7], v[144:147], v[214:217], v[4:7]
	v_mfma_f32_16x16x32_bf16 v[0:3], v[168:171], v[214:217], v[0:3]
	v_mfma_f32_16x16x32_bf16 v[52:55], v[148:151], v[190:193], v[52:55]
	v_mfma_f32_16x16x32_bf16 v[48:51], v[172:175], v[190:193], v[48:51]
	v_mfma_f32_16x16x32_bf16 v[36:39], v[148:151], v[202:205], v[36:39]
	v_mfma_f32_16x16x32_bf16 v[32:35], v[172:175], v[202:205], v[32:35]
	v_mfma_f32_16x16x32_bf16 v[20:23], v[148:151], v[210:213], v[20:23]
	v_mfma_f32_16x16x32_bf16 v[16:19], v[172:175], v[210:213], v[16:19]
	v_mfma_f32_16x16x32_bf16 v[4:7], v[148:151], v[218:221], v[4:7]
	v_mfma_f32_16x16x32_bf16 v[0:3], v[172:175], v[218:221], v[0:3]
	s_barrier
	s_setprio 0
	s_add_i32 s53, s53, 2
	s_add_u32 s26, s26, 0x100
	s_addc_u32 s27, s27, 0
	s_add_u32 s49, s49, 0x100
	s_addc_u32 s52, s52, 0

; #define PG8_STAGE(bufoff, gbase, voff) do { _Pragma("unroll") for (int _i = 0; _i < 2; ++_i) \
;         __builtin_amdgcn_global_load_lds((const unsigned*)((const char*)(gbase) + (voff)[_i]), (PG8_LAS unsigned*)(lds + (bufoff) + ldsw + _i * 8192), 16, 0, 0); } while (0)
; #define PG8_WAIT_V(n) asm volatile("s_waitcnt vmcnt(" #n ")" ::: "memory")
; #define PG8_BAR __builtin_amdgcn_s_barrier()
; template <class Epi, class Sched, bool ALIGN_EPI = false, bool SP2 = false>
; __device__ __forceinline__ void gemm_phase(PG8_LAS unsigned char* lds, const Gemm g, const Sched& S, const Epi& E) {
;     ...
;         PG8_STAGE(PG8_SB(0, 0), cB, voffB); PG8_STAGE(PG8_SB(0, 1), cB + hstep, voffB); PG8_STAGE(PG8_SA(0, 0), cA, voffA); PG8_STAGE(PG8_SA(0, 1), cA + hstep, voffA);
;         if (wr == 1) PG8_BAR;
;         PG8_WAIT_V(2); PG8_BAR;
;         PG8_STAGE(PG8_SB(1, 0), cB + kstep, voffB); PG8_STAGE(PG8_SA(1, 0), cA + kstep, voffA); PG8_STAGE(PG8_SB(1, 1), cB + hstep + kstep, voffB);
;         PG8_WAIT_V(6); PG8_BAR;
;     __device__ __forceinline__ void operator()(const f32x4 (&acc)[2][2][4][2], const Unit& u, int wr, int wc, int fr, int fq) const {
;     ...
;                     if (fq == 0) xl[((ai * HALF + wr * 64 + m * 16 + fr) * 2 + bj) * 4 + wc] = sq;
;                 }
;         asm volatile("s_waitcnt lgkmcnt(0)" ::: "memory"); __builtin_amdgcn_s_barrier(); asm volatile("" ::: "memory");
;         const f32x4 ga = *(const f32x4*)(gn + wc * 32 + 8 * fq), gb = *(const f32x4*)(gn + wc * 32 + 8 * fq + 4);
; #pragma unroll
;         for (int ai = 0; ai < 2; ++ai)
; #pragma unroll
;             for (int m = 0; m < 4; ++m) {
;                 const int rl = ai * HALF + wr * 64 + m * 16 + fr; const float rs = rsv[ai][m];
;                 bf16_t* rowp = base + (size_t)(u.pm * BM + rl) * 2048 + col0;
; #pragma unroll
;                 for (int bj = 0; bj < 2; ++bj) {
;                     const f32x4 pp = *(const __attribute__((address_space(3))) f32x4*)(xl + (rl * 2 + bj) * 4);
.LBB0_944:
	v_bfe_u32 v14, v196, 4, 2
	v_and_b32_e32 v13, 15, v196
	v_lshlrev_b32_e32 v15, 4, v14
	v_lshlrev_b32_e32 v16, 2, v196
	s_and_b32 s1, s2, 3
	v_lshl_or_b32 v157, s3, 6, v13
	v_lshl_or_b32 v13, v13, 6, v15
	s_lshl_b32 s2, s3, 13
	v_and_b32_e32 v16, 32, v16
	s_mov_b64 s[10:11], 0x80
	v_bitop3_b32 v13, v13, s2, v16 bitop3:0xde
	v_lshlrev_b32_e32 v17, 6, v196
	s_movk_i32 s2, 0x3c0
	s_add_i32 m0, s35, 0x18000
	v_lshl_add_u64 v[6:7], v[6:7], 0, s[10:11]
	s_lshl_b32 s5, s1, 5
	v_and_or_b32 v15, v17, s2, v15
	s_lshl_b32 s2, s1, 12
	s_waitcnt vmcnt(2)
	s_barrier
	global_load_lds_dwordx4 v[6:7], off
	v_lshl_add_u64 v[2:3], v[2:3], 0, s[10:11]
	s_add_i32 m0, s35, 0x1a000
	s_add_i32 s46, s35, 0x8000
	s_add_i32 s47, s35, 0xa000
	v_bitop3_b32 v159, s2, v15, v16 bitop3:0xf6
	global_load_lds_dwordx4 v[2:3], off
	v_lshl_add_u64 v[0:1], v[0:1], 0, s[10:11]
	s_mov_b32 m0, s46
	s_add_u32 s2, s28, 0x80080
	global_load_lds_dwordx4 v[0:1], off
	v_lshl_add_u64 v[0:1], v[4:5], 0, s[10:11]
	s_mov_b32 m0, s47
	s_addc_u32 s3, s29, 0
	global_load_lds_dwordx4 v[0:1], off
	s_add_i32 m0, s35, 0x1c000
	v_lshl_add_u64 v[0:1], s[2:3], 0, v[142:143]
	global_load_lds_dwordx4 v[0:1], off
	v_lshl_add_u64 v[0:1], s[2:3], 0, v[146:147]
	s_add_i32 m0, s35, 0x1e000
	s_cmpk_lt_u32 s12, 0x100
	global_load_lds_dwordx4 v[0:1], off
	v_lshlrev_b32_e32 v12, 3, v14
	s_cselect_b64 s[12:13], -1, 0
	v_cmp_eq_u32_e64 s[2:3], 0, v14
	v_lshlrev_b32_e32 v0, 5, v157
	s_add_i32 s16, 0, 0x20000
	v_cvt_f32_u32_e32 v14, s15
	v_add_u32_e32 v199, s16, v0
	s_lshl_b32 s1, s1, 2
	v_add_u32_e32 v200, s1, v199
	s_add_i32 s1, s1, 0
	s_add_i32 s14, s1, 0x20200
	v_add_u32_e32 v201, s14, v0
	s_add_i32 s14, s1, 0x20400
	v_rcp_iflag_f32_e32 v14, v14
	v_add_u32_e32 v202, s14, v0
	s_add_i32 s14, s1, 0x20600
	v_add_u32_e32 v203, s14, v0
	s_add_i32 s14, s1, 0x21000
	v_add_u32_e32 v204, s14, v0
	s_add_i32 s14, s1, 0x21200
	v_add_u32_e32 v205, s14, v0
	s_add_i32 s14, s1, 0x21400
	s_add_i32 s1, s1, 0x21600
	v_mul_f32_e32 v14, 0x4f7ffffe, v14
	v_add_u32_e32 v206, s14, v0
	v_cvt_u32_f32_e32 v14, v14
	v_add_u32_e32 v207, s1, v0
	v_lshlrev_b32_e32 v0, 9, v196
	v_and_b32_e32 v0, 0x70000, v0
	v_lshlrev_b32_e32 v10, 12, v10
	v_or3_b32 v0, v8, v0, v10
	v_add_u32_e32 v150, v0, v9
	v_lshlrev_b32_e32 v0, 5, v11
	s_sub_i32 s1, 0, s15
	v_readfirstlane_b32 s14, v14
	v_and_b32_e32 v0, 0xf0000, v0
	s_waitcnt vmcnt(0)
	v_or_b32_e32 v197, 16, v157
	v_or_b32_e32 v214, 32, v157
	v_or_b32_e32 v165, 48, v157
	v_add_u32_e32 v169, 0x80, v157
	v_add_u32_e32 v173, 0x90, v157
	v_add_u32_e32 v177, 0xa0, v157
	v_add_u32_e32 v198, 0xb0, v157
	s_mul_i32 s1, s1, s14
	v_or3_b32 v0, v8, v0, v10
	v_lshlrev_b32_e32 v1, 5, v197
	v_lshlrev_b32_e32 v2, 5, v214
	v_lshlrev_b32_e32 v3, 5, v165
	v_lshlrev_b32_e32 v4, 5, v169
	v_lshlrev_b32_e32 v5, 5, v173
	v_lshlrev_b32_e32 v6, 5, v177
	v_lshlrev_b32_e32 v7, 5, v198
	s_mul_hi_u32 s1, s14, s1
	v_add_u32_e32 v152, v0, v9
	s_add_i32 s69, 0, 0x10000
	s_add_i32 s70, 0, 0x14000
	v_mbcnt_lo_u32_b32 v0, -1, 0
	s_ashr_i32 s64, s88, 31
	s_ashr_i32 s65, s89, 31
	v_or_b32_e32 v208, s5, v12
	s_add_i32 s68, s14, s1
	v_mov_b32_e32 v151, v149
	v_mov_b32_e32 v153, v149
	v_add_u32_e32 v209, s69, v159
	v_add_u32_e32 v210, s70, v159
	v_add_u32_e32 v211, 0, v13
	s_lshl_b32 s71, s5, 2
	v_lshlrev_b32_e32 v212, 2, v12
	s_brev_b32 s14, 60
	s_mov_b32 s72, 0x800000
	v_mbcnt_hi_u32_b32 v213, -1, v0
	v_add_u32_e32 v215, s16, v1
	v_add_u32_e32 v216, s16, v2
	v_add_u32_e32 v217, s16, v3
	v_add_u32_e32 v218, s16, v4
	v_add_u32_e32 v219, s16, v5
	v_add_u32_e32 v220, s16, v6
	v_add_u32_e32 v221, s16, v7
	s_barrier
	s_branch .LBB0_947

; #define PG8_STAGE(bufoff, gbase, voff) do { _Pragma("unroll") for (int _i = 0; _i < 2; ++_i) \
;         __builtin_amdgcn_global_load_lds((const unsigned*)((const char*)(gbase) + (voff)[_i]), (PG8_LAS unsigned*)(lds + (bufoff) + ldsw + _i * 8192), 16, 0, 0); } while (0)
; #define PG8_LDA(dst, b, h) do { _Pragma("unroll") for (int m = 0; m < 4; ++m) _Pragma("unroll") for (int k = 0; k < 2; ++k) dst[m][k] = *(const PG8_LAS bf16x8*)(lds + PG8_SA(b, h) + aoff + m * 2048 + k * 1024); } while (0)
; #define PG8_LDB(dst, b, h) do { _Pragma("unroll") for (int n = 0; n < 2; ++n) _Pragma("unroll") for (int k = 0; k < 2; ++k) dst[n][k] = *(const PG8_LAS bf16x8*)(lds + PG8_SB(b, h) + boff + n * 2048 + k * 1024); } while (0)
; #define PG8_WAIT_V(n) asm volatile("s_waitcnt vmcnt(" #n ")" ::: "memory")
; #define PG8_BAR __builtin_amdgcn_s_barrier()
; template <class Epi, class Sched, bool ALIGN_EPI = false, bool SP2 = false>
; __device__ __forceinline__ void gemm_phase(PG8_LAS unsigned char* lds, const Gemm g, const Sched& S, const Epi& E) {
;     ...
;         const char* nA = has_next ? (const char*)g.A + (size_t)nxt.pm * tstep : cA; const char* nB = has_next ? (const char*)g.Bt + (size_t)nxt.pn * tstep : cB;
;         for (int t = 0; t < nt; t += 2) {
;             const bool last = (t == nt - 2);
;             const char* a1 = cA + (size_t)(t + 1) * kstep;
;             const char* a2 = last ? nA : cA + (size_t)(t + 2) * kstep; const char* b2 = last ? nB : cB + (size_t)(t + 2) * kstep;
;             const char* a3 = a2 + kstep; const char* b3 = b2 + kstep;
;             if (last && has_next) S.a_ready(nxt);
;             if constexpr (SP2) {
;             PG8_LDB(B0, 0, 0); PG8_LDB(B1, 0, 1); PG8_SCHED; PG8_LDA(At, 0, 0); PG8_STAGE(PG8_SA(1, 1), a1 + hstep, voffA);
;             PG8_WAIT_V(8); PG8_WAIT_L(0); PG8_BAR; PG8_MMA(0, 0, At, B0); PG8_MMA(0, 1, At, B1); PG8_BAR; PG8_SCHED;
;             PG8_LDA(At, 0, 1); PG8_STAGE(PG8_SB(0, 0), b2, voffB); PG8_STAGE(PG8_SB(0, 1), b2 + hstep, voffB); PG8_STAGE(PG8_SA(0, 0), a2, voffA);
;     ...
; #pragma unroll
;         for (int a = 0; a < 2; ++a)
; #pragma unroll
;             for (int b = 0; b < 2; ++b)
; #pragma unroll
;                 for (int m = 0; m < 4; ++m)
; #pragma unroll
;                     for (int n = 0; n < 2; ++n) acc[a][b][m][n] = (f32x4){0.f, 0.f, 0.f, 0.f};
;         cur = nxt; cA = nA; cB = nB; ++ui;
.LBB0_954:
	s_ashr_i32 s53, s52, 31
	s_lshl_b64 s[22:23], s[52:53], 20
	s_add_u32 s54, s74, s22
	s_addc_u32 s55, s75, s23
	s_and_b64 s[24:25], s[62:63], exec
	s_cselect_b32 s1, s55, s27
	s_cselect_b32 s5, s54, s26
	s_ashr_i32 s41, s40, 31
	s_lshl_b64 s[24:25], s[40:41], 20
	s_add_u32 s56, s94, s24
	s_addc_u32 s57, s95, s25
	s_and_b64 s[30:31], s[62:63], exec
	s_cselect_b32 s17, s57, s29
	s_cselect_b32 s19, s56, s28
	s_add_u32 s26, s26, 0x80080
	s_addc_u32 s27, s27, 0
	s_add_u32 s33, s28, 0x100
	s_addc_u32 s44, s29, 0
	s_mov_b32 s45, -2
	s_waitcnt vmcnt(0)
	ds_read_b128 v[128:131], v209
	ds_read_b128 v[132:135], v209 offset:1024
	ds_read_b128 v[136:139], v209 offset:2048
	ds_read_b128 v[178:181], v209 offset:3072
	ds_read_b128 v[182:185], v210
	ds_read_b128 v[186:189], v210 offset:1024
	ds_read_b128 v[190:193], v210 offset:2048
	ds_read_b128 v[222:225], v210 offset:3072
	s_add_u32 s28, s26, 0xfff80080
	s_addc_u32 s29, s27, -1
	s_cmp_eq_u32 s45, 28
	s_cselect_b32 s31, s1, s29
	s_cselect_b32 s30, s5, s28
	s_cselect_b32 s29, s17, s44
	s_cselect_b32 s28, s19, s33
	v_lshl_add_u64 v[166:167], s[26:27], 0, v[150:151]
	s_add_i32 m0, s35, 0xc000
	ds_read_b128 v[226:229], v211
	ds_read_b128 v[230:233], v211 offset:1024
	ds_read_b128 v[234:237], v211 offset:2048
	ds_read_b128 v[238:241], v211 offset:3072
	ds_read_b128 v[242:245], v211 offset:4096
	ds_read_b128 v[246:249], v211 offset:5120
	ds_read_b128 v[250:253], v211 offset:6144
	ds_read_b128 v[160:163], v211 offset:7168
	global_load_lds_dwordx4 v[166:167], off
	v_lshl_add_u64 v[166:167], s[26:27], 0, v[152:153]
	s_add_i32 m0, s35, 0xe000
	s_nop 0
	global_load_lds_dwordx4 v[166:167], off
	s_nop 0
	s_waitcnt lgkmcnt(0)
	s_setprio 1
	s_barrier
	v_mfma_f32_16x16x32_bf16 v[124:127], v[128:131], v[226:229], 0
	v_mfma_f32_16x16x32_bf16 v[120:123], v[136:139], v[226:229], 0
	v_mfma_f32_16x16x32_bf16 v[116:119], v[128:131], v[234:237], 0
	v_mfma_f32_16x16x32_bf16 v[108:111], v[136:139], v[234:237], 0
	v_mfma_f32_16x16x32_bf16 v[100:103], v[128:131], v[242:245], 0
	v_mfma_f32_16x16x32_bf16 v[92:95], v[136:139], v[242:245], 0
	v_mfma_f32_16x16x32_bf16 v[84:87], v[128:131], v[250:253], 0
	v_mfma_f32_16x16x32_bf16 v[76:79], v[136:139], v[250:253], 0
	v_mfma_f32_16x16x32_bf16 v[124:127], v[132:135], v[230:233], v[124:127]
	v_mfma_f32_16x16x32_bf16 v[120:123], v[178:181], v[230:233], v[120:123]
	v_mfma_f32_16x16x32_bf16 v[116:119], v[132:135], v[238:241], v[116:119]
	v_mfma_f32_16x16x32_bf16 v[108:111], v[178:181], v[238:241], v[108:111]
	v_mfma_f32_16x16x32_bf16 v[100:103], v[132:135], v[246:249], v[100:103]
	v_mfma_f32_16x16x32_bf16 v[92:95], v[178:181], v[246:249], v[92:95]
	v_mfma_f32_16x16x32_bf16 v[84:87], v[132:135], v[160:163], v[84:87]
	v_mfma_f32_16x16x32_bf16 v[76:79], v[178:181], v[160:163], v[76:79]
	v_mfma_f32_16x16x32_bf16 v[112:115], v[182:185], v[226:229], 0
	v_mfma_f32_16x16x32_bf16 v[104:107], v[190:193], v[226:229], 0
	v_mfma_f32_16x16x32_bf16 v[96:99], v[182:185], v[234:237], 0
	v_mfma_f32_16x16x32_bf16 v[88:91], v[190:193], v[234:237], 0
	v_mfma_f32_16x16x32_bf16 v[80:83], v[182:185], v[242:245], 0
	v_mfma_f32_16x16x32_bf16 v[72:75], v[190:193], v[242:245], 0
	v_mfma_f32_16x16x32_bf16 v[68:71], v[182:185], v[250:253], 0
	v_mfma_f32_16x16x32_bf16 v[64:67], v[190:193], v[250:253], 0
	v_mfma_f32_16x16x32_bf16 v[112:115], v[186:189], v[230:233], v[112:115]
	v_mfma_f32_16x16x32_bf16 v[104:107], v[222:225], v[230:233], v[104:107]
	v_mfma_f32_16x16x32_bf16 v[96:99], v[186:189], v[238:241], v[96:99]
	v_mfma_f32_16x16x32_bf16 v[88:91], v[222:225], v[238:241], v[88:91]
	v_mfma_f32_16x16x32_bf16 v[80:83], v[186:189], v[246:249], v[80:83]
	v_mfma_f32_16x16x32_bf16 v[72:75], v[222:225], v[246:249], v[72:75]
	v_mfma_f32_16x16x32_bf16 v[68:71], v[186:189], v[160:163], v[68:71]
	v_mfma_f32_16x16x32_bf16 v[64:67], v[222:225], v[160:163], v[64:67]
	s_barrier
	s_setprio 0
	s_add_i32 s48, s69, s34
	v_lshl_add_u64 v[166:167], s[28:29], 0, v[142:143]
	s_mov_b32 m0, s48
	ds_read_b128 v[160:163], v211 offset:16384
	ds_read_b128 v[226:229], v211 offset:17408
	ds_read_b128 v[230:233], v211 offset:18432
	ds_read_b128 v[234:237], v211 offset:19456
	ds_read_b128 v[238:241], v211 offset:20480
	ds_read_b128 v[242:245], v211 offset:21504
	ds_read_b128 v[246:249], v211 offset:22528
	ds_read_b128 v[250:253], v211 offset:23552
	global_load_lds_dwordx4 v[166:167], off
	s_add_i32 m0, s48, 0x2000
	s_add_u32 s48, s28, 0x80000
	v_lshl_add_u64 v[170:171], s[28:29], 0, v[146:147]
	s_addc_u32 s49, s29, 0
	s_add_i32 s50, s70, s34
	global_load_lds_dwordx4 v[170:171], off
	v_lshl_add_u64 v[174:175], s[48:49], 0, v[142:143]
	s_mov_b32 m0, s50
	v_lshl_add_u64 v[194:195], s[30:31], 0, v[144:145]
	global_load_lds_dwordx4 v[174:175], off
	v_lshl_add_u64 v[174:175], s[48:49], 0, v[146:147]
	s_add_i32 m0, s50, 0x2000
	s_nop 0
	global_load_lds_dwordx4 v[174:175], off
	v_lshl_add_u64 v[174:175], s[30:31], 0, v[140:141]
	s_mov_b32 m0, s35
	s_nop 0
	global_load_lds_dwordx4 v[174:175], off
	s_mov_b32 m0, s37
	s_nop 0
	global_load_lds_dwordx4 v[194:195], off
	s_nop 0
	s_waitcnt lgkmcnt(0)
	s_setprio 1
	s_barrier
; #define PG8_STAGE(bufoff, gbase, voff) do { _Pragma("unroll") for (int _i = 0; _i < 2; ++_i) \
;         __builtin_amdgcn_global_load_lds((const unsigned*)((const char*)(gbase) + (voff)[_i]), (PG8_LAS unsigned*)(lds + (bufoff) + ldsw + _i * 8192), 16, 0, 0); } while (0)
; #define PG8_LDA(dst, b, h) do { _Pragma("unroll") for (int m = 0; m < 4; ++m) _Pragma("unroll") for (int k = 0; k < 2; ++k) dst[m][k] = *(const PG8_LAS bf16x8*)(lds + PG8_SA(b, h) + aoff + m * 2048 + k * 1024); } while (0)
; #define PG8_LDB(dst, b, h) do { _Pragma("unroll") for (int n = 0; n < 2; ++n) _Pragma("unroll") for (int k = 0; k < 2; ++k) dst[n][k] = *(const PG8_LAS bf16x8*)(lds + PG8_SB(b, h) + boff + n * 2048 + k * 1024); } while (0)
; #define PG8_MMA(ai, bj, At, Bt) do { __builtin_amdgcn_s_setprio(1); _Pragma("unroll") for (int m = 0; m < 4; ++m) _Pragma("unroll") for (int n = 0; n < 2; ++n) _Pragma("unroll") for (int k = 0; k < 2; ++k) \
;         acc[ai][bj][m][n] = __builtin_amdgcn_mfma_f32_16x16x32_bf16(Bt[n][k], At[m][k], acc[ai][bj][m][n], 0, 0, 0); __builtin_amdgcn_s_setprio(0); } while (0)
; #define PG8_WAIT_V(n) asm volatile("s_waitcnt vmcnt(" #n ")" ::: "memory")
; #define PG8_WAIT_L(n) asm volatile("s_waitcnt lgkmcnt(" #n ")" ::: "memory")
; #define PG8_BAR __builtin_amdgcn_s_barrier()
; #define PG8_SCHED __builtin_amdgcn_sched_barrier(0)
; template <class Epi, class Sched, bool ALIGN_EPI = false, bool SP2 = false>
; __device__ __forceinline__ void gemm_phase(PG8_LAS unsigned char* lds, const Gemm g, const Sched& S, const Epi& E) {
;     ...
;             PG8_WAIT_V(8); PG8_WAIT_L(0); PG8_BAR; PG8_MMA(1, 0, At, B0); PG8_MMA(1, 1, At, B1); PG8_BAR; PG8_SCHED;
;             PG8_LDB(B0, 1, 0); PG8_LDB(B1, 1, 1); PG8_SCHED; PG8_LDA(At, 1, 0); PG8_STAGE(PG8_SA(0, 1), a2 + hstep, voffA);
;             PG8_WAIT_V(8); PG8_WAIT_L(0); PG8_BAR; PG8_MMA(0, 0, At, B0); PG8_MMA(0, 1, At, B1); PG8_BAR; PG8_SCHED;
	v_mfma_f32_16x16x32_bf16 v[60:63], v[128:131], v[160:163], 0
	v_mfma_f32_16x16x32_bf16 v[56:59], v[136:139], v[160:163], 0
	v_mfma_f32_16x16x32_bf16 v[52:55], v[128:131], v[230:233], 0
	v_mfma_f32_16x16x32_bf16 v[44:47], v[136:139], v[230:233], 0
	v_mfma_f32_16x16x32_bf16 v[36:39], v[128:131], v[238:241], 0
	v_mfma_f32_16x16x32_bf16 v[28:31], v[136:139], v[238:241], 0
	v_mfma_f32_16x16x32_bf16 v[20:23], v[128:131], v[246:249], 0
	v_mfma_f32_16x16x32_bf16 v[12:15], v[136:139], v[246:249], 0
	v_mfma_f32_16x16x32_bf16 v[60:63], v[132:135], v[226:229], v[60:63]
	v_mfma_f32_16x16x32_bf16 v[56:59], v[178:181], v[226:229], v[56:59]
	v_mfma_f32_16x16x32_bf16 v[52:55], v[132:135], v[234:237], v[52:55]
	v_mfma_f32_16x16x32_bf16 v[44:47], v[178:181], v[234:237], v[44:47]
	v_mfma_f32_16x16x32_bf16 v[36:39], v[132:135], v[242:245], v[36:39]
	v_mfma_f32_16x16x32_bf16 v[28:31], v[178:181], v[242:245], v[28:31]
	v_mfma_f32_16x16x32_bf16 v[20:23], v[132:135], v[250:253], v[20:23]
	v_mfma_f32_16x16x32_bf16 v[12:15], v[178:181], v[250:253], v[12:15]
	v_mfma_f32_16x16x32_bf16 v[48:51], v[182:185], v[160:163], 0
	v_mfma_f32_16x16x32_bf16 v[40:43], v[190:193], v[160:163], 0
	v_mfma_f32_16x16x32_bf16 v[32:35], v[182:185], v[230:233], 0
	v_mfma_f32_16x16x32_bf16 v[24:27], v[190:193], v[230:233], 0
	v_mfma_f32_16x16x32_bf16 v[16:19], v[182:185], v[238:241], 0
	v_mfma_f32_16x16x32_bf16 v[8:11], v[190:193], v[238:241], 0
	v_mfma_f32_16x16x32_bf16 v[4:7], v[182:185], v[246:249], 0
	v_mfma_f32_16x16x32_bf16 v[0:3], v[190:193], v[246:249], 0
	v_mfma_f32_16x16x32_bf16 v[48:51], v[186:189], v[226:229], v[48:51]
	v_mfma_f32_16x16x32_bf16 v[40:43], v[222:225], v[226:229], v[40:43]
	v_mfma_f32_16x16x32_bf16 v[32:35], v[186:189], v[234:237], v[32:35]
	v_mfma_f32_16x16x32_bf16 v[24:27], v[222:225], v[234:237], v[24:27]
	v_mfma_f32_16x16x32_bf16 v[16:19], v[186:189], v[242:245], v[16:19]
	v_mfma_f32_16x16x32_bf16 v[8:11], v[222:225], v[242:245], v[8:11]
	v_mfma_f32_16x16x32_bf16 v[4:7], v[186:189], v[250:253], v[4:7]
	v_mfma_f32_16x16x32_bf16 v[0:3], v[222:225], v[250:253], v[0:3]
	s_barrier
	s_setprio 0
	s_add_i32 s48, 0, 0x18000
	v_add_u32_e32 v148, s48, v159
	s_add_i32 s49, 0, 0x1c000
	ds_read_b128 v[128:131], v148
	ds_read_b128 v[132:135], v148 offset:1024
	ds_read_b128 v[136:139], v148 offset:2048
	ds_read_b128 v[160:163], v148 offset:3072
	v_add_u32_e32 v148, s49, v159
	ds_read_b128 v[178:181], v148
	ds_read_b128 v[182:185], v148 offset:1024
	ds_read_b128 v[186:189], v148 offset:2048
	ds_read_b128 v[190:193], v148 offset:3072
	s_add_u32 s30, s30, 0x80000
	s_addc_u32 s31, s31, 0
	s_mov_b32 m0, s39
	v_lshl_add_u64 v[154:155], s[30:31], 0, v[140:141]
	ds_read_b128 v[222:225], v211 offset:32768
	ds_read_b128 v[226:229], v211 offset:33792
	ds_read_b128 v[230:233], v211 offset:34816
	ds_read_b128 v[234:237], v211 offset:35840
	ds_read_b128 v[238:241], v211 offset:36864
	ds_read_b128 v[242:245], v211 offset:37888
	ds_read_b128 v[246:249], v211 offset:38912
	ds_read_b128 v[250:253], v211 offset:39936
	global_load_lds_dwordx4 v[154:155], off
	v_lshl_add_u64 v[154:155], s[30:31], 0, v[144:145]
	s_mov_b32 m0, s42
	s_nop 0
	global_load_lds_dwordx4 v[154:155], off
	s_waitcnt vmcnt(8)
	s_waitcnt lgkmcnt(0)
	s_setprio 1
	s_barrier
	v_mfma_f32_16x16x32_bf16 v[124:127], v[128:131], v[222:225], v[124:127]
	v_mfma_f32_16x16x32_bf16 v[120:123], v[136:139], v[222:225], v[120:123]
	v_mfma_f32_16x16x32_bf16 v[116:119], v[128:131], v[230:233], v[116:119]
	v_mfma_f32_16x16x32_bf16 v[108:111], v[136:139], v[230:233], v[108:111]
	v_mfma_f32_16x16x32_bf16 v[100:103], v[128:131], v[238:241], v[100:103]
	v_mfma_f32_16x16x32_bf16 v[92:95], v[136:139], v[238:241], v[92:95]
	v_mfma_f32_16x16x32_bf16 v[84:87], v[128:131], v[246:249], v[84:87]
	v_mfma_f32_16x16x32_bf16 v[76:79], v[136:139], v[246:249], v[76:79]
	v_mfma_f32_16x16x32_bf16 v[124:127], v[132:135], v[226:229], v[124:127]
	v_mfma_f32_16x16x32_bf16 v[120:123], v[160:163], v[226:229], v[120:123]
	v_mfma_f32_16x16x32_bf16 v[116:119], v[132:135], v[234:237], v[116:119]
	v_mfma_f32_16x16x32_bf16 v[108:111], v[160:163], v[234:237], v[108:111]
	v_mfma_f32_16x16x32_bf16 v[100:103], v[132:135], v[242:245], v[100:103]
	v_mfma_f32_16x16x32_bf16 v[92:95], v[160:163], v[242:245], v[92:95]
	v_mfma_f32_16x16x32_bf16 v[84:87], v[132:135], v[250:253], v[84:87]
	v_mfma_f32_16x16x32_bf16 v[76:79], v[160:163], v[250:253], v[76:79]
	v_mfma_f32_16x16x32_bf16 v[112:115], v[178:181], v[222:225], v[112:115]
	v_mfma_f32_16x16x32_bf16 v[104:107], v[186:189], v[222:225], v[104:107]
	v_mfma_f32_16x16x32_bf16 v[96:99], v[178:181], v[230:233], v[96:99]
	v_mfma_f32_16x16x32_bf16 v[88:91], v[186:189], v[230:233], v[88:91]
	v_mfma_f32_16x16x32_bf16 v[80:83], v[178:181], v[238:241], v[80:83]
	v_mfma_f32_16x16x32_bf16 v[72:75], v[186:189], v[238:241], v[72:75]
	v_mfma_f32_16x16x32_bf16 v[68:71], v[178:181], v[246:249], v[68:71]
	v_mfma_f32_16x16x32_bf16 v[64:67], v[186:189], v[246:249], v[64:67]
	v_mfma_f32_16x16x32_bf16 v[112:115], v[182:185], v[226:229], v[112:115]
	v_mfma_f32_16x16x32_bf16 v[104:107], v[190:193], v[226:229], v[104:107]
	v_mfma_f32_16x16x32_bf16 v[96:99], v[182:185], v[234:237], v[96:99]
	v_mfma_f32_16x16x32_bf16 v[88:91], v[190:193], v[234:237], v[88:91]
	v_mfma_f32_16x16x32_bf16 v[80:83], v[182:185], v[242:245], v[80:83]
	v_mfma_f32_16x16x32_bf16 v[72:75], v[190:193], v[242:245], v[72:75]
	v_mfma_f32_16x16x32_bf16 v[68:71], v[182:185], v[250:253], v[68:71]
	v_mfma_f32_16x16x32_bf16 v[64:67], v[190:193], v[250:253], v[64:67]
	s_barrier
; #define PG8_STAGE(bufoff, gbase, voff) do { _Pragma("unroll") for (int _i = 0; _i < 2; ++_i) \
;         __builtin_amdgcn_global_load_lds((const unsigned*)((const char*)(gbase) + (voff)[_i]), (PG8_LAS unsigned*)(lds + (bufoff) + ldsw + _i * 8192), 16, 0, 0); } while (0)
; #define PG8_LDA(dst, b, h) do { _Pragma("unroll") for (int m = 0; m < 4; ++m) _Pragma("unroll") for (int k = 0; k < 2; ++k) dst[m][k] = *(const PG8_LAS bf16x8*)(lds + PG8_SA(b, h) + aoff + m * 2048 + k * 1024); } while (0)
; #define PG8_MMA(ai, bj, At, Bt) do { __builtin_amdgcn_s_setprio(1); _Pragma("unroll") for (int m = 0; m < 4; ++m) _Pragma("unroll") for (int n = 0; n < 2; ++n) _Pragma("unroll") for (int k = 0; k < 2; ++k) \
;         acc[ai][bj][m][n] = __builtin_amdgcn_mfma_f32_16x16x32_bf16(Bt[n][k], At[m][k], acc[ai][bj][m][n], 0, 0, 0); __builtin_amdgcn_s_setprio(0); } while (0)
; #define PG8_WAIT_V(n) asm volatile("s_waitcnt vmcnt(" #n ")" ::: "memory")
; #define PG8_WAIT_L(n) asm volatile("s_waitcnt lgkmcnt(" #n ")" ::: "memory")
; #define PG8_BAR __builtin_amdgcn_s_barrier()
; #define PG8_SCHED __builtin_amdgcn_sched_barrier(0)
; template <class Epi, class Sched, bool ALIGN_EPI = false, bool SP2 = false>
; __device__ __forceinline__ void gemm_phase(PG8_LAS unsigned char* lds, const Gemm g, const Sched& S, const Epi& E) {
;     ...
;             PG8_LDA(At, 1, 1); PG8_STAGE(PG8_SB(1, 0), b3, voffB); PG8_STAGE(PG8_SB(1, 1), b3 + hstep, voffB); PG8_STAGE(PG8_SA(1, 0), a3, voffA);
;             PG8_WAIT_V(8); PG8_WAIT_L(0); PG8_BAR; PG8_MMA(1, 0, At, B0); PG8_MMA(1, 1, At, B1); PG8_BAR; PG8_SCHED;
	s_setprio 0
	s_add_i32 s30, s48, s34
	v_lshl_add_u64 v[154:155], v[166:167], 0, s[10:11]
	s_mov_b32 m0, s30
	ds_read_b128 v[222:225], v211 offset:49152
	ds_read_b128 v[226:229], v211 offset:50176
	ds_read_b128 v[230:233], v211 offset:51200
	ds_read_b128 v[234:237], v211 offset:52224
	ds_read_b128 v[238:241], v211 offset:53248
	ds_read_b128 v[242:245], v211 offset:54272
	ds_read_b128 v[246:249], v211 offset:55296
	ds_read_b128 v[250:253], v211 offset:56320
	global_load_lds_dwordx4 v[154:155], off
	s_add_i32 m0, s30, 0x2000
	s_add_u32 s28, s28, 0x80080
	v_lshl_add_u64 v[154:155], v[170:171], 0, s[10:11]
	s_addc_u32 s29, s29, 0
	s_add_i32 s30, s49, s34
	global_load_lds_dwordx4 v[154:155], off
	v_lshl_add_u64 v[154:155], s[28:29], 0, v[142:143]
	s_mov_b32 m0, s30
	s_nop 0
	global_load_lds_dwordx4 v[154:155], off
	v_lshl_add_u64 v[154:155], s[28:29], 0, v[146:147]
	s_add_i32 m0, s30, 0x2000
	s_nop 0
	global_load_lds_dwordx4 v[154:155], off
	v_lshl_add_u64 v[154:155], v[174:175], 0, s[10:11]
	s_mov_b32 m0, s46
	s_nop 0
	global_load_lds_dwordx4 v[154:155], off
	v_lshl_add_u64 v[154:155], v[194:195], 0, s[10:11]
	s_mov_b32 m0, s47
	s_nop 0
	global_load_lds_dwordx4 v[154:155], off
	s_waitcnt vmcnt(8)
	s_waitcnt lgkmcnt(0)
	s_setprio 1
	s_barrier
	v_mfma_f32_16x16x32_bf16 v[60:63], v[128:131], v[222:225], v[60:63]
	v_mfma_f32_16x16x32_bf16 v[56:59], v[136:139], v[222:225], v[56:59]
	v_mfma_f32_16x16x32_bf16 v[52:55], v[128:131], v[230:233], v[52:55]
	v_mfma_f32_16x16x32_bf16 v[44:47], v[136:139], v[230:233], v[44:47]
	v_mfma_f32_16x16x32_bf16 v[36:39], v[128:131], v[238:241], v[36:39]
	v_mfma_f32_16x16x32_bf16 v[28:31], v[136:139], v[238:241], v[28:31]
	v_mfma_f32_16x16x32_bf16 v[20:23], v[128:131], v[246:249], v[20:23]
	v_mfma_f32_16x16x32_bf16 v[12:15], v[136:139], v[246:249], v[12:15]
	v_mfma_f32_16x16x32_bf16 v[60:63], v[132:135], v[226:229], v[60:63]
	v_mfma_f32_16x16x32_bf16 v[56:59], v[160:163], v[226:229], v[56:59]
	v_mfma_f32_16x16x32_bf16 v[52:55], v[132:135], v[234:237], v[52:55]
	v_mfma_f32_16x16x32_bf16 v[44:47], v[160:163], v[234:237], v[44:47]
	v_mfma_f32_16x16x32_bf16 v[36:39], v[132:135], v[242:245], v[36:39]
	v_mfma_f32_16x16x32_bf16 v[28:31], v[160:163], v[242:245], v[28:31]
	v_mfma_f32_16x16x32_bf16 v[20:23], v[132:135], v[250:253], v[20:23]
	v_mfma_f32_16x16x32_bf16 v[12:15], v[160:163], v[250:253], v[12:15]
	v_mfma_f32_16x16x32_bf16 v[48:51], v[178:181], v[222:225], v[48:51]
	v_mfma_f32_16x16x32_bf16 v[40:43], v[186:189], v[222:225], v[40:43]
	v_mfma_f32_16x16x32_bf16 v[32:35], v[178:181], v[230:233], v[32:35]
	v_mfma_f32_16x16x32_bf16 v[24:27], v[186:189], v[230:233], v[24:27]
	v_mfma_f32_16x16x32_bf16 v[16:19], v[178:181], v[238:241], v[16:19]
	v_mfma_f32_16x16x32_bf16 v[8:11], v[186:189], v[238:241], v[8:11]
	v_mfma_f32_16x16x32_bf16 v[4:7], v[178:181], v[246:249], v[4:7]
	v_mfma_f32_16x16x32_bf16 v[0:3], v[186:189], v[246:249], v[0:3]
	v_mfma_f32_16x16x32_bf16 v[48:51], v[182:185], v[226:229], v[48:51]
	v_mfma_f32_16x16x32_bf16 v[40:43], v[190:193], v[226:229], v[40:43]
	v_mfma_f32_16x16x32_bf16 v[32:35], v[182:185], v[234:237], v[32:35]
	v_mfma_f32_16x16x32_bf16 v[24:27], v[190:193], v[234:237], v[24:27]
	v_mfma_f32_16x16x32_bf16 v[16:19], v[182:185], v[242:245], v[16:19]
	v_mfma_f32_16x16x32_bf16 v[8:11], v[190:193], v[242:245], v[8:11]
	v_mfma_f32_16x16x32_bf16 v[4:7], v[182:185], v[250:253], v[4:7]
	v_mfma_f32_16x16x32_bf16 v[0:3], v[190:193], v[250:253], v[0:3]
	s_barrier
	s_setprio 0
	s_add_i32 s45, s45, 2
	s_add_u32 s26, s26, 0x100
	s_addc_u32 s27, s27, 0
	s_add_u32 s33, s33, 0x100
	s_addc_u32 s44, s44, 0

; #define PG8_STAGE(bufoff, gbase, voff) do { _Pragma("unroll") for (int _i = 0; _i < 2; ++_i) \
;         __builtin_amdgcn_global_load_lds((const unsigned*)((const char*)(gbase) + (voff)[_i]), (PG8_LAS unsigned*)(lds + (bufoff) + ldsw + _i * 8192), 16, 0, 0); } while (0)
; #define PG8_WAIT_V(n) asm volatile("s_waitcnt vmcnt(" #n ")" ::: "memory")
; #define PG8_BAR __builtin_amdgcn_s_barrier()
; template <class Epi, class Sched, bool ALIGN_EPI = false, bool SP2 = false>
; __device__ __forceinline__ void gemm_phase(PG8_LAS unsigned char* lds, const Gemm g, const Sched& S, const Epi& E) {
;     ...
;         PG8_STAGE(PG8_SB(0, 0), cB, voffB); PG8_STAGE(PG8_SB(0, 1), cB + hstep, voffB); PG8_STAGE(PG8_SA(0, 0), cA, voffA); PG8_STAGE(PG8_SA(0, 1), cA + hstep, voffA);
;         if (wr == 1) PG8_BAR;
;         PG8_WAIT_V(2); PG8_BAR;
;         PG8_STAGE(PG8_SB(1, 0), cB + kstep, voffB); PG8_STAGE(PG8_SA(1, 0), cA + kstep, voffA); PG8_STAGE(PG8_SB(1, 1), cB + hstep + kstep, voffB);
;         PG8_WAIT_V(6); PG8_BAR;
.LBB0_1170:
	s_mov_b64 s[12:13], 0x80
	s_and_b32 s38, s3, 3
	s_add_i32 m0, s35, 0x18000
	v_lshl_add_u64 v[6:7], v[6:7], 0, s[12:13]
	s_lshl_b32 s3, s2, 13
	s_lshl_b32 s7, s38, 12
	s_waitcnt vmcnt(2)
	s_barrier
	global_load_lds_dwordx4 v[6:7], off
	v_lshl_add_u64 v[4:5], v[4:5], 0, s[12:13]
	s_add_i32 m0, s35, 0x1a000
	s_add_i32 s39, s35, 0x8000
	s_add_i32 s40, s35, 0xa000
	global_load_lds_dwordx4 v[4:5], off
	v_lshl_add_u64 v[0:1], v[0:1], 0, s[12:13]
	s_mov_b32 m0, s39
	s_add_u32 s4, s28, 0x80080
	global_load_lds_dwordx4 v[0:1], off
	v_lshl_add_u64 v[0:1], v[2:3], 0, s[12:13]
	s_mov_b32 m0, s40
	s_addc_u32 s5, s29, 0
	global_load_lds_dwordx4 v[0:1], off
	s_add_i32 m0, s35, 0x1c000
	v_lshl_add_u64 v[0:1], s[4:5], 0, v[154:155]
	global_load_lds_dwordx4 v[0:1], off
	v_lshl_add_u64 v[0:1], s[4:5], 0, v[158:159]
	s_add_i32 m0, s35, 0x1e000
	v_lshlrev_b32_e32 v4, 2, v196
	global_load_lds_dwordx4 v[0:1], off
	v_bfe_u32 v0, v196, 4, 2
	v_and_b32_e32 v1, 15, v196
	v_lshlrev_b32_e32 v3, 4, v0
	v_lshl_or_b32 v178, s2, 6, v1
	v_lshl_or_b32 v1, v1, 6, v3
	v_and_b32_e32 v4, 32, v4
	v_lshlrev_b32_e32 v5, 6, v196
	s_movk_i32 s2, 0x3c0
	v_lshlrev_b32_e32 v2, 3, v0
	v_bitop3_b32 v1, v1, s3, v4 bitop3:0xde
	v_and_or_b32 v3, v5, s2, v3
	v_cmp_eq_u32_e64 s[2:3], 0, v0
	v_lshlrev_b32_e32 v0, 9, v196
	v_lshl_or_b32 v180, s38, 5, v2
	v_and_b32_e32 v0, 0x70000, v0
	v_lshlrev_b32_e32 v2, 12, v10
	v_or3_b32 v0, v8, v0, v2
	s_cmpk_lt_u32 s14, 0x100
	v_add_u32_e32 v160, v0, v9
	v_lshlrev_b32_e32 v0, 5, v11
	s_cselect_b64 s[14:15], -1, 0
	s_ashr_i32 s41, s88, 31
	s_ashr_i32 s42, s89, 31
	v_and_b32_e32 v0, 0xf0000, v0
	s_waitcnt vmcnt(0)
	s_cmp_lg_u64 s[50:51], 0
	v_or3_b32 v0, v8, v0, v2
	v_bitop3_b32 v179, s7, v3, v4 bitop3:0xf6
	s_cselect_b64 s[16:17], -1, 0
	v_add_u32_e32 v162, v0, v9
	s_add_i32 s43, 0, 0x10000
	s_add_i32 s44, 0, 0x14000
	v_mbcnt_lo_u32_b32 v0, -1, 0
	v_mov_b32_e32 v161, v155
	v_mov_b32_e32 v163, v155
	v_mov_b64_e32 v[164:165], 0x400
	v_mov_b64_e32 v[166:167], 0x3ff
	v_add_u32_e32 v181, s43, v179
	v_add_u32_e32 v182, s44, v179
	v_add_u32_e32 v183, 0, v1
	v_mbcnt_hi_u32_b32 v184, -1, v0
	s_mov_b32 s45, 0
	s_barrier
	s_branch .LBB0_1173

; #define PG8_STAGE(bufoff, gbase, voff) do { _Pragma("unroll") for (int _i = 0; _i < 2; ++_i) \
;         __builtin_amdgcn_global_load_lds((const unsigned*)((const char*)(gbase) + (voff)[_i]), (PG8_LAS unsigned*)(lds + (bufoff) + ldsw + _i * 8192), 16, 0, 0); } while (0)
; #define PG8_LDA(dst, b, h) do { _Pragma("unroll") for (int m = 0; m < 4; ++m) _Pragma("unroll") for (int k = 0; k < 2; ++k) dst[m][k] = *(const PG8_LAS bf16x8*)(lds + PG8_SA(b, h) + aoff + m * 2048 + k * 1024); } while (0)
; #define PG8_LDB(dst, b, h) do { _Pragma("unroll") for (int n = 0; n < 2; ++n) _Pragma("unroll") for (int k = 0; k < 2; ++k) dst[n][k] = *(const PG8_LAS bf16x8*)(lds + PG8_SB(b, h) + boff + n * 2048 + k * 1024); } while (0)
; #define PG8_WAIT_V(n) asm volatile("s_waitcnt vmcnt(" #n ")" ::: "memory")
; #define PG8_BAR __builtin_amdgcn_s_barrier()
; template <class Epi, class Sched, bool ALIGN_EPI = false, bool SP2 = false>
; __device__ __forceinline__ void gemm_phase(PG8_LAS unsigned char* lds, const Gemm g, const Sched& S, const Epi& E) {
;     ...
;         const char* nA = has_next ? (const char*)g.A + (size_t)nxt.pm * tstep : cA; const char* nB = has_next ? (const char*)g.Bt + (size_t)nxt.pn * tstep : cB;
;         for (int t = 0; t < nt; t += 2) {
;             const bool last = (t == nt - 2);
;             const char* a1 = cA + (size_t)(t + 1) * kstep;
;             const char* a2 = last ? nA : cA + (size_t)(t + 2) * kstep; const char* b2 = last ? nB : cB + (size_t)(t + 2) * kstep;
;             const char* a3 = a2 + kstep; const char* b3 = b2 + kstep;
;             if (last && has_next) S.a_ready(nxt);
;             if constexpr (SP2) {
;             PG8_LDB(B0, 0, 0); PG8_LDB(B1, 0, 1); PG8_SCHED; PG8_LDA(At, 0, 0); PG8_STAGE(PG8_SA(1, 1), a1 + hstep, voffA);
;             PG8_WAIT_V(8); PG8_WAIT_L(0); PG8_BAR; PG8_MMA(0, 0, At, B0); PG8_MMA(0, 1, At, B1); PG8_BAR; PG8_SCHED;
;             PG8_LDA(At, 0, 1); PG8_STAGE(PG8_SB(0, 0), b2, voffB); PG8_STAGE(PG8_SB(0, 1), b2 + hstep, voffB); PG8_STAGE(PG8_SA(0, 0), a2, voffA);
;     ...
; #pragma unroll
;         for (int a = 0; a < 2; ++a)
; #pragma unroll
;             for (int b = 0; b < 2; ++b)
; #pragma unroll
;                 for (int m = 0; m < 4; ++m)
; #pragma unroll
;                     for (int n = 0; n < 2; ++n) acc[a][b][m][n] = (f32x4){0.f, 0.f, 0.f, 0.f};
;         cur = nxt; cA = nA; cB = nB; ++ui;
.LBB0_1179:
	s_ashr_i32 s21, s20, 31
	s_lshl_b64 s[22:23], s[20:21], 20
	s_add_u32 s22, s56, s22
	s_addc_u32 s23, s57, s23
	s_and_b64 s[24:25], s[4:5], exec
	s_cselect_b32 s7, s23, s27
	s_cselect_b32 s21, s22, s26
	s_ashr_i32 s19, s18, 31
	s_lshl_b64 s[24:25], s[18:19], 20
	s_add_u32 s24, s68, s24
	s_addc_u32 s25, s69, s25
	s_and_b64 s[30:31], s[4:5], exec
	s_cselect_b32 s19, s25, s29
	s_cselect_b32 s46, s24, s28
	s_add_u32 s26, s26, 0x80080
	s_addc_u32 s27, s27, 0
	s_add_u32 s47, s28, 0x100
	s_addc_u32 s48, s29, 0
	s_mov_b32 s49, -2
	s_waitcnt lgkmcnt(0)
	ds_read_b128 v[128:131], v181
	ds_read_b128 v[132:135], v181 offset:1024
	ds_read_b128 v[136:139], v181 offset:2048
	ds_read_b128 v[140:143], v181 offset:3072
	ds_read_b128 v[144:147], v182
	ds_read_b128 v[148:151], v182 offset:1024
	ds_read_b128 v[168:171], v182 offset:2048
	ds_read_b128 v[172:175], v182 offset:3072
	s_add_u32 s28, s26, 0xfff80080
	s_addc_u32 s29, s27, -1
	s_cmp_eq_u32 s49, 28
	s_cselect_b32 s31, s7, s29
	s_cselect_b32 s30, s21, s28
	s_cselect_b32 s29, s19, s48
	s_cselect_b32 s28, s46, s47
	v_lshl_add_u64 v[176:177], s[26:27], 0, v[160:161]
	s_add_i32 m0, s35, 0xc000
	ds_read_b128 v[186:189], v183
	ds_read_b128 v[190:193], v183 offset:1024
	ds_read_b128 v[198:201], v183 offset:2048
	ds_read_b128 v[202:205], v183 offset:3072
	ds_read_b128 v[206:209], v183 offset:4096
	ds_read_b128 v[210:213], v183 offset:5120
	ds_read_b128 v[214:217], v183 offset:6144
	ds_read_b128 v[218:221], v183 offset:7168
	global_load_lds_dwordx4 v[176:177], off
	v_lshl_add_u64 v[176:177], s[26:27], 0, v[162:163]
	s_add_i32 m0, s35, 0xe000
	s_nop 0
	global_load_lds_dwordx4 v[176:177], off
	s_nop 0
	s_waitcnt lgkmcnt(0)
	s_setprio 1
	s_barrier
	v_mfma_f32_16x16x32_bf16 v[124:127], v[128:131], v[186:189], 0
	v_mfma_f32_16x16x32_bf16 v[120:123], v[136:139], v[186:189], 0
	v_mfma_f32_16x16x32_bf16 v[104:107], v[128:131], v[198:201], 0
	v_mfma_f32_16x16x32_bf16 v[108:111], v[136:139], v[198:201], 0
	v_mfma_f32_16x16x32_bf16 v[88:91], v[128:131], v[206:209], 0
	v_mfma_f32_16x16x32_bf16 v[92:95], v[136:139], v[206:209], 0
	v_mfma_f32_16x16x32_bf16 v[72:75], v[128:131], v[214:217], 0
	v_mfma_f32_16x16x32_bf16 v[76:79], v[136:139], v[214:217], 0
	v_mfma_f32_16x16x32_bf16 v[124:127], v[132:135], v[190:193], v[124:127]
	v_mfma_f32_16x16x32_bf16 v[120:123], v[140:143], v[190:193], v[120:123]
	v_mfma_f32_16x16x32_bf16 v[104:107], v[132:135], v[202:205], v[104:107]
	v_mfma_f32_16x16x32_bf16 v[108:111], v[140:143], v[202:205], v[108:111]
	v_mfma_f32_16x16x32_bf16 v[88:91], v[132:135], v[210:213], v[88:91]
	v_mfma_f32_16x16x32_bf16 v[92:95], v[140:143], v[210:213], v[92:95]
	v_mfma_f32_16x16x32_bf16 v[72:75], v[132:135], v[218:221], v[72:75]
	v_mfma_f32_16x16x32_bf16 v[76:79], v[140:143], v[218:221], v[76:79]
	v_mfma_f32_16x16x32_bf16 v[116:119], v[144:147], v[186:189], 0
	v_mfma_f32_16x16x32_bf16 v[112:115], v[168:171], v[186:189], 0
	v_mfma_f32_16x16x32_bf16 v[100:103], v[144:147], v[198:201], 0
	v_mfma_f32_16x16x32_bf16 v[96:99], v[168:171], v[198:201], 0
	v_mfma_f32_16x16x32_bf16 v[84:87], v[144:147], v[206:209], 0
	v_mfma_f32_16x16x32_bf16 v[80:83], v[168:171], v[206:209], 0
	v_mfma_f32_16x16x32_bf16 v[68:71], v[144:147], v[214:217], 0
	v_mfma_f32_16x16x32_bf16 v[64:67], v[168:171], v[214:217], 0
	v_mfma_f32_16x16x32_bf16 v[116:119], v[148:151], v[190:193], v[116:119]
	v_mfma_f32_16x16x32_bf16 v[112:115], v[172:175], v[190:193], v[112:115]
	v_mfma_f32_16x16x32_bf16 v[100:103], v[148:151], v[202:205], v[100:103]
	v_mfma_f32_16x16x32_bf16 v[96:99], v[172:175], v[202:205], v[96:99]
	v_mfma_f32_16x16x32_bf16 v[84:87], v[148:151], v[210:213], v[84:87]
	v_mfma_f32_16x16x32_bf16 v[80:83], v[172:175], v[210:213], v[80:83]
	v_mfma_f32_16x16x32_bf16 v[68:71], v[148:151], v[218:221], v[68:71]
	v_mfma_f32_16x16x32_bf16 v[64:67], v[172:175], v[218:221], v[64:67]
	s_barrier
	s_setprio 0
	s_add_i32 s50, s43, s34
	v_lshl_add_u64 v[176:177], s[28:29], 0, v[154:155]
	s_mov_b32 m0, s50
	ds_read_b128 v[186:189], v183 offset:16384
	ds_read_b128 v[190:193], v183 offset:17408
	ds_read_b128 v[198:201], v183 offset:18432
	ds_read_b128 v[202:205], v183 offset:19456
	ds_read_b128 v[206:209], v183 offset:20480
	ds_read_b128 v[210:213], v183 offset:21504
	ds_read_b128 v[214:217], v183 offset:22528
	ds_read_b128 v[218:221], v183 offset:23552
	global_load_lds_dwordx4 v[176:177], off
	s_add_i32 m0, s50, 0x2000
	s_add_u32 s50, s28, 0x80000
	v_lshl_add_u64 v[194:195], s[28:29], 0, v[158:159]
	s_addc_u32 s51, s29, 0
	s_add_i32 s52, s44, s34
	global_load_lds_dwordx4 v[194:195], off
	v_lshl_add_u64 v[222:223], s[50:51], 0, v[154:155]
	s_mov_b32 m0, s52
	v_lshl_add_u64 v[224:225], s[30:31], 0, v[156:157]
	global_load_lds_dwordx4 v[222:223], off
	v_lshl_add_u64 v[222:223], s[50:51], 0, v[158:159]
	s_add_i32 m0, s52, 0x2000
	s_nop 0
	global_load_lds_dwordx4 v[222:223], off
	v_lshl_add_u64 v[222:223], s[30:31], 0, v[152:153]
	s_mov_b32 m0, s35
	s_nop 0
	global_load_lds_dwordx4 v[222:223], off
	s_mov_b32 m0, s33
	s_nop 0
	global_load_lds_dwordx4 v[224:225], off
	s_nop 0
	s_waitcnt lgkmcnt(0)
	s_setprio 1
	s_barrier
; #define PG8_STAGE(bufoff, gbase, voff) do { _Pragma("unroll") for (int _i = 0; _i < 2; ++_i) \
;         __builtin_amdgcn_global_load_lds((const unsigned*)((const char*)(gbase) + (voff)[_i]), (PG8_LAS unsigned*)(lds + (bufoff) + ldsw + _i * 8192), 16, 0, 0); } while (0)
; #define PG8_LDA(dst, b, h) do { _Pragma("unroll") for (int m = 0; m < 4; ++m) _Pragma("unroll") for (int k = 0; k < 2; ++k) dst[m][k] = *(const PG8_LAS bf16x8*)(lds + PG8_SA(b, h) + aoff + m * 2048 + k * 1024); } while (0)
; #define PG8_LDB(dst, b, h) do { _Pragma("unroll") for (int n = 0; n < 2; ++n) _Pragma("unroll") for (int k = 0; k < 2; ++k) dst[n][k] = *(const PG8_LAS bf16x8*)(lds + PG8_SB(b, h) + boff + n * 2048 + k * 1024); } while (0)
; #define PG8_MMA(ai, bj, At, Bt) do { __builtin_amdgcn_s_setprio(1); _Pragma("unroll") for (int m = 0; m < 4; ++m) _Pragma("unroll") for (int n = 0; n < 2; ++n) _Pragma("unroll") for (int k = 0; k < 2; ++k) \
;         acc[ai][bj][m][n] = __builtin_amdgcn_mfma_f32_16x16x32_bf16(Bt[n][k], At[m][k], acc[ai][bj][m][n], 0, 0, 0); __builtin_amdgcn_s_setprio(0); } while (0)
; #define PG8_WAIT_V(n) asm volatile("s_waitcnt vmcnt(" #n ")" ::: "memory")
; #define PG8_WAIT_L(n) asm volatile("s_waitcnt lgkmcnt(" #n ")" ::: "memory")
; #define PG8_BAR __builtin_amdgcn_s_barrier()
; #define PG8_SCHED __builtin_amdgcn_sched_barrier(0)
; template <class Epi, class Sched, bool ALIGN_EPI = false, bool SP2 = false>
; __device__ __forceinline__ void gemm_phase(PG8_LAS unsigned char* lds, const Gemm g, const Sched& S, const Epi& E) {
;     ...
;             PG8_WAIT_V(8); PG8_WAIT_L(0); PG8_BAR; PG8_MMA(1, 0, At, B0); PG8_MMA(1, 1, At, B1); PG8_BAR; PG8_SCHED;
;             PG8_LDB(B0, 1, 0); PG8_LDB(B1, 1, 1); PG8_SCHED; PG8_LDA(At, 1, 0); PG8_STAGE(PG8_SA(0, 1), a2 + hstep, voffA);
;             PG8_WAIT_V(8); PG8_WAIT_L(0); PG8_BAR; PG8_MMA(0, 0, At, B0); PG8_MMA(0, 1, At, B1); PG8_BAR; PG8_SCHED;
	v_mfma_f32_16x16x32_bf16 v[56:59], v[128:131], v[186:189], 0
	v_mfma_f32_16x16x32_bf16 v[60:63], v[136:139], v[186:189], 0
	v_mfma_f32_16x16x32_bf16 v[40:43], v[128:131], v[198:201], 0
	v_mfma_f32_16x16x32_bf16 v[44:47], v[136:139], v[198:201], 0
	v_mfma_f32_16x16x32_bf16 v[24:27], v[128:131], v[206:209], 0
	v_mfma_f32_16x16x32_bf16 v[28:31], v[136:139], v[206:209], 0
	v_mfma_f32_16x16x32_bf16 v[8:11], v[128:131], v[214:217], 0
	v_mfma_f32_16x16x32_bf16 v[12:15], v[136:139], v[214:217], 0
	v_mfma_f32_16x16x32_bf16 v[56:59], v[132:135], v[190:193], v[56:59]
	v_mfma_f32_16x16x32_bf16 v[60:63], v[140:143], v[190:193], v[60:63]
	v_mfma_f32_16x16x32_bf16 v[40:43], v[132:135], v[202:205], v[40:43]
	v_mfma_f32_16x16x32_bf16 v[44:47], v[140:143], v[202:205], v[44:47]
	v_mfma_f32_16x16x32_bf16 v[24:27], v[132:135], v[210:213], v[24:27]
	v_mfma_f32_16x16x32_bf16 v[28:31], v[140:143], v[210:213], v[28:31]
	v_mfma_f32_16x16x32_bf16 v[8:11], v[132:135], v[218:221], v[8:11]
	v_mfma_f32_16x16x32_bf16 v[12:15], v[140:143], v[218:221], v[12:15]
	v_mfma_f32_16x16x32_bf16 v[52:55], v[144:147], v[186:189], 0
	v_mfma_f32_16x16x32_bf16 v[48:51], v[168:171], v[186:189], 0
	v_mfma_f32_16x16x32_bf16 v[36:39], v[144:147], v[198:201], 0
	v_mfma_f32_16x16x32_bf16 v[32:35], v[168:171], v[198:201], 0
	v_mfma_f32_16x16x32_bf16 v[20:23], v[144:147], v[206:209], 0
	v_mfma_f32_16x16x32_bf16 v[16:19], v[168:171], v[206:209], 0
	v_mfma_f32_16x16x32_bf16 v[4:7], v[144:147], v[214:217], 0
	v_mfma_f32_16x16x32_bf16 v[0:3], v[168:171], v[214:217], 0
	v_mfma_f32_16x16x32_bf16 v[52:55], v[148:151], v[190:193], v[52:55]
	v_mfma_f32_16x16x32_bf16 v[48:51], v[172:175], v[190:193], v[48:51]
	v_mfma_f32_16x16x32_bf16 v[36:39], v[148:151], v[202:205], v[36:39]
	v_mfma_f32_16x16x32_bf16 v[32:35], v[172:175], v[202:205], v[32:35]
	v_mfma_f32_16x16x32_bf16 v[20:23], v[148:151], v[210:213], v[20:23]
	v_mfma_f32_16x16x32_bf16 v[16:19], v[172:175], v[210:213], v[16:19]
	v_mfma_f32_16x16x32_bf16 v[4:7], v[148:151], v[218:221], v[4:7]
	v_mfma_f32_16x16x32_bf16 v[0:3], v[172:175], v[218:221], v[0:3]
	s_barrier
	s_setprio 0
	s_add_i32 s50, 0, 0x18000
	s_add_i32 s51, 0, 0x1c000
	v_add_u32_e32 v140, s50, v179
	v_add_u32_e32 v172, s51, v179
	ds_read_b128 v[128:131], v140
	ds_read_b128 v[132:135], v140 offset:1024
	ds_read_b128 v[136:139], v140 offset:2048
	ds_read_b128 v[140:143], v140 offset:3072
	ds_read_b128 v[144:147], v172
	ds_read_b128 v[148:151], v172 offset:1024
	ds_read_b128 v[168:171], v172 offset:2048
	ds_read_b128 v[172:175], v172 offset:3072
	s_add_u32 s30, s30, 0x80000
	s_addc_u32 s31, s31, 0
	s_mov_b32 m0, s36
	v_lshl_add_u64 v[226:227], s[30:31], 0, v[152:153]
	ds_read_b128 v[186:189], v183 offset:32768
	ds_read_b128 v[190:193], v183 offset:33792
	ds_read_b128 v[198:201], v183 offset:34816
	ds_read_b128 v[202:205], v183 offset:35840
	ds_read_b128 v[206:209], v183 offset:36864
	ds_read_b128 v[210:213], v183 offset:37888
	ds_read_b128 v[214:217], v183 offset:38912
	ds_read_b128 v[218:221], v183 offset:39936
	global_load_lds_dwordx4 v[226:227], off
	v_lshl_add_u64 v[226:227], s[30:31], 0, v[156:157]
	s_mov_b32 m0, s37
	s_nop 0
	global_load_lds_dwordx4 v[226:227], off
	s_waitcnt vmcnt(8)
	s_waitcnt lgkmcnt(0)
	s_setprio 1
	s_barrier
	v_mfma_f32_16x16x32_bf16 v[124:127], v[128:131], v[186:189], v[124:127]
	v_mfma_f32_16x16x32_bf16 v[120:123], v[136:139], v[186:189], v[120:123]
	v_mfma_f32_16x16x32_bf16 v[104:107], v[128:131], v[198:201], v[104:107]
	v_mfma_f32_16x16x32_bf16 v[108:111], v[136:139], v[198:201], v[108:111]
	v_mfma_f32_16x16x32_bf16 v[88:91], v[128:131], v[206:209], v[88:91]
	v_mfma_f32_16x16x32_bf16 v[92:95], v[136:139], v[206:209], v[92:95]
	v_mfma_f32_16x16x32_bf16 v[72:75], v[128:131], v[214:217], v[72:75]
	v_mfma_f32_16x16x32_bf16 v[76:79], v[136:139], v[214:217], v[76:79]
	v_mfma_f32_16x16x32_bf16 v[124:127], v[132:135], v[190:193], v[124:127]
	v_mfma_f32_16x16x32_bf16 v[120:123], v[140:143], v[190:193], v[120:123]
	v_mfma_f32_16x16x32_bf16 v[104:107], v[132:135], v[202:205], v[104:107]
	v_mfma_f32_16x16x32_bf16 v[108:111], v[140:143], v[202:205], v[108:111]
	v_mfma_f32_16x16x32_bf16 v[88:91], v[132:135], v[210:213], v[88:91]
	v_mfma_f32_16x16x32_bf16 v[92:95], v[140:143], v[210:213], v[92:95]
	v_mfma_f32_16x16x32_bf16 v[72:75], v[132:135], v[218:221], v[72:75]
	v_mfma_f32_16x16x32_bf16 v[76:79], v[140:143], v[218:221], v[76:79]
	v_mfma_f32_16x16x32_bf16 v[116:119], v[144:147], v[186:189], v[116:119]
	v_mfma_f32_16x16x32_bf16 v[112:115], v[168:171], v[186:189], v[112:115]
	v_mfma_f32_16x16x32_bf16 v[100:103], v[144:147], v[198:201], v[100:103]
	v_mfma_f32_16x16x32_bf16 v[96:99], v[168:171], v[198:201], v[96:99]
	v_mfma_f32_16x16x32_bf16 v[84:87], v[144:147], v[206:209], v[84:87]
	v_mfma_f32_16x16x32_bf16 v[80:83], v[168:171], v[206:209], v[80:83]
	v_mfma_f32_16x16x32_bf16 v[68:71], v[144:147], v[214:217], v[68:71]
	v_mfma_f32_16x16x32_bf16 v[64:67], v[168:171], v[214:217], v[64:67]
	v_mfma_f32_16x16x32_bf16 v[116:119], v[148:151], v[190:193], v[116:119]
	v_mfma_f32_16x16x32_bf16 v[112:115], v[172:175], v[190:193], v[112:115]
	v_mfma_f32_16x16x32_bf16 v[100:103], v[148:151], v[202:205], v[100:103]
	v_mfma_f32_16x16x32_bf16 v[96:99], v[172:175], v[202:205], v[96:99]
	v_mfma_f32_16x16x32_bf16 v[84:87], v[148:151], v[210:213], v[84:87]
	v_mfma_f32_16x16x32_bf16 v[80:83], v[172:175], v[210:213], v[80:83]
	v_mfma_f32_16x16x32_bf16 v[68:71], v[148:151], v[218:221], v[68:71]
	v_mfma_f32_16x16x32_bf16 v[64:67], v[172:175], v[218:221], v[64:67]
	s_barrier
; #define PG8_STAGE(bufoff, gbase, voff) do { _Pragma("unroll") for (int _i = 0; _i < 2; ++_i) \
;         __builtin_amdgcn_global_load_lds((const unsigned*)((const char*)(gbase) + (voff)[_i]), (PG8_LAS unsigned*)(lds + (bufoff) + ldsw + _i * 8192), 16, 0, 0); } while (0)
; #define PG8_LDA(dst, b, h) do { _Pragma("unroll") for (int m = 0; m < 4; ++m) _Pragma("unroll") for (int k = 0; k < 2; ++k) dst[m][k] = *(const PG8_LAS bf16x8*)(lds + PG8_SA(b, h) + aoff + m * 2048 + k * 1024); } while (0)
; #define PG8_MMA(ai, bj, At, Bt) do { __builtin_amdgcn_s_setprio(1); _Pragma("unroll") for (int m = 0; m < 4; ++m) _Pragma("unroll") for (int n = 0; n < 2; ++n) _Pragma("unroll") for (int k = 0; k < 2; ++k) \
;         acc[ai][bj][m][n] = __builtin_amdgcn_mfma_f32_16x16x32_bf16(Bt[n][k], At[m][k], acc[ai][bj][m][n], 0, 0, 0); __builtin_amdgcn_s_setprio(0); } while (0)
; #define PG8_WAIT_V(n) asm volatile("s_waitcnt vmcnt(" #n ")" ::: "memory")
; #define PG8_WAIT_L(n) asm volatile("s_waitcnt lgkmcnt(" #n ")" ::: "memory")
; #define PG8_BAR __builtin_amdgcn_s_barrier()
; #define PG8_SCHED __builtin_amdgcn_sched_barrier(0)
; template <class Epi, class Sched, bool ALIGN_EPI = false, bool SP2 = false>
; __device__ __forceinline__ void gemm_phase(PG8_LAS unsigned char* lds, const Gemm g, const Sched& S, const Epi& E) {
;     ...
;         for (int t = 0; t < nt; t += 2) {
;             const bool last = (t == nt - 2);
;             const char* a1 = cA + (size_t)(t + 1) * kstep;
;             const char* a2 = last ? nA : cA + (size_t)(t + 2) * kstep; const char* b2 = last ? nB : cB + (size_t)(t + 2) * kstep;
;             const char* a3 = a2 + kstep; const char* b3 = b2 + kstep;
;     ...
;             PG8_LDA(At, 1, 1); PG8_STAGE(PG8_SB(1, 0), b3, voffB); PG8_STAGE(PG8_SB(1, 1), b3 + hstep, voffB); PG8_STAGE(PG8_SA(1, 0), a3, voffA);
;             PG8_WAIT_V(8); PG8_WAIT_L(0); PG8_BAR; PG8_MMA(1, 0, At, B0); PG8_MMA(1, 1, At, B1); PG8_BAR; PG8_SCHED;
	s_setprio 0
	s_add_i32 s30, s50, s34
	v_lshl_add_u64 v[176:177], v[176:177], 0, s[12:13]
	s_mov_b32 m0, s30
	ds_read_b128 v[186:189], v183 offset:49152
	ds_read_b128 v[190:193], v183 offset:50176
	ds_read_b128 v[198:201], v183 offset:51200
	ds_read_b128 v[202:205], v183 offset:52224
	ds_read_b128 v[206:209], v183 offset:53248
	ds_read_b128 v[210:213], v183 offset:54272
	ds_read_b128 v[214:217], v183 offset:55296
	ds_read_b128 v[218:221], v183 offset:56320
	global_load_lds_dwordx4 v[176:177], off
	s_add_i32 m0, s30, 0x2000
	s_add_u32 s28, s28, 0x80080
	v_lshl_add_u64 v[176:177], v[194:195], 0, s[12:13]
	s_addc_u32 s29, s29, 0
	s_add_i32 s30, s51, s34
	global_load_lds_dwordx4 v[176:177], off
	v_lshl_add_u64 v[176:177], s[28:29], 0, v[154:155]
	s_mov_b32 m0, s30
	s_nop 0
	global_load_lds_dwordx4 v[176:177], off
	v_lshl_add_u64 v[176:177], s[28:29], 0, v[158:159]
	s_add_i32 m0, s30, 0x2000
	s_nop 0
	global_load_lds_dwordx4 v[176:177], off
	v_lshl_add_u64 v[176:177], v[222:223], 0, s[12:13]
	s_mov_b32 m0, s39
	s_nop 0
	global_load_lds_dwordx4 v[176:177], off
	v_lshl_add_u64 v[176:177], v[224:225], 0, s[12:13]
	s_mov_b32 m0, s40
	s_nop 0
	global_load_lds_dwordx4 v[176:177], off
	s_waitcnt vmcnt(8)
	s_waitcnt lgkmcnt(0)
	s_setprio 1
	s_barrier
	v_mfma_f32_16x16x32_bf16 v[56:59], v[128:131], v[186:189], v[56:59]
	v_mfma_f32_16x16x32_bf16 v[60:63], v[136:139], v[186:189], v[60:63]
	v_mfma_f32_16x16x32_bf16 v[40:43], v[128:131], v[198:201], v[40:43]
	v_mfma_f32_16x16x32_bf16 v[44:47], v[136:139], v[198:201], v[44:47]
	v_mfma_f32_16x16x32_bf16 v[24:27], v[128:131], v[206:209], v[24:27]
	v_mfma_f32_16x16x32_bf16 v[28:31], v[136:139], v[206:209], v[28:31]
	v_mfma_f32_16x16x32_bf16 v[8:11], v[128:131], v[214:217], v[8:11]
	v_mfma_f32_16x16x32_bf16 v[12:15], v[136:139], v[214:217], v[12:15]
	v_mfma_f32_16x16x32_bf16 v[56:59], v[132:135], v[190:193], v[56:59]
	v_mfma_f32_16x16x32_bf16 v[60:63], v[140:143], v[190:193], v[60:63]
	v_mfma_f32_16x16x32_bf16 v[40:43], v[132:135], v[202:205], v[40:43]
	v_mfma_f32_16x16x32_bf16 v[44:47], v[140:143], v[202:205], v[44:47]
	v_mfma_f32_16x16x32_bf16 v[24:27], v[132:135], v[210:213], v[24:27]
	v_mfma_f32_16x16x32_bf16 v[28:31], v[140:143], v[210:213], v[28:31]
	v_mfma_f32_16x16x32_bf16 v[8:11], v[132:135], v[218:221], v[8:11]
	v_mfma_f32_16x16x32_bf16 v[12:15], v[140:143], v[218:221], v[12:15]
	v_mfma_f32_16x16x32_bf16 v[52:55], v[144:147], v[186:189], v[52:55]
	v_mfma_f32_16x16x32_bf16 v[48:51], v[168:171], v[186:189], v[48:51]
	v_mfma_f32_16x16x32_bf16 v[36:39], v[144:147], v[198:201], v[36:39]
	v_mfma_f32_16x16x32_bf16 v[32:35], v[168:171], v[198:201], v[32:35]
	v_mfma_f32_16x16x32_bf16 v[20:23], v[144:147], v[206:209], v[20:23]
	v_mfma_f32_16x16x32_bf16 v[16:19], v[168:171], v[206:209], v[16:19]
	v_mfma_f32_16x16x32_bf16 v[4:7], v[144:147], v[214:217], v[4:7]
	v_mfma_f32_16x16x32_bf16 v[0:3], v[168:171], v[214:217], v[0:3]
	v_mfma_f32_16x16x32_bf16 v[52:55], v[148:151], v[190:193], v[52:55]
	v_mfma_f32_16x16x32_bf16 v[48:51], v[172:175], v[190:193], v[48:51]
	v_mfma_f32_16x16x32_bf16 v[36:39], v[148:151], v[202:205], v[36:39]
	v_mfma_f32_16x16x32_bf16 v[32:35], v[172:175], v[202:205], v[32:35]
	v_mfma_f32_16x16x32_bf16 v[20:23], v[148:151], v[210:213], v[20:23]
	v_mfma_f32_16x16x32_bf16 v[16:19], v[172:175], v[210:213], v[16:19]
	v_mfma_f32_16x16x32_bf16 v[4:7], v[148:151], v[218:221], v[4:7]
	v_mfma_f32_16x16x32_bf16 v[0:3], v[172:175], v[218:221], v[0:3]
	s_barrier
	s_setprio 0
	s_add_i32 s49, s49, 2
	s_add_u32 s26, s26, 0x100
	s_addc_u32 s27, s27, 0
	s_add_u32 s47, s47, 0x100
	s_addc_u32 s48, s48, 0

; #define PG8_STAGE(bufoff, gbase, voff) do { _Pragma("unroll") for (int _i = 0; _i < 2; ++_i) \
;         __builtin_amdgcn_global_load_lds((const unsigned*)((const char*)(gbase) + (voff)[_i]), (PG8_LAS unsigned*)(lds + (bufoff) + ldsw + _i * 8192), 16, 0, 0); } while (0)
; #define PG8_WAIT_V(n) asm volatile("s_waitcnt vmcnt(" #n ")" ::: "memory")
; #define PG8_BAR __builtin_amdgcn_s_barrier()
; template <class Epi, class Sched, bool ALIGN_EPI = false, bool SP2 = false>
; __device__ __forceinline__ void gemm_phase(PG8_LAS unsigned char* lds, const Gemm g, const Sched& S, const Epi& E) {
;     const int tid = threadIdx.x, wid = __builtin_amdgcn_readfirstlane(tid >> 6), lane = tid & 63, wr = wid >> 2, wc = wid & 3, fr = lane & 15, fq = lane >> 4;
;     const int K = g.K, nt = K / BK;
;     unsigned voffA[2], voffB[2];
; #pragma unroll
;     for (int i = 0; i < 2; ++i) { int R, C; stage_rc(tid * 16 + i * 8192, R, C); const int Rb = Epi::PERM ? ((R & ~31) + perm32(R & 31)) : R;
;         voffA[i] = (unsigned)(R * K + C) * 2u; voffB[i] = (unsigned)(Rb * K + C) * 2u; }
;     const size_t kstep = (size_t)(BK * 2);
;     const size_t hstep = (size_t)HALF * K * 2;
;     const size_t tstep = 2 * hstep;
;     const unsigned ldsw = (unsigned)wid * 1024u;
;     const int aoff = lds_byte(wr * 64 + fr, fq * 8), boff = lds_byte(wc * 32 + fr, fq * 8);
;     ...
;         PG8_STAGE(PG8_SB(1, 0), cB + kstep, voffB); PG8_STAGE(PG8_SA(1, 0), cA + kstep, voffA); PG8_STAGE(PG8_SB(1, 1), cB + hstep + kstep, voffB);
;         PG8_WAIT_V(6); PG8_BAR;
.LBB0_1361:
	v_readlane_b32 s12, v254, 35
	v_readlane_b32 s18, v254, 41
	v_readlane_b32 s19, v254, 42
	s_mov_b64 s[62:63], s[18:19]
	v_readlane_b32 s13, v254, 36
	v_readlane_b32 s20, v254, 43
	v_readlane_b32 s21, v254, 44
	s_add_u32 s12, s62, 0x6000
	v_readlane_b32 s14, v254, 37
	v_readlane_b32 s16, v254, 39
	v_readlane_b32 s17, v254, 40
	s_mov_b64 s[64:65], s[20:21]
	s_addc_u32 s13, s63, 0
	v_readlane_b32 s15, v254, 38
	s_add_u32 s14, s64, 0x2000
	s_mov_b64 s[16:17], 0x80
	s_addc_u32 s15, s65, 0
	s_and_b32 s4, s2, 3
	s_add_i32 m0, s50, 0x18000
	v_lshl_add_u64 v[6:7], v[6:7], 0, s[16:17]
	s_lshl_b32 s5, s33, 13
	s_lshl_b32 s7, s4, 12
	s_waitcnt vmcnt(2)
	s_barrier
	global_load_lds_dwordx4 v[6:7], off
	v_lshl_add_u64 v[4:5], v[4:5], 0, s[16:17]
	s_add_i32 m0, s50, 0x1a000
	s_add_i32 s55, s50, 0x8000
	s_add_i32 s56, s50, 0xa000
	global_load_lds_dwordx4 v[4:5], off
	v_lshl_add_u64 v[0:1], v[0:1], 0, s[16:17]
	s_mov_b32 m0, s55
	s_add_u32 s2, s42, 0x80080
	global_load_lds_dwordx4 v[0:1], off
	v_lshl_add_u64 v[0:1], v[2:3], 0, s[16:17]
	s_mov_b32 m0, s56
	s_addc_u32 s3, s43, 0
	global_load_lds_dwordx4 v[0:1], off
	s_add_i32 m0, s50, 0x1c000
	v_lshl_add_u64 v[0:1], s[2:3], 0, v[144:145]
	global_load_lds_dwordx4 v[0:1], off
	v_lshl_add_u64 v[0:1], s[2:3], 0, v[146:147]
	s_add_i32 m0, s50, 0x1e000
	v_and_b32_e32 v2, 15, v196
	global_load_lds_dwordx4 v[0:1], off
	v_bfe_u32 v0, v196, 4, 2
	v_lshlrev_b32_e32 v1, 4, v0
	v_lshlrev_b32_e32 v4, 2, v196
	v_lshl_or_b32 v3, v2, 6, v1
	v_and_b32_e32 v4, 32, v4
	v_bitop3_b32 v5, v3, s5, v4 bitop3:0xde
	v_lshlrev_b32_e32 v3, 6, v196
	s_movk_i32 s2, 0x3c0
	v_and_or_b32 v1, v3, s2, v1
	v_lshlrev_b32_e32 v0, 2, v0
	v_bitop3_b32 v167, s7, v1, v4 bitop3:0xf6
	v_lshl_or_b32 v169, s4, 4, v0
	v_add_u32_e32 v0, -14, v2
	v_mov_b32_e32 v1, v145
	v_readlane_b32 s20, v254, 53
	v_lshlrev_b64 v[0:1], 12, v[0:1]
	v_readlane_b32 s21, v254, 54
	v_readlane_b32 s22, v254, 45
	v_readlane_b32 s23, v254, 46
	v_lshl_add_u64 v[152:153], s[20:21], 0, v[0:1]
	v_cvt_f32_u32_e32 v0, s46
	v_readlane_b32 s22, v254, 55
	v_readlane_b32 s24, v254, 47
	v_readlane_b32 s25, v254, 48
	v_rcp_iflag_f32_e32 v0, v0
	v_readlane_b32 s26, v254, 49
	v_readlane_b32 s27, v254, 50
	v_lshl_or_b32 v163, s33, 6, v2
	v_mul_f32_e32 v0, 0x4f7ffffe, v0
	s_cmpk_lt_u32 s6, 0x100
	v_cmp_eq_u32_e64 s[2:3], 0, v2
	v_cmp_gt_u32_e64 s[4:5], 2, v2
	v_cmp_lt_u32_e64 s[6:7], 13, v2
	v_lshlrev_b32_e32 v2, 12, v2
	v_mov_b32_e32 v3, v145
	v_readlane_b32 s23, v254, 56
	v_cvt_u32_f32_e32 v0, v0
	v_lshl_add_u64 v[148:149], s[20:21], 0, v[2:3]
	v_lshl_add_u64 v[150:151], s[22:23], 0, v[2:3]
	v_readlane_b32 s20, v254, 24
	s_cselect_b64 s[18:19], -1, 0
	s_ashr_i32 s57, s88, 31
	s_ashr_i32 s58, s89, 31
	v_readlane_b32 s26, v254, 30
	v_readlane_b32 s27, v254, 31
	v_readlane_b32 s21, v254, 25
	v_readlane_b32 s22, v254, 26
	s_cmp_lg_u64 s[26:27], 0
	v_readlane_b32 s23, v254, 27
	s_cselect_b64 s[20:21], -1, 0
	s_add_u32 s22, s62, 0x8000
	v_readfirstlane_b32 s27, v0
	v_lshlrev_b32_e32 v0, 9, v196
	v_readlane_b32 s24, v254, 28
	s_addc_u32 s23, s63, 0
	v_and_b32_e32 v0, 0x70000, v0
	v_lshlrev_b32_e32 v1, 12, v10
	v_readlane_b32 s25, v254, 29
	s_add_u32 s24, s62, 0xa000
	v_or3_b32 v0, v8, v0, v1
	s_addc_u32 s25, s63, 0
	s_sub_i32 s26, 0, s46
	v_add_u32_e32 v154, v0, v9
	v_lshlrev_b32_e32 v0, 5, v11
	s_waitcnt vmcnt(0)
	s_mul_i32 s26, s26, s27
	v_and_b32_e32 v0, 0xf0000, v0
	s_mul_hi_u32 s26, s27, s26
	v_or3_b32 v0, v8, v0, v1
	s_add_i32 s62, 0, 0x10000
	s_add_i32 s63, 0, 0x14000
	s_add_i32 s59, s27, s26
	v_mov_b32_e32 v155, v145
	s_waitcnt vmcnt(0)
	v_add_u32_e32 v156, v0, v9
	v_mov_b32_e32 v157, v145
	v_add_u32_e32 v173, s62, v167
	v_add_u32_e32 v175, s63, v167
	v_add_u32_e32 v177, 0, v5
	s_mov_b32 s64, 0x90000
	s_mov_b32 s65, 0xa0000
	v_mov_b64_e32 v[158:159], 0xfff
	s_barrier
	s_branch .LBB0_1364

; #define PG8_STAGE(bufoff, gbase, voff) do { _Pragma("unroll") for (int _i = 0; _i < 2; ++_i) \
;         __builtin_amdgcn_global_load_lds((const unsigned*)((const char*)(gbase) + (voff)[_i]), (PG8_LAS unsigned*)(lds + (bufoff) + ldsw + _i * 8192), 16, 0, 0); } while (0)
; #define PG8_LDA(dst, b, h) do { _Pragma("unroll") for (int m = 0; m < 4; ++m) _Pragma("unroll") for (int k = 0; k < 2; ++k) dst[m][k] = *(const PG8_LAS bf16x8*)(lds + PG8_SA(b, h) + aoff + m * 2048 + k * 1024); } while (0)
; #define PG8_LDB(dst, b, h) do { _Pragma("unroll") for (int n = 0; n < 2; ++n) _Pragma("unroll") for (int k = 0; k < 2; ++k) dst[n][k] = *(const PG8_LAS bf16x8*)(lds + PG8_SB(b, h) + boff + n * 2048 + k * 1024); } while (0)
; #define PG8_WAIT_V(n) asm volatile("s_waitcnt vmcnt(" #n ")" ::: "memory")
; #define PG8_WAIT_L(n) asm volatile("s_waitcnt lgkmcnt(" #n ")" ::: "memory")
; #define PG8_BAR __builtin_amdgcn_s_barrier()
; #define PG8_SCHED __builtin_amdgcn_sched_barrier(0)
; template <class Epi, class Sched, bool ALIGN_EPI = false, bool SP2 = false>
; __device__ __forceinline__ void gemm_phase(PG8_LAS unsigned char* lds, const Gemm g, const Sched& S, const Epi& E) {
;     ...
;         for (int t = 0; t < nt; t += 2) {
;             const bool last = (t == nt - 2);
;             const char* a1 = cA + (size_t)(t + 1) * kstep;
;             const char* a2 = last ? nA : cA + (size_t)(t + 2) * kstep; const char* b2 = last ? nB : cB + (size_t)(t + 2) * kstep;
;             const char* a3 = a2 + kstep; const char* b3 = b2 + kstep;
;             if (last && has_next) S.a_ready(nxt);
;             if constexpr (SP2) {
;             PG8_LDB(B0, 0, 0); PG8_LDB(B1, 0, 1); PG8_SCHED; PG8_LDA(At, 0, 0); PG8_STAGE(PG8_SA(1, 1), a1 + hstep, voffA);
;             PG8_WAIT_V(8); PG8_WAIT_L(0); PG8_BAR; PG8_MMA(0, 0, At, B0); PG8_MMA(0, 1, At, B1); PG8_BAR; PG8_SCHED;
;             PG8_LDA(At, 0, 1); PG8_STAGE(PG8_SB(0, 0), b2, voffB); PG8_STAGE(PG8_SB(0, 1), b2 + hstep, voffB); PG8_STAGE(PG8_SA(0, 0), a2, voffA);
;     ...
; #pragma unroll
;         for (int a = 0; a < 2; ++a)
; #pragma unroll
;             for (int b = 0; b < 2; ++b)
; #pragma unroll
;                 for (int m = 0; m < 4; ++m)
; #pragma unroll
;                     for (int n = 0; n < 2; ++n) acc[a][b][m][n] = (f32x4){0.f, 0.f, 0.f, 0.f};
.LBB0_1372:
	s_ashr_i32 s29, s28, 31
	s_lshl_b64 s[34:35], s[28:29], 20
	s_add_u32 s34, s74, s34
	s_addc_u32 s35, s75, s35
	s_and_b64 s[36:37], s[30:31], exec
	s_cselect_b32 s29, s35, s9
	s_cselect_b32 s39, s34, s8
	s_ashr_i32 s27, s26, 31
	s_lshl_b64 s[36:37], s[26:27], 20
	v_readlane_b32 s44, v254, 22
	v_readlane_b32 s45, v254, 23
	s_add_u32 s36, s44, s36
	s_addc_u32 s37, s45, s37
	s_and_b64 s[44:45], s[30:31], exec
	s_cselect_b32 s27, s37, s43
	s_cselect_b32 s41, s36, s42
	s_add_u32 s8, s8, 0x80080
	s_addc_u32 s9, s9, 0
	s_add_u32 s48, s42, 0x100
	s_addc_u32 s49, s43, 0
	s_mov_b32 s66, -2
	ds_read_b128 v[108:111], v173
	ds_read_b128 v[112:115], v173 offset:1024
	ds_read_b128 v[116:119], v173 offset:2048
	ds_read_b128 v[120:123], v173 offset:3072
	ds_read_b128 v[178:181], v175
	ds_read_b128 v[182:185], v175 offset:1024
	ds_read_b128 v[186:189], v175 offset:2048
	ds_read_b128 v[190:193], v175 offset:3072
	s_add_u32 s42, s8, 0xfff80080
	s_addc_u32 s43, s9, -1
	s_cmp_eq_u32 s66, 28
	s_cselect_b32 s45, s29, s43
	s_cselect_b32 s44, s39, s42
	s_cselect_b32 s43, s27, s49
	s_cselect_b32 s42, s41, s48
	v_lshl_add_u64 v[160:161], s[8:9], 0, v[154:155]
	s_add_i32 m0, s50, 0xc000
	ds_read_b128 v[198:201], v177
	ds_read_b128 v[202:205], v177 offset:1024
	ds_read_b128 v[206:209], v177 offset:2048
	ds_read_b128 v[210:213], v177 offset:3072
	ds_read_b128 v[214:217], v177 offset:4096
	ds_read_b128 v[218:221], v177 offset:5120
	ds_read_b128 v[222:225], v177 offset:6144
	ds_read_b128 v[226:229], v177 offset:7168
	global_load_lds_dwordx4 v[160:161], off
	v_lshl_add_u64 v[160:161], s[8:9], 0, v[156:157]
	s_add_i32 m0, s50, 0xe000
	s_nop 0
	global_load_lds_dwordx4 v[160:161], off
	s_nop 0
	s_waitcnt lgkmcnt(0)
	s_setprio 1
	s_barrier
	v_mfma_f32_16x16x32_bf16 v[140:143], v[108:111], v[198:201], 0
	v_mfma_f32_16x16x32_bf16 v[136:139], v[116:119], v[198:201], 0
	v_mfma_f32_16x16x32_bf16 v[100:103], v[108:111], v[206:209], 0
	v_mfma_f32_16x16x32_bf16 v[124:127], v[116:119], v[206:209], 0
	v_mfma_f32_16x16x32_bf16 v[84:87], v[108:111], v[214:217], 0
	v_mfma_f32_16x16x32_bf16 v[92:95], v[116:119], v[214:217], 0
	v_mfma_f32_16x16x32_bf16 v[68:71], v[108:111], v[222:225], 0
	v_mfma_f32_16x16x32_bf16 v[76:79], v[116:119], v[222:225], 0
	v_mfma_f32_16x16x32_bf16 v[140:143], v[112:115], v[202:205], v[140:143]
	v_mfma_f32_16x16x32_bf16 v[136:139], v[120:123], v[202:205], v[136:139]
	v_mfma_f32_16x16x32_bf16 v[100:103], v[112:115], v[210:213], v[100:103]
	v_mfma_f32_16x16x32_bf16 v[124:127], v[120:123], v[210:213], v[124:127]
	v_mfma_f32_16x16x32_bf16 v[84:87], v[112:115], v[218:221], v[84:87]
	v_mfma_f32_16x16x32_bf16 v[92:95], v[120:123], v[218:221], v[92:95]
	v_mfma_f32_16x16x32_bf16 v[68:71], v[112:115], v[226:229], v[68:71]
	v_mfma_f32_16x16x32_bf16 v[76:79], v[120:123], v[226:229], v[76:79]
	v_mfma_f32_16x16x32_bf16 v[128:131], v[178:181], v[198:201], 0
	v_mfma_f32_16x16x32_bf16 v[132:135], v[186:189], v[198:201], 0
	v_mfma_f32_16x16x32_bf16 v[104:107], v[178:181], v[206:209], 0
	v_mfma_f32_16x16x32_bf16 v[96:99], v[186:189], v[206:209], 0
	v_mfma_f32_16x16x32_bf16 v[88:91], v[178:181], v[214:217], 0
	v_mfma_f32_16x16x32_bf16 v[80:83], v[186:189], v[214:217], 0
	v_mfma_f32_16x16x32_bf16 v[72:75], v[178:181], v[222:225], 0
	v_mfma_f32_16x16x32_bf16 v[64:67], v[186:189], v[222:225], 0
	v_mfma_f32_16x16x32_bf16 v[128:131], v[182:185], v[202:205], v[128:131]
	v_mfma_f32_16x16x32_bf16 v[132:135], v[190:193], v[202:205], v[132:135]
	v_mfma_f32_16x16x32_bf16 v[104:107], v[182:185], v[210:213], v[104:107]
	v_mfma_f32_16x16x32_bf16 v[96:99], v[190:193], v[210:213], v[96:99]
	v_mfma_f32_16x16x32_bf16 v[88:91], v[182:185], v[218:221], v[88:91]
	v_mfma_f32_16x16x32_bf16 v[80:83], v[190:193], v[218:221], v[80:83]
	v_mfma_f32_16x16x32_bf16 v[72:75], v[182:185], v[226:229], v[72:75]
	v_mfma_f32_16x16x32_bf16 v[64:67], v[190:193], v[226:229], v[64:67]
	s_barrier
	s_setprio 0
	s_add_i32 s67, s62, s47
	v_lshl_add_u64 v[160:161], s[42:43], 0, v[144:145]
	s_mov_b32 m0, s67
	ds_read_b128 v[198:201], v177 offset:16384
	ds_read_b128 v[202:205], v177 offset:17408
	ds_read_b128 v[206:209], v177 offset:18432
	ds_read_b128 v[210:213], v177 offset:19456
	ds_read_b128 v[214:217], v177 offset:20480
	ds_read_b128 v[218:221], v177 offset:21504
	ds_read_b128 v[222:225], v177 offset:22528
	ds_read_b128 v[226:229], v177 offset:23552
	global_load_lds_dwordx4 v[160:161], off
	s_add_i32 m0, s67, 0x2000
	s_add_u32 s68, s42, 0x80000
	v_lshl_add_u64 v[164:165], s[42:43], 0, v[146:147]
	s_addc_u32 s69, s43, 0
	s_add_i32 s67, s63, s47
	global_load_lds_dwordx4 v[164:165], off
	v_lshl_add_u64 v[170:171], s[68:69], 0, v[144:145]
	s_mov_b32 m0, s67
	v_lshl_add_u64 v[194:195], s[44:45], 0, v[146:147]
	global_load_lds_dwordx4 v[170:171], off
	v_lshl_add_u64 v[170:171], s[68:69], 0, v[146:147]
	s_add_i32 m0, s67, 0x2000
	s_nop 0
	global_load_lds_dwordx4 v[170:171], off
	v_lshl_add_u64 v[170:171], s[44:45], 0, v[144:145]
	s_mov_b32 m0, s50
	s_nop 0
	global_load_lds_dwordx4 v[170:171], off
	s_mov_b32 m0, s51
	s_nop 0
	global_load_lds_dwordx4 v[194:195], off
	s_nop 0
	s_waitcnt lgkmcnt(0)
	s_setprio 1
	s_barrier
; #define PG8_STAGE(bufoff, gbase, voff) do { _Pragma("unroll") for (int _i = 0; _i < 2; ++_i) \
;         __builtin_amdgcn_global_load_lds((const unsigned*)((const char*)(gbase) + (voff)[_i]), (PG8_LAS unsigned*)(lds + (bufoff) + ldsw + _i * 8192), 16, 0, 0); } while (0)
; #define PG8_LDA(dst, b, h) do { _Pragma("unroll") for (int m = 0; m < 4; ++m) _Pragma("unroll") for (int k = 0; k < 2; ++k) dst[m][k] = *(const PG8_LAS bf16x8*)(lds + PG8_SA(b, h) + aoff + m * 2048 + k * 1024); } while (0)
; #define PG8_LDB(dst, b, h) do { _Pragma("unroll") for (int n = 0; n < 2; ++n) _Pragma("unroll") for (int k = 0; k < 2; ++k) dst[n][k] = *(const PG8_LAS bf16x8*)(lds + PG8_SB(b, h) + boff + n * 2048 + k * 1024); } while (0)
; #define PG8_MMA(ai, bj, At, Bt) do { __builtin_amdgcn_s_setprio(1); _Pragma("unroll") for (int m = 0; m < 4; ++m) _Pragma("unroll") for (int n = 0; n < 2; ++n) _Pragma("unroll") for (int k = 0; k < 2; ++k) \
;         acc[ai][bj][m][n] = __builtin_amdgcn_mfma_f32_16x16x32_bf16(Bt[n][k], At[m][k], acc[ai][bj][m][n], 0, 0, 0); __builtin_amdgcn_s_setprio(0); } while (0)
; #define PG8_WAIT_V(n) asm volatile("s_waitcnt vmcnt(" #n ")" ::: "memory")
; #define PG8_WAIT_L(n) asm volatile("s_waitcnt lgkmcnt(" #n ")" ::: "memory")
; #define PG8_BAR __builtin_amdgcn_s_barrier()
; #define PG8_SCHED __builtin_amdgcn_sched_barrier(0)
; template <class Epi, class Sched, bool ALIGN_EPI = false, bool SP2 = false>
; __device__ __forceinline__ void gemm_phase(PG8_LAS unsigned char* lds, const Gemm g, const Sched& S, const Epi& E) {
;     ...
;             PG8_WAIT_V(8); PG8_WAIT_L(0); PG8_BAR; PG8_MMA(1, 0, At, B0); PG8_MMA(1, 1, At, B1); PG8_BAR; PG8_SCHED;
;             PG8_LDB(B0, 1, 0); PG8_LDB(B1, 1, 1); PG8_SCHED; PG8_LDA(At, 1, 0); PG8_STAGE(PG8_SA(0, 1), a2 + hstep, voffA);
;             PG8_WAIT_V(8); PG8_WAIT_L(0); PG8_BAR; PG8_MMA(0, 0, At, B0); PG8_MMA(0, 1, At, B1); PG8_BAR; PG8_SCHED;
	v_mfma_f32_16x16x32_bf16 v[60:63], v[108:111], v[198:201], 0
	v_mfma_f32_16x16x32_bf16 v[56:59], v[116:119], v[198:201], 0
	v_mfma_f32_16x16x32_bf16 v[36:39], v[108:111], v[206:209], 0
	v_mfma_f32_16x16x32_bf16 v[44:47], v[116:119], v[206:209], 0
	v_mfma_f32_16x16x32_bf16 v[20:23], v[108:111], v[214:217], 0
	v_mfma_f32_16x16x32_bf16 v[28:31], v[116:119], v[214:217], 0
	v_mfma_f32_16x16x32_bf16 v[4:7], v[108:111], v[222:225], 0
	v_mfma_f32_16x16x32_bf16 v[12:15], v[116:119], v[222:225], 0
	v_mfma_f32_16x16x32_bf16 v[60:63], v[112:115], v[202:205], v[60:63]
	v_mfma_f32_16x16x32_bf16 v[56:59], v[120:123], v[202:205], v[56:59]
	v_mfma_f32_16x16x32_bf16 v[36:39], v[112:115], v[210:213], v[36:39]
	v_mfma_f32_16x16x32_bf16 v[44:47], v[120:123], v[210:213], v[44:47]
	v_mfma_f32_16x16x32_bf16 v[20:23], v[112:115], v[218:221], v[20:23]
	v_mfma_f32_16x16x32_bf16 v[28:31], v[120:123], v[218:221], v[28:31]
	v_mfma_f32_16x16x32_bf16 v[4:7], v[112:115], v[226:229], v[4:7]
	v_mfma_f32_16x16x32_bf16 v[12:15], v[120:123], v[226:229], v[12:15]
	v_mfma_f32_16x16x32_bf16 v[48:51], v[178:181], v[198:201], 0
	v_mfma_f32_16x16x32_bf16 v[52:55], v[186:189], v[198:201], 0
	v_mfma_f32_16x16x32_bf16 v[40:43], v[178:181], v[206:209], 0
	v_mfma_f32_16x16x32_bf16 v[32:35], v[186:189], v[206:209], 0
	v_mfma_f32_16x16x32_bf16 v[24:27], v[178:181], v[214:217], 0
	v_mfma_f32_16x16x32_bf16 v[16:19], v[186:189], v[214:217], 0
	v_mfma_f32_16x16x32_bf16 v[8:11], v[178:181], v[222:225], 0
	v_mfma_f32_16x16x32_bf16 v[0:3], v[186:189], v[222:225], 0
	v_mfma_f32_16x16x32_bf16 v[48:51], v[182:185], v[202:205], v[48:51]
	v_mfma_f32_16x16x32_bf16 v[52:55], v[190:193], v[202:205], v[52:55]
	v_mfma_f32_16x16x32_bf16 v[40:43], v[182:185], v[210:213], v[40:43]
	v_mfma_f32_16x16x32_bf16 v[32:35], v[190:193], v[210:213], v[32:35]
	v_mfma_f32_16x16x32_bf16 v[24:27], v[182:185], v[218:221], v[24:27]
	v_mfma_f32_16x16x32_bf16 v[16:19], v[190:193], v[218:221], v[16:19]
	v_mfma_f32_16x16x32_bf16 v[8:11], v[182:185], v[226:229], v[8:11]
	v_mfma_f32_16x16x32_bf16 v[0:3], v[190:193], v[226:229], v[0:3]
	s_barrier
	s_setprio 0
	s_add_i32 s67, 0, 0x18000
	s_add_i32 s68, 0, 0x1c000
	v_add_u32_e32 v120, s67, v167
	v_add_u32_e32 v162, s68, v167
	ds_read_b128 v[108:111], v120
	ds_read_b128 v[112:115], v120 offset:1024
	ds_read_b128 v[116:119], v120 offset:2048
	ds_read_b128 v[120:123], v120 offset:3072
	ds_read_b128 v[178:181], v162
	ds_read_b128 v[182:185], v162 offset:1024
	ds_read_b128 v[186:189], v162 offset:2048
	ds_read_b128 v[190:193], v162 offset:3072
	s_add_u32 s44, s44, 0x80000
	s_addc_u32 s45, s45, 0
	s_mov_b32 m0, s52
	v_lshl_add_u64 v[230:231], s[44:45], 0, v[144:145]
	ds_read_b128 v[198:201], v177 offset:32768
	ds_read_b128 v[202:205], v177 offset:33792
	ds_read_b128 v[206:209], v177 offset:34816
	ds_read_b128 v[210:213], v177 offset:35840
	ds_read_b128 v[214:217], v177 offset:36864
	ds_read_b128 v[218:221], v177 offset:37888
	ds_read_b128 v[222:225], v177 offset:38912
	ds_read_b128 v[226:229], v177 offset:39936
	global_load_lds_dwordx4 v[230:231], off
	v_lshl_add_u64 v[230:231], s[44:45], 0, v[146:147]
	s_mov_b32 m0, s53
	s_nop 0
	global_load_lds_dwordx4 v[230:231], off
	s_waitcnt vmcnt(8)
	s_waitcnt lgkmcnt(0)
	s_setprio 1
	s_barrier
	v_mfma_f32_16x16x32_bf16 v[140:143], v[108:111], v[198:201], v[140:143]
	v_mfma_f32_16x16x32_bf16 v[136:139], v[116:119], v[198:201], v[136:139]
	v_mfma_f32_16x16x32_bf16 v[100:103], v[108:111], v[206:209], v[100:103]
	v_mfma_f32_16x16x32_bf16 v[124:127], v[116:119], v[206:209], v[124:127]
	v_mfma_f32_16x16x32_bf16 v[84:87], v[108:111], v[214:217], v[84:87]
	v_mfma_f32_16x16x32_bf16 v[92:95], v[116:119], v[214:217], v[92:95]
	v_mfma_f32_16x16x32_bf16 v[68:71], v[108:111], v[222:225], v[68:71]
	v_mfma_f32_16x16x32_bf16 v[76:79], v[116:119], v[222:225], v[76:79]
	v_mfma_f32_16x16x32_bf16 v[140:143], v[112:115], v[202:205], v[140:143]
	v_mfma_f32_16x16x32_bf16 v[136:139], v[120:123], v[202:205], v[136:139]
	v_mfma_f32_16x16x32_bf16 v[100:103], v[112:115], v[210:213], v[100:103]
	v_mfma_f32_16x16x32_bf16 v[124:127], v[120:123], v[210:213], v[124:127]
	v_mfma_f32_16x16x32_bf16 v[84:87], v[112:115], v[218:221], v[84:87]
	v_mfma_f32_16x16x32_bf16 v[92:95], v[120:123], v[218:221], v[92:95]
	v_mfma_f32_16x16x32_bf16 v[68:71], v[112:115], v[226:229], v[68:71]
	v_mfma_f32_16x16x32_bf16 v[76:79], v[120:123], v[226:229], v[76:79]
	v_mfma_f32_16x16x32_bf16 v[128:131], v[178:181], v[198:201], v[128:131]
	v_mfma_f32_16x16x32_bf16 v[132:135], v[186:189], v[198:201], v[132:135]
	v_mfma_f32_16x16x32_bf16 v[104:107], v[178:181], v[206:209], v[104:107]
	v_mfma_f32_16x16x32_bf16 v[96:99], v[186:189], v[206:209], v[96:99]
	v_mfma_f32_16x16x32_bf16 v[88:91], v[178:181], v[214:217], v[88:91]
	v_mfma_f32_16x16x32_bf16 v[80:83], v[186:189], v[214:217], v[80:83]
	v_mfma_f32_16x16x32_bf16 v[72:75], v[178:181], v[222:225], v[72:75]
	v_mfma_f32_16x16x32_bf16 v[64:67], v[186:189], v[222:225], v[64:67]
	v_mfma_f32_16x16x32_bf16 v[128:131], v[182:185], v[202:205], v[128:131]
	v_mfma_f32_16x16x32_bf16 v[132:135], v[190:193], v[202:205], v[132:135]
	v_mfma_f32_16x16x32_bf16 v[104:107], v[182:185], v[210:213], v[104:107]
	v_mfma_f32_16x16x32_bf16 v[96:99], v[190:193], v[210:213], v[96:99]
	v_mfma_f32_16x16x32_bf16 v[88:91], v[182:185], v[218:221], v[88:91]
	v_mfma_f32_16x16x32_bf16 v[80:83], v[190:193], v[218:221], v[80:83]
	v_mfma_f32_16x16x32_bf16 v[72:75], v[182:185], v[226:229], v[72:75]
	v_mfma_f32_16x16x32_bf16 v[64:67], v[190:193], v[226:229], v[64:67]
	s_barrier
; #define PG8_STAGE(bufoff, gbase, voff) do { _Pragma("unroll") for (int _i = 0; _i < 2; ++_i) \
;         __builtin_amdgcn_global_load_lds((const unsigned*)((const char*)(gbase) + (voff)[_i]), (PG8_LAS unsigned*)(lds + (bufoff) + ldsw + _i * 8192), 16, 0, 0); } while (0)
; #define PG8_LDA(dst, b, h) do { _Pragma("unroll") for (int m = 0; m < 4; ++m) _Pragma("unroll") for (int k = 0; k < 2; ++k) dst[m][k] = *(const PG8_LAS bf16x8*)(lds + PG8_SA(b, h) + aoff + m * 2048 + k * 1024); } while (0)
; #define PG8_MMA(ai, bj, At, Bt) do { __builtin_amdgcn_s_setprio(1); _Pragma("unroll") for (int m = 0; m < 4; ++m) _Pragma("unroll") for (int n = 0; n < 2; ++n) _Pragma("unroll") for (int k = 0; k < 2; ++k) \
;         acc[ai][bj][m][n] = __builtin_amdgcn_mfma_f32_16x16x32_bf16(Bt[n][k], At[m][k], acc[ai][bj][m][n], 0, 0, 0); __builtin_amdgcn_s_setprio(0); } while (0)
; #define PG8_WAIT_V(n) asm volatile("s_waitcnt vmcnt(" #n ")" ::: "memory")
; #define PG8_WAIT_L(n) asm volatile("s_waitcnt lgkmcnt(" #n ")" ::: "memory")
; #define PG8_BAR __builtin_amdgcn_s_barrier()
; #define PG8_SCHED __builtin_amdgcn_sched_barrier(0)
; template <class Epi, class Sched, bool ALIGN_EPI = false, bool SP2 = false>
; __device__ __forceinline__ void gemm_phase(PG8_LAS unsigned char* lds, const Gemm g, const Sched& S, const Epi& E) {
;     ...
;             PG8_LDA(At, 1, 1); PG8_STAGE(PG8_SB(1, 0), b3, voffB); PG8_STAGE(PG8_SB(1, 1), b3 + hstep, voffB); PG8_STAGE(PG8_SA(1, 0), a3, voffA);
;             PG8_WAIT_V(8); PG8_WAIT_L(0); PG8_BAR; PG8_MMA(1, 0, At, B0); PG8_MMA(1, 1, At, B1); PG8_BAR; PG8_SCHED;
	s_setprio 0
	s_add_i32 s44, s67, s47
	v_lshl_add_u64 v[160:161], v[160:161], 0, s[16:17]
	s_mov_b32 m0, s44
	ds_read_b128 v[198:201], v177 offset:49152
	ds_read_b128 v[202:205], v177 offset:50176
	ds_read_b128 v[206:209], v177 offset:51200
	ds_read_b128 v[210:213], v177 offset:52224
	ds_read_b128 v[214:217], v177 offset:53248
	ds_read_b128 v[218:221], v177 offset:54272
	ds_read_b128 v[222:225], v177 offset:55296
	ds_read_b128 v[226:229], v177 offset:56320
	global_load_lds_dwordx4 v[160:161], off
	s_add_i32 m0, s44, 0x2000
	s_add_u32 s42, s42, 0x80080
	v_lshl_add_u64 v[160:161], v[164:165], 0, s[16:17]
	s_addc_u32 s43, s43, 0
	s_add_i32 s44, s68, s47
	global_load_lds_dwordx4 v[160:161], off
	v_lshl_add_u64 v[160:161], s[42:43], 0, v[144:145]
	s_mov_b32 m0, s44
	s_nop 0
	global_load_lds_dwordx4 v[160:161], off
	v_lshl_add_u64 v[160:161], s[42:43], 0, v[146:147]
	s_add_i32 m0, s44, 0x2000
	s_nop 0
	global_load_lds_dwordx4 v[160:161], off
	v_lshl_add_u64 v[160:161], v[170:171], 0, s[16:17]
	s_mov_b32 m0, s55
	s_nop 0
	global_load_lds_dwordx4 v[160:161], off
	v_lshl_add_u64 v[160:161], v[194:195], 0, s[16:17]
	s_mov_b32 m0, s56
	s_nop 0
	global_load_lds_dwordx4 v[160:161], off
	s_waitcnt vmcnt(8)
	s_waitcnt lgkmcnt(0)
	s_setprio 1
	s_barrier
	v_mfma_f32_16x16x32_bf16 v[60:63], v[108:111], v[198:201], v[60:63]
	v_mfma_f32_16x16x32_bf16 v[56:59], v[116:119], v[198:201], v[56:59]
	v_mfma_f32_16x16x32_bf16 v[36:39], v[108:111], v[206:209], v[36:39]
	v_mfma_f32_16x16x32_bf16 v[44:47], v[116:119], v[206:209], v[44:47]
	v_mfma_f32_16x16x32_bf16 v[20:23], v[108:111], v[214:217], v[20:23]
	v_mfma_f32_16x16x32_bf16 v[28:31], v[116:119], v[214:217], v[28:31]
	v_mfma_f32_16x16x32_bf16 v[4:7], v[108:111], v[222:225], v[4:7]
	v_mfma_f32_16x16x32_bf16 v[12:15], v[116:119], v[222:225], v[12:15]
	v_mfma_f32_16x16x32_bf16 v[60:63], v[112:115], v[202:205], v[60:63]
	v_mfma_f32_16x16x32_bf16 v[56:59], v[120:123], v[202:205], v[56:59]
	v_mfma_f32_16x16x32_bf16 v[36:39], v[112:115], v[210:213], v[36:39]
	v_mfma_f32_16x16x32_bf16 v[44:47], v[120:123], v[210:213], v[44:47]
	v_mfma_f32_16x16x32_bf16 v[20:23], v[112:115], v[218:221], v[20:23]
	v_mfma_f32_16x16x32_bf16 v[28:31], v[120:123], v[218:221], v[28:31]
	v_mfma_f32_16x16x32_bf16 v[4:7], v[112:115], v[226:229], v[4:7]
	v_mfma_f32_16x16x32_bf16 v[12:15], v[120:123], v[226:229], v[12:15]
	v_mfma_f32_16x16x32_bf16 v[48:51], v[178:181], v[198:201], v[48:51]
	v_mfma_f32_16x16x32_bf16 v[52:55], v[186:189], v[198:201], v[52:55]
	v_mfma_f32_16x16x32_bf16 v[40:43], v[178:181], v[206:209], v[40:43]
	v_mfma_f32_16x16x32_bf16 v[32:35], v[186:189], v[206:209], v[32:35]
	v_mfma_f32_16x16x32_bf16 v[24:27], v[178:181], v[214:217], v[24:27]
	v_mfma_f32_16x16x32_bf16 v[16:19], v[186:189], v[214:217], v[16:19]
	v_mfma_f32_16x16x32_bf16 v[8:11], v[178:181], v[222:225], v[8:11]
	v_mfma_f32_16x16x32_bf16 v[0:3], v[186:189], v[222:225], v[0:3]
	v_mfma_f32_16x16x32_bf16 v[48:51], v[182:185], v[202:205], v[48:51]
	v_mfma_f32_16x16x32_bf16 v[52:55], v[190:193], v[202:205], v[52:55]
	v_mfma_f32_16x16x32_bf16 v[40:43], v[182:185], v[210:213], v[40:43]
	v_mfma_f32_16x16x32_bf16 v[32:35], v[190:193], v[210:213], v[32:35]
	v_mfma_f32_16x16x32_bf16 v[24:27], v[182:185], v[218:221], v[24:27]
	v_mfma_f32_16x16x32_bf16 v[16:19], v[190:193], v[218:221], v[16:19]
	v_mfma_f32_16x16x32_bf16 v[8:11], v[182:185], v[226:229], v[8:11]
	v_mfma_f32_16x16x32_bf16 v[0:3], v[190:193], v[226:229], v[0:3]
	s_barrier
	s_setprio 0
	s_add_i32 s66, s66, 2
	s_add_u32 s8, s8, 0x100
	s_addc_u32 s9, s9, 0
	s_add_u32 s48, s48, 0x100
	s_addc_u32 s49, s49, 0

; #define PG8_STAGE(bufoff, gbase, voff) do { _Pragma("unroll") for (int _i = 0; _i < 2; ++_i) \
;         __builtin_amdgcn_global_load_lds((const unsigned*)((const char*)(gbase) + (voff)[_i]), (PG8_LAS unsigned*)(lds + (bufoff) + ldsw + _i * 8192), 16, 0, 0); } while (0)
; #define PG8_WAIT_V(n) asm volatile("s_waitcnt vmcnt(" #n ")" ::: "memory")
; #define PG8_BAR __builtin_amdgcn_s_barrier()
; template <class Epi, class Sched, bool ALIGN_EPI = false, bool SP2 = false>
; __device__ __forceinline__ void gemm_phase(PG8_LAS unsigned char* lds, const Gemm g, const Sched& S, const Epi& E) {
;     const int tid = threadIdx.x, wid = __builtin_amdgcn_readfirstlane(tid >> 6), lane = tid & 63, wr = wid >> 2, wc = wid & 3, fr = lane & 15, fq = lane >> 4;
;     const int K = g.K, nt = K / BK;
;     unsigned voffA[2], voffB[2];
; #pragma unroll
;     for (int i = 0; i < 2; ++i) { int R, C; stage_rc(tid * 16 + i * 8192, R, C); const int Rb = Epi::PERM ? ((R & ~31) + perm32(R & 31)) : R;
;         voffA[i] = (unsigned)(R * K + C) * 2u; voffB[i] = (unsigned)(Rb * K + C) * 2u; }
;     const size_t kstep = (size_t)(BK * 2);
;     const size_t hstep = (size_t)HALF * K * 2;
;     const size_t tstep = 2 * hstep;
;     const unsigned ldsw = (unsigned)wid * 1024u;
;     const int aoff = lds_byte(wr * 64 + fr, fq * 8), boff = lds_byte(wc * 32 + fr, fq * 8);
;     ...
;         PG8_STAGE(PG8_SB(1, 0), cB + kstep, voffB); PG8_STAGE(PG8_SA(1, 0), cA + kstep, voffA); PG8_STAGE(PG8_SB(1, 1), cB + hstep + kstep, voffB);
;         PG8_WAIT_V(6); PG8_BAR;
.LBB0_1539:
	s_and_b32 s7, s4, 3
	s_mov_b64 s[4:5], 0x80
	s_add_i32 m0, s19, 0x18000
	v_lshl_add_u64 v[6:7], v[6:7], 0, s[4:5]
	s_lshl_b32 s10, s1, 13
	s_lshl_b32 s11, s7, 12
	s_waitcnt vmcnt(2)
	s_barrier
	global_load_lds_dwordx4 v[6:7], off
	v_lshl_add_u64 v[4:5], v[4:5], 0, s[4:5]
	s_add_i32 m0, s19, 0x1a000
	s_add_i32 s33, s19, 0x8000
	s_add_i32 s34, s19, 0xa000
	global_load_lds_dwordx4 v[4:5], off
	v_lshl_add_u64 v[0:1], v[0:1], 0, s[4:5]
	s_mov_b32 m0, s33
	s_add_u32 s8, s22, 0x80080
	global_load_lds_dwordx4 v[0:1], off
	v_lshl_add_u64 v[0:1], v[2:3], 0, s[4:5]
	s_mov_b32 m0, s34
	s_addc_u32 s9, s23, 0
	global_load_lds_dwordx4 v[0:1], off
	s_add_i32 m0, s19, 0x1c000
	v_lshl_add_u64 v[0:1], s[8:9], 0, v[130:131]
	global_load_lds_dwordx4 v[0:1], off
	v_lshl_add_u64 v[0:1], s[8:9], 0, v[134:135]
	s_add_i32 m0, s19, 0x1e000
	s_sext_i32_i8 s38, s0
	global_load_lds_dwordx4 v[0:1], off
	v_bfe_u32 v0, v196, 4, 2
	v_and_b32_e32 v1, 15, v196
	v_lshlrev_b32_e32 v2, 3, v0
	v_lshlrev_b32_e32 v0, 4, v0
	v_lshlrev_b32_e32 v3, 2, v196
	v_lshlrev_b32_e32 v4, 6, v196
	s_movk_i32 s0, 0x3c0
	v_lshl_or_b32 v152, s1, 6, v1
	v_lshl_or_b32 v1, v1, 6, v0
	v_and_b32_e32 v3, 32, v3
	v_and_or_b32 v0, v4, s0, v0
	v_bitop3_b32 v153, s11, v0, v3 bitop3:0xf6
	v_lshlrev_b32_e32 v0, 9, v196
	v_lshl_or_b32 v154, s7, 5, v2
	v_and_b32_e32 v0, 0x70000, v0
	v_lshlrev_b32_e32 v2, 12, v10
	s_cmpk_lt_u32 s6, 0x100
	v_or3_b32 v0, v8, v0, v2
	s_cselect_b64 s[6:7], -1, 0
	s_ashr_i32 s35, s88, 31
	v_add_u32_e32 v136, v0, v9
	v_lshlrev_b32_e32 v0, 5, v11
	s_waitcnt vmcnt(0)
	s_cmp_lg_u64 s[48:49], 0
	v_and_b32_e32 v0, 0xf0000, v0
	v_bitop3_b32 v1, v1, s10, v3 bitop3:0xde
	s_cselect_b64 s[8:9], -1, 0
	v_or3_b32 v0, v8, v0, v2
	s_add_i32 s36, 0, 0x10000
	s_add_i32 s37, 0, 0x14000
	v_mov_b32_e32 v137, v131
	v_add_u32_e32 v138, v0, v9
	v_mov_b32_e32 v139, v131
	v_mov_b64_e32 v[140:141], 0x400
	v_mov_b64_e32 v[142:143], 0x3ff
	v_add_u32_e32 v155, s36, v153
	v_add_u32_e32 v156, s37, v153
	v_add_u32_e32 v157, 0, v1
	s_barrier
	s_branch .LBB0_1542

; #define PG8_STAGE(bufoff, gbase, voff) do { _Pragma("unroll") for (int _i = 0; _i < 2; ++_i) \
;         __builtin_amdgcn_global_load_lds((const unsigned*)((const char*)(gbase) + (voff)[_i]), (PG8_LAS unsigned*)(lds + (bufoff) + ldsw + _i * 8192), 16, 0, 0); } while (0)
; #define PG8_LDA(dst, b, h) do { _Pragma("unroll") for (int m = 0; m < 4; ++m) _Pragma("unroll") for (int k = 0; k < 2; ++k) dst[m][k] = *(const PG8_LAS bf16x8*)(lds + PG8_SA(b, h) + aoff + m * 2048 + k * 1024); } while (0)
; #define PG8_LDB(dst, b, h) do { _Pragma("unroll") for (int n = 0; n < 2; ++n) _Pragma("unroll") for (int k = 0; k < 2; ++k) dst[n][k] = *(const PG8_LAS bf16x8*)(lds + PG8_SB(b, h) + boff + n * 2048 + k * 1024); } while (0)
; #define PG8_WAIT_V(n) asm volatile("s_waitcnt vmcnt(" #n ")" ::: "memory")
; #define PG8_WAIT_L(n) asm volatile("s_waitcnt lgkmcnt(" #n ")" ::: "memory")
; #define PG8_BAR __builtin_amdgcn_s_barrier()
; #define PG8_SCHED __builtin_amdgcn_sched_barrier(0)
; template <class Epi, class Sched, bool ALIGN_EPI = false, bool SP2 = false>
; __device__ __forceinline__ void gemm_phase(PG8_LAS unsigned char* lds, const Gemm g, const Sched& S, const Epi& E) {
;     ...
;         for (int t = 0; t < nt; t += 2) {
;             const bool last = (t == nt - 2);
;             const char* a1 = cA + (size_t)(t + 1) * kstep;
;             const char* a2 = last ? nA : cA + (size_t)(t + 2) * kstep; const char* b2 = last ? nB : cB + (size_t)(t + 2) * kstep;
;             const char* a3 = a2 + kstep; const char* b3 = b2 + kstep;
;             if (last && has_next) S.a_ready(nxt);
;             if constexpr (SP2) {
;             PG8_LDB(B0, 0, 0); PG8_LDB(B1, 0, 1); PG8_SCHED; PG8_LDA(At, 0, 0); PG8_STAGE(PG8_SA(1, 1), a1 + hstep, voffA);
;             PG8_WAIT_V(8); PG8_WAIT_L(0); PG8_BAR; PG8_MMA(0, 0, At, B0); PG8_MMA(0, 1, At, B1); PG8_BAR; PG8_SCHED;
;             PG8_LDA(At, 0, 1); PG8_STAGE(PG8_SB(0, 0), b2, voffB); PG8_STAGE(PG8_SB(0, 1), b2 + hstep, voffB); PG8_STAGE(PG8_SA(0, 0), a2, voffA);
;     ...
; #pragma unroll
;         for (int a = 0; a < 2; ++a)
; #pragma unroll
;             for (int b = 0; b < 2; ++b)
; #pragma unroll
;                 for (int m = 0; m < 4; ++m)
; #pragma unroll
;                     for (int n = 0; n < 2; ++n) acc[a][b][m][n] = (f32x4){0.f, 0.f, 0.f, 0.f};
.LBB0_1548:
	s_ashr_i32 s13, s12, 31
	s_lshl_b64 s[14:15], s[12:13], 20
	s_add_u32 s14, s60, s14
	s_addc_u32 s15, s61, s15
	s_and_b64 s[16:17], s[0:1], exec
	s_cselect_b32 s13, s15, s21
	s_cselect_b32 s39, s14, s20
	s_ashr_i32 s11, s10, 31
	s_lshl_b64 s[16:17], s[10:11], 20
	s_add_u32 s16, s72, s16
	s_addc_u32 s17, s73, s17
	s_and_b64 s[24:25], s[0:1], exec
	s_cselect_b32 s11, s17, s23
	s_cselect_b32 s40, s16, s22
	s_add_u32 s20, s20, 0x80080
	s_addc_u32 s21, s21, 0
	s_add_u32 s41, s22, 0x100
	s_addc_u32 s42, s23, 0
	s_mov_b32 s43, -2
	ds_read_b128 v[144:147], v155
	ds_read_b128 v[148:151], v155 offset:1024
	ds_read_b128 v[158:161], v155 offset:2048
	ds_read_b128 v[162:165], v155 offset:3072
	ds_read_b128 v[166:169], v156
	ds_read_b128 v[170:173], v156 offset:1024
	ds_read_b128 v[174:177], v156 offset:2048
	ds_read_b128 v[178:181], v156 offset:3072
	s_add_u32 s22, s20, 0xfff80080
	s_addc_u32 s23, s21, -1
	s_cmp_eq_u32 s43, 28
	s_cselect_b32 s25, s13, s23
	s_cselect_b32 s24, s39, s22
	s_cselect_b32 s23, s11, s42
	s_cselect_b32 s22, s40, s41
	v_lshl_add_u64 v[214:215], s[20:21], 0, v[136:137]
	s_add_i32 m0, s19, 0xc000
	ds_read_b128 v[182:185], v157
	ds_read_b128 v[186:189], v157 offset:1024
	ds_read_b128 v[190:193], v157 offset:2048
	ds_read_b128 v[194:197], v157 offset:3072
	ds_read_b128 v[198:201], v157 offset:4096
	ds_read_b128 v[202:205], v157 offset:5120
	ds_read_b128 v[206:209], v157 offset:6144
	ds_read_b128 v[210:213], v157 offset:7168
	global_load_lds_dwordx4 v[214:215], off
	v_lshl_add_u64 v[214:215], s[20:21], 0, v[138:139]
	s_add_i32 m0, s19, 0xe000
	s_nop 0
	global_load_lds_dwordx4 v[214:215], off
	s_nop 0
	s_waitcnt lgkmcnt(0)
	s_setprio 1
	s_barrier
	v_mfma_f32_16x16x32_bf16 v[124:127], v[144:147], v[182:185], 0
	v_mfma_f32_16x16x32_bf16 v[120:123], v[158:161], v[182:185], 0
	v_mfma_f32_16x16x32_bf16 v[108:111], v[144:147], v[190:193], 0
	v_mfma_f32_16x16x32_bf16 v[104:107], v[158:161], v[190:193], 0
	v_mfma_f32_16x16x32_bf16 v[88:91], v[144:147], v[198:201], 0
	v_mfma_f32_16x16x32_bf16 v[92:95], v[158:161], v[198:201], 0
	v_mfma_f32_16x16x32_bf16 v[72:75], v[144:147], v[206:209], 0
	v_mfma_f32_16x16x32_bf16 v[76:79], v[158:161], v[206:209], 0
	v_mfma_f32_16x16x32_bf16 v[124:127], v[148:151], v[186:189], v[124:127]
	v_mfma_f32_16x16x32_bf16 v[120:123], v[162:165], v[186:189], v[120:123]
	v_mfma_f32_16x16x32_bf16 v[108:111], v[148:151], v[194:197], v[108:111]
	v_mfma_f32_16x16x32_bf16 v[104:107], v[162:165], v[194:197], v[104:107]
	v_mfma_f32_16x16x32_bf16 v[88:91], v[148:151], v[202:205], v[88:91]
	v_mfma_f32_16x16x32_bf16 v[92:95], v[162:165], v[202:205], v[92:95]
	v_mfma_f32_16x16x32_bf16 v[72:75], v[148:151], v[210:213], v[72:75]
	v_mfma_f32_16x16x32_bf16 v[76:79], v[162:165], v[210:213], v[76:79]
	v_mfma_f32_16x16x32_bf16 v[116:119], v[166:169], v[182:185], 0
	v_mfma_f32_16x16x32_bf16 v[112:115], v[174:177], v[182:185], 0
	v_mfma_f32_16x16x32_bf16 v[96:99], v[166:169], v[190:193], 0
	v_mfma_f32_16x16x32_bf16 v[100:103], v[174:177], v[190:193], 0
	v_mfma_f32_16x16x32_bf16 v[80:83], v[166:169], v[198:201], 0
	v_mfma_f32_16x16x32_bf16 v[84:87], v[174:177], v[198:201], 0
	v_mfma_f32_16x16x32_bf16 v[64:67], v[166:169], v[206:209], 0
	v_mfma_f32_16x16x32_bf16 v[68:71], v[174:177], v[206:209], 0
	v_mfma_f32_16x16x32_bf16 v[116:119], v[170:173], v[186:189], v[116:119]
	v_mfma_f32_16x16x32_bf16 v[112:115], v[178:181], v[186:189], v[112:115]
	v_mfma_f32_16x16x32_bf16 v[96:99], v[170:173], v[194:197], v[96:99]
	v_mfma_f32_16x16x32_bf16 v[100:103], v[178:181], v[194:197], v[100:103]
	v_mfma_f32_16x16x32_bf16 v[80:83], v[170:173], v[202:205], v[80:83]
	v_mfma_f32_16x16x32_bf16 v[84:87], v[178:181], v[202:205], v[84:87]
	v_mfma_f32_16x16x32_bf16 v[64:67], v[170:173], v[210:213], v[64:67]
	v_mfma_f32_16x16x32_bf16 v[68:71], v[178:181], v[210:213], v[68:71]
	s_barrier
	s_setprio 0
	s_add_i32 s44, s36, s27
	v_lshl_add_u64 v[214:215], s[22:23], 0, v[130:131]
	s_mov_b32 m0, s44
	ds_read_b128 v[182:185], v157 offset:16384
	ds_read_b128 v[186:189], v157 offset:17408
	ds_read_b128 v[190:193], v157 offset:18432
	ds_read_b128 v[194:197], v157 offset:19456
	ds_read_b128 v[198:201], v157 offset:20480
	ds_read_b128 v[202:205], v157 offset:21504
	ds_read_b128 v[206:209], v157 offset:22528
	ds_read_b128 v[210:213], v157 offset:23552
	global_load_lds_dwordx4 v[214:215], off
	s_add_i32 m0, s44, 0x2000
	s_add_u32 s44, s22, 0x80000
	v_lshl_add_u64 v[216:217], s[22:23], 0, v[134:135]
	s_addc_u32 s45, s23, 0
	s_add_i32 s46, s37, s27
	global_load_lds_dwordx4 v[216:217], off
	v_lshl_add_u64 v[218:219], s[44:45], 0, v[130:131]
	s_mov_b32 m0, s46
	v_lshl_add_u64 v[220:221], s[24:25], 0, v[132:133]
	global_load_lds_dwordx4 v[218:219], off
	v_lshl_add_u64 v[218:219], s[44:45], 0, v[134:135]
	s_add_i32 m0, s46, 0x2000
	s_nop 0
	global_load_lds_dwordx4 v[218:219], off
	v_lshl_add_u64 v[218:219], s[24:25], 0, v[128:129]
	s_mov_b32 m0, s19
	s_nop 0
	global_load_lds_dwordx4 v[218:219], off
	s_mov_b32 m0, s28
	s_nop 0
	global_load_lds_dwordx4 v[220:221], off
	s_nop 0
	s_waitcnt lgkmcnt(0)
	s_setprio 1
	s_barrier
; #define PG8_STAGE(bufoff, gbase, voff) do { _Pragma("unroll") for (int _i = 0; _i < 2; ++_i) \
;         __builtin_amdgcn_global_load_lds((const unsigned*)((const char*)(gbase) + (voff)[_i]), (PG8_LAS unsigned*)(lds + (bufoff) + ldsw + _i * 8192), 16, 0, 0); } while (0)
; #define PG8_LDA(dst, b, h) do { _Pragma("unroll") for (int m = 0; m < 4; ++m) _Pragma("unroll") for (int k = 0; k < 2; ++k) dst[m][k] = *(const PG8_LAS bf16x8*)(lds + PG8_SA(b, h) + aoff + m * 2048 + k * 1024); } while (0)
; #define PG8_LDB(dst, b, h) do { _Pragma("unroll") for (int n = 0; n < 2; ++n) _Pragma("unroll") for (int k = 0; k < 2; ++k) dst[n][k] = *(const PG8_LAS bf16x8*)(lds + PG8_SB(b, h) + boff + n * 2048 + k * 1024); } while (0)
; #define PG8_MMA(ai, bj, At, Bt) do { __builtin_amdgcn_s_setprio(1); _Pragma("unroll") for (int m = 0; m < 4; ++m) _Pragma("unroll") for (int n = 0; n < 2; ++n) _Pragma("unroll") for (int k = 0; k < 2; ++k) \
;         acc[ai][bj][m][n] = __builtin_amdgcn_mfma_f32_16x16x32_bf16(Bt[n][k], At[m][k], acc[ai][bj][m][n], 0, 0, 0); __builtin_amdgcn_s_setprio(0); } while (0)
; #define PG8_WAIT_V(n) asm volatile("s_waitcnt vmcnt(" #n ")" ::: "memory")
; #define PG8_WAIT_L(n) asm volatile("s_waitcnt lgkmcnt(" #n ")" ::: "memory")
; #define PG8_BAR __builtin_amdgcn_s_barrier()
; #define PG8_SCHED __builtin_amdgcn_sched_barrier(0)
; template <class Epi, class Sched, bool ALIGN_EPI = false, bool SP2 = false>
; __device__ __forceinline__ void gemm_phase(PG8_LAS unsigned char* lds, const Gemm g, const Sched& S, const Epi& E) {
;     ...
;             PG8_WAIT_V(8); PG8_WAIT_L(0); PG8_BAR; PG8_MMA(1, 0, At, B0); PG8_MMA(1, 1, At, B1); PG8_BAR; PG8_SCHED;
;             PG8_LDB(B0, 1, 0); PG8_LDB(B1, 1, 1); PG8_SCHED; PG8_LDA(At, 1, 0); PG8_STAGE(PG8_SA(0, 1), a2 + hstep, voffA);
;             PG8_WAIT_V(8); PG8_WAIT_L(0); PG8_BAR; PG8_MMA(0, 0, At, B0); PG8_MMA(0, 1, At, B1); PG8_BAR; PG8_SCHED;
	v_mfma_f32_16x16x32_bf16 v[56:59], v[144:147], v[182:185], 0
	v_mfma_f32_16x16x32_bf16 v[60:63], v[158:161], v[182:185], 0
	v_mfma_f32_16x16x32_bf16 v[40:43], v[144:147], v[190:193], 0
	v_mfma_f32_16x16x32_bf16 v[44:47], v[158:161], v[190:193], 0
	v_mfma_f32_16x16x32_bf16 v[24:27], v[144:147], v[198:201], 0
	v_mfma_f32_16x16x32_bf16 v[28:31], v[158:161], v[198:201], 0
	v_mfma_f32_16x16x32_bf16 v[8:11], v[144:147], v[206:209], 0
	v_mfma_f32_16x16x32_bf16 v[12:15], v[158:161], v[206:209], 0
	v_mfma_f32_16x16x32_bf16 v[56:59], v[148:151], v[186:189], v[56:59]
	v_mfma_f32_16x16x32_bf16 v[60:63], v[162:165], v[186:189], v[60:63]
	v_mfma_f32_16x16x32_bf16 v[40:43], v[148:151], v[194:197], v[40:43]
	v_mfma_f32_16x16x32_bf16 v[44:47], v[162:165], v[194:197], v[44:47]
	v_mfma_f32_16x16x32_bf16 v[24:27], v[148:151], v[202:205], v[24:27]
	v_mfma_f32_16x16x32_bf16 v[28:31], v[162:165], v[202:205], v[28:31]
	v_mfma_f32_16x16x32_bf16 v[8:11], v[148:151], v[210:213], v[8:11]
	v_mfma_f32_16x16x32_bf16 v[12:15], v[162:165], v[210:213], v[12:15]
	v_mfma_f32_16x16x32_bf16 v[48:51], v[166:169], v[182:185], 0
	v_mfma_f32_16x16x32_bf16 v[52:55], v[174:177], v[182:185], 0
	v_mfma_f32_16x16x32_bf16 v[32:35], v[166:169], v[190:193], 0
	v_mfma_f32_16x16x32_bf16 v[36:39], v[174:177], v[190:193], 0
	v_mfma_f32_16x16x32_bf16 v[16:19], v[166:169], v[198:201], 0
	v_mfma_f32_16x16x32_bf16 v[20:23], v[174:177], v[198:201], 0
	v_mfma_f32_16x16x32_bf16 v[0:3], v[166:169], v[206:209], 0
	v_mfma_f32_16x16x32_bf16 v[4:7], v[174:177], v[206:209], 0
	v_mfma_f32_16x16x32_bf16 v[48:51], v[170:173], v[186:189], v[48:51]
	v_mfma_f32_16x16x32_bf16 v[52:55], v[178:181], v[186:189], v[52:55]
	v_mfma_f32_16x16x32_bf16 v[32:35], v[170:173], v[194:197], v[32:35]
	v_mfma_f32_16x16x32_bf16 v[36:39], v[178:181], v[194:197], v[36:39]
	v_mfma_f32_16x16x32_bf16 v[16:19], v[170:173], v[202:205], v[16:19]
	v_mfma_f32_16x16x32_bf16 v[20:23], v[178:181], v[202:205], v[20:23]
	v_mfma_f32_16x16x32_bf16 v[0:3], v[170:173], v[210:213], v[0:3]
	v_mfma_f32_16x16x32_bf16 v[4:7], v[178:181], v[210:213], v[4:7]
	s_barrier
	s_setprio 0
	s_add_i32 s44, 0, 0x18000
	s_add_i32 s45, 0, 0x1c000
	v_add_u32_e32 v162, s44, v153
	v_add_u32_e32 v178, s45, v153
	ds_read_b128 v[144:147], v162
	ds_read_b128 v[148:151], v162 offset:1024
	ds_read_b128 v[158:161], v162 offset:2048
	ds_read_b128 v[162:165], v162 offset:3072
	ds_read_b128 v[166:169], v178
	ds_read_b128 v[170:173], v178 offset:1024
	ds_read_b128 v[174:177], v178 offset:2048
	ds_read_b128 v[178:181], v178 offset:3072
	s_add_u32 s24, s24, 0x80000
	s_addc_u32 s25, s25, 0
	s_mov_b32 m0, s29
	v_lshl_add_u64 v[222:223], s[24:25], 0, v[128:129]
	ds_read_b128 v[182:185], v157 offset:32768
	ds_read_b128 v[186:189], v157 offset:33792
	ds_read_b128 v[190:193], v157 offset:34816
	ds_read_b128 v[194:197], v157 offset:35840
	ds_read_b128 v[198:201], v157 offset:36864
	ds_read_b128 v[202:205], v157 offset:37888
	ds_read_b128 v[206:209], v157 offset:38912
	ds_read_b128 v[210:213], v157 offset:39936
	global_load_lds_dwordx4 v[222:223], off
	v_lshl_add_u64 v[222:223], s[24:25], 0, v[132:133]
	s_mov_b32 m0, s30
	s_nop 0
	global_load_lds_dwordx4 v[222:223], off
	s_waitcnt vmcnt(8)
	s_waitcnt lgkmcnt(0)
	s_setprio 1
	s_barrier
	v_mfma_f32_16x16x32_bf16 v[124:127], v[144:147], v[182:185], v[124:127]
	v_mfma_f32_16x16x32_bf16 v[120:123], v[158:161], v[182:185], v[120:123]
	v_mfma_f32_16x16x32_bf16 v[108:111], v[144:147], v[190:193], v[108:111]
	v_mfma_f32_16x16x32_bf16 v[104:107], v[158:161], v[190:193], v[104:107]
	v_mfma_f32_16x16x32_bf16 v[88:91], v[144:147], v[198:201], v[88:91]
	v_mfma_f32_16x16x32_bf16 v[92:95], v[158:161], v[198:201], v[92:95]
	v_mfma_f32_16x16x32_bf16 v[72:75], v[144:147], v[206:209], v[72:75]
	v_mfma_f32_16x16x32_bf16 v[76:79], v[158:161], v[206:209], v[76:79]
	v_mfma_f32_16x16x32_bf16 v[124:127], v[148:151], v[186:189], v[124:127]
	v_mfma_f32_16x16x32_bf16 v[120:123], v[162:165], v[186:189], v[120:123]
	v_mfma_f32_16x16x32_bf16 v[108:111], v[148:151], v[194:197], v[108:111]
	v_mfma_f32_16x16x32_bf16 v[104:107], v[162:165], v[194:197], v[104:107]
	v_mfma_f32_16x16x32_bf16 v[88:91], v[148:151], v[202:205], v[88:91]
	v_mfma_f32_16x16x32_bf16 v[92:95], v[162:165], v[202:205], v[92:95]
	v_mfma_f32_16x16x32_bf16 v[72:75], v[148:151], v[210:213], v[72:75]
	v_mfma_f32_16x16x32_bf16 v[76:79], v[162:165], v[210:213], v[76:79]
	v_mfma_f32_16x16x32_bf16 v[116:119], v[166:169], v[182:185], v[116:119]
	v_mfma_f32_16x16x32_bf16 v[112:115], v[174:177], v[182:185], v[112:115]
	v_mfma_f32_16x16x32_bf16 v[96:99], v[166:169], v[190:193], v[96:99]
	v_mfma_f32_16x16x32_bf16 v[100:103], v[174:177], v[190:193], v[100:103]
	v_mfma_f32_16x16x32_bf16 v[80:83], v[166:169], v[198:201], v[80:83]
	v_mfma_f32_16x16x32_bf16 v[84:87], v[174:177], v[198:201], v[84:87]
	v_mfma_f32_16x16x32_bf16 v[64:67], v[166:169], v[206:209], v[64:67]
	v_mfma_f32_16x16x32_bf16 v[68:71], v[174:177], v[206:209], v[68:71]
	v_mfma_f32_16x16x32_bf16 v[116:119], v[170:173], v[186:189], v[116:119]
	v_mfma_f32_16x16x32_bf16 v[112:115], v[178:181], v[186:189], v[112:115]
	v_mfma_f32_16x16x32_bf16 v[96:99], v[170:173], v[194:197], v[96:99]
	v_mfma_f32_16x16x32_bf16 v[100:103], v[178:181], v[194:197], v[100:103]
	v_mfma_f32_16x16x32_bf16 v[80:83], v[170:173], v[202:205], v[80:83]
	v_mfma_f32_16x16x32_bf16 v[84:87], v[178:181], v[202:205], v[84:87]
	v_mfma_f32_16x16x32_bf16 v[64:67], v[170:173], v[210:213], v[64:67]
	v_mfma_f32_16x16x32_bf16 v[68:71], v[178:181], v[210:213], v[68:71]
	s_barrier
; #define PG8_STAGE(bufoff, gbase, voff) do { _Pragma("unroll") for (int _i = 0; _i < 2; ++_i) \
;         __builtin_amdgcn_global_load_lds((const unsigned*)((const char*)(gbase) + (voff)[_i]), (PG8_LAS unsigned*)(lds + (bufoff) + ldsw + _i * 8192), 16, 0, 0); } while (0)
; #define PG8_LDA(dst, b, h) do { _Pragma("unroll") for (int m = 0; m < 4; ++m) _Pragma("unroll") for (int k = 0; k < 2; ++k) dst[m][k] = *(const PG8_LAS bf16x8*)(lds + PG8_SA(b, h) + aoff + m * 2048 + k * 1024); } while (0)
; #define PG8_MMA(ai, bj, At, Bt) do { __builtin_amdgcn_s_setprio(1); _Pragma("unroll") for (int m = 0; m < 4; ++m) _Pragma("unroll") for (int n = 0; n < 2; ++n) _Pragma("unroll") for (int k = 0; k < 2; ++k) \
;         acc[ai][bj][m][n] = __builtin_amdgcn_mfma_f32_16x16x32_bf16(Bt[n][k], At[m][k], acc[ai][bj][m][n], 0, 0, 0); __builtin_amdgcn_s_setprio(0); } while (0)
; #define PG8_WAIT_V(n) asm volatile("s_waitcnt vmcnt(" #n ")" ::: "memory")
; #define PG8_WAIT_L(n) asm volatile("s_waitcnt lgkmcnt(" #n ")" ::: "memory")
; #define PG8_BAR __builtin_amdgcn_s_barrier()
; #define PG8_SCHED __builtin_amdgcn_sched_barrier(0)
; template <class Epi, class Sched, bool ALIGN_EPI = false, bool SP2 = false>
; __device__ __forceinline__ void gemm_phase(PG8_LAS unsigned char* lds, const Gemm g, const Sched& S, const Epi& E) {
;     ...
;             PG8_LDA(At, 1, 1); PG8_STAGE(PG8_SB(1, 0), b3, voffB); PG8_STAGE(PG8_SB(1, 1), b3 + hstep, voffB); PG8_STAGE(PG8_SA(1, 0), a3, voffA);
;             PG8_WAIT_V(8); PG8_WAIT_L(0); PG8_BAR; PG8_MMA(1, 0, At, B0); PG8_MMA(1, 1, At, B1); PG8_BAR; PG8_SCHED;
	s_setprio 0
	s_add_i32 s24, s44, s27
	v_lshl_add_u64 v[214:215], v[214:215], 0, s[4:5]
	s_mov_b32 m0, s24
	ds_read_b128 v[182:185], v157 offset:49152
	ds_read_b128 v[186:189], v157 offset:50176
	ds_read_b128 v[190:193], v157 offset:51200
	ds_read_b128 v[194:197], v157 offset:52224
	ds_read_b128 v[198:201], v157 offset:53248
	ds_read_b128 v[202:205], v157 offset:54272
	ds_read_b128 v[206:209], v157 offset:55296
	ds_read_b128 v[210:213], v157 offset:56320
	global_load_lds_dwordx4 v[214:215], off
	s_add_i32 m0, s24, 0x2000
	s_add_u32 s22, s22, 0x80080
	v_lshl_add_u64 v[214:215], v[216:217], 0, s[4:5]
	s_addc_u32 s23, s23, 0
	s_add_i32 s24, s45, s27
	global_load_lds_dwordx4 v[214:215], off
	v_lshl_add_u64 v[214:215], s[22:23], 0, v[130:131]
	s_mov_b32 m0, s24
	s_nop 0
	global_load_lds_dwordx4 v[214:215], off
	v_lshl_add_u64 v[214:215], s[22:23], 0, v[134:135]
	s_add_i32 m0, s24, 0x2000
	s_nop 0
	global_load_lds_dwordx4 v[214:215], off
	v_lshl_add_u64 v[214:215], v[218:219], 0, s[4:5]
	s_mov_b32 m0, s33
	s_nop 0
	global_load_lds_dwordx4 v[214:215], off
	v_lshl_add_u64 v[214:215], v[220:221], 0, s[4:5]
	s_mov_b32 m0, s34
	s_nop 0
	global_load_lds_dwordx4 v[214:215], off
	s_waitcnt vmcnt(8)
	s_waitcnt lgkmcnt(0)
	s_setprio 1
	s_barrier
	v_mfma_f32_16x16x32_bf16 v[56:59], v[144:147], v[182:185], v[56:59]
	v_mfma_f32_16x16x32_bf16 v[60:63], v[158:161], v[182:185], v[60:63]
	v_mfma_f32_16x16x32_bf16 v[40:43], v[144:147], v[190:193], v[40:43]
	v_mfma_f32_16x16x32_bf16 v[44:47], v[158:161], v[190:193], v[44:47]
	v_mfma_f32_16x16x32_bf16 v[24:27], v[144:147], v[198:201], v[24:27]
	v_mfma_f32_16x16x32_bf16 v[28:31], v[158:161], v[198:201], v[28:31]
	v_mfma_f32_16x16x32_bf16 v[8:11], v[144:147], v[206:209], v[8:11]
	v_mfma_f32_16x16x32_bf16 v[12:15], v[158:161], v[206:209], v[12:15]
	v_mfma_f32_16x16x32_bf16 v[56:59], v[148:151], v[186:189], v[56:59]
	v_mfma_f32_16x16x32_bf16 v[60:63], v[162:165], v[186:189], v[60:63]
	v_mfma_f32_16x16x32_bf16 v[40:43], v[148:151], v[194:197], v[40:43]
	v_mfma_f32_16x16x32_bf16 v[44:47], v[162:165], v[194:197], v[44:47]
	v_mfma_f32_16x16x32_bf16 v[24:27], v[148:151], v[202:205], v[24:27]
	v_mfma_f32_16x16x32_bf16 v[28:31], v[162:165], v[202:205], v[28:31]
	v_mfma_f32_16x16x32_bf16 v[8:11], v[148:151], v[210:213], v[8:11]
	v_mfma_f32_16x16x32_bf16 v[12:15], v[162:165], v[210:213], v[12:15]
	v_mfma_f32_16x16x32_bf16 v[48:51], v[166:169], v[182:185], v[48:51]
	v_mfma_f32_16x16x32_bf16 v[52:55], v[174:177], v[182:185], v[52:55]
	v_mfma_f32_16x16x32_bf16 v[32:35], v[166:169], v[190:193], v[32:35]
	v_mfma_f32_16x16x32_bf16 v[36:39], v[174:177], v[190:193], v[36:39]
	v_mfma_f32_16x16x32_bf16 v[16:19], v[166:169], v[198:201], v[16:19]
	v_mfma_f32_16x16x32_bf16 v[20:23], v[174:177], v[198:201], v[20:23]
	v_mfma_f32_16x16x32_bf16 v[0:3], v[166:169], v[206:209], v[0:3]
	v_mfma_f32_16x16x32_bf16 v[4:7], v[174:177], v[206:209], v[4:7]
	v_mfma_f32_16x16x32_bf16 v[48:51], v[170:173], v[186:189], v[48:51]
	v_mfma_f32_16x16x32_bf16 v[52:55], v[178:181], v[186:189], v[52:55]
	v_mfma_f32_16x16x32_bf16 v[32:35], v[170:173], v[194:197], v[32:35]
	v_mfma_f32_16x16x32_bf16 v[36:39], v[178:181], v[194:197], v[36:39]
	v_mfma_f32_16x16x32_bf16 v[16:19], v[170:173], v[202:205], v[16:19]
	v_mfma_f32_16x16x32_bf16 v[20:23], v[178:181], v[202:205], v[20:23]
	v_mfma_f32_16x16x32_bf16 v[0:3], v[170:173], v[210:213], v[0:3]
	v_mfma_f32_16x16x32_bf16 v[4:7], v[178:181], v[210:213], v[4:7]
	s_barrier
	s_setprio 0
	s_add_i32 s43, s43, 2
	s_add_u32 s20, s20, 0x100
	s_addc_u32 s21, s21, 0
	s_add_u32 s41, s41, 0x100
	s_addc_u32 s42, s42, 0
